# EpiBf16 epilogue stores (MLP1 x2, hyena in, filter GEMM) write-through sc1 so the barrier's L2 writeback has less to flush
# baseline (speedup 1.0000x reference)
.LBB0_110:
	s_add_u32 s8, s60, 0xfff00080
	s_addc_u32 s9, s61, -1
	s_add_i32 s16, 0, 0x10000
	v_add_u32_e32 v140, s16, v169
	ds_read_b128 v[128:131], v140
	ds_read_b128 v[132:135], v140 offset:1024
	ds_read_b128 v[136:139], v140 offset:2048
	ds_read_b128 v[140:143], v140 offset:3072
	s_cmp_eq_u32 s15, 60
	s_cselect_b32 s9, s5, s9
	s_cselect_b32 s8, s50, s8
	s_cselect_b32 s63, s1, s14
	s_cselect_b32 s62, s12, s13
	v_lshl_add_u64 v[164:165], s[60:61], 0, v[178:179]
	s_add_i32 m0, s38, 0xc000
	ds_read_b128 v[144:147], v171
	ds_read_b128 v[148:151], v171 offset:1024
	ds_read_b128 v[152:155], v171 offset:2048
	ds_read_b128 v[156:159], v171 offset:3072
	ds_read_b128 v[182:185], v171 offset:4096
	ds_read_b128 v[186:189], v171 offset:5120
	ds_read_b128 v[190:193], v171 offset:6144
	ds_read_b128 v[194:197], v171 offset:7168
	global_load_lds_dwordx4 v[164:165], off
	v_lshl_add_u64 v[164:165], s[60:61], 0, v[180:181]
	s_add_i32 m0, s38, 0xe000
	s_nop 0
	global_load_lds_dwordx4 v[164:165], off
	s_waitcnt lgkmcnt(8)
	s_barrier
	s_waitcnt lgkmcnt(0)
	s_setprio 1
	s_waitcnt lgkmcnt(0)
	v_mfma_f32_16x16x32_bf16 v[124:127], v[128:131], v[144:147], v[124:127]
	v_mfma_f32_16x16x32_bf16 v[120:123], v[136:139], v[144:147], v[120:123]
	v_mfma_f32_16x16x32_bf16 v[116:119], v[128:131], v[152:155], v[116:119]
	v_mfma_f32_16x16x32_bf16 v[112:115], v[136:139], v[152:155], v[112:115]
	v_mfma_f32_16x16x32_bf16 v[108:111], v[128:131], v[182:185], v[108:111]
	v_mfma_f32_16x16x32_bf16 v[104:107], v[136:139], v[182:185], v[104:107]
	v_mfma_f32_16x16x32_bf16 v[100:103], v[128:131], v[190:193], v[100:103]
	v_mfma_f32_16x16x32_bf16 v[96:99], v[136:139], v[190:193], v[96:99]
	v_mfma_f32_16x16x32_bf16 v[124:127], v[132:135], v[148:151], v[124:127]
	v_mfma_f32_16x16x32_bf16 v[120:123], v[140:143], v[148:151], v[120:123]
	v_mfma_f32_16x16x32_bf16 v[116:119], v[132:135], v[156:159], v[116:119]
	v_mfma_f32_16x16x32_bf16 v[112:115], v[140:143], v[156:159], v[112:115]
	v_mfma_f32_16x16x32_bf16 v[108:111], v[132:135], v[186:189], v[108:111]
	v_mfma_f32_16x16x32_bf16 v[104:107], v[140:143], v[186:189], v[104:107]
	v_mfma_f32_16x16x32_bf16 v[100:103], v[132:135], v[194:197], v[100:103]
	v_mfma_f32_16x16x32_bf16 v[96:99], v[140:143], v[194:197], v[96:99]
	s_setprio 0
	s_barrier
	s_add_i32 s18, 0, 0x14000
	s_add_i32 s16, s16, s37
	v_add_u32_e32 v162, s18, v169
	v_lshl_add_u64 v[164:165], s[62:63], 0, v[160:161]
	s_mov_b32 m0, s16
	ds_read_b128 v[198:201], v162
	ds_read_b128 v[202:205], v162 offset:1024
	ds_read_b128 v[206:209], v162 offset:2048
	ds_read_b128 v[210:213], v162 offset:3072
	global_load_lds_dwordx4 v[164:165], off
	v_lshl_add_u64 v[166:167], s[62:63], 0, v[172:173]
	s_add_i32 m0, s16, 0x2000
	s_nop 0
	global_load_lds_dwordx4 v[166:167], off
	s_barrier
	s_waitcnt lgkmcnt(0)
	s_setprio 1
	s_waitcnt lgkmcnt(0)
	v_mfma_f32_16x16x32_bf16 v[60:63], v[198:201], v[144:147], v[60:63]
	v_mfma_f32_16x16x32_bf16 v[56:59], v[206:209], v[144:147], v[56:59]
	v_mfma_f32_16x16x32_bf16 v[52:55], v[198:201], v[152:155], v[52:55]
	v_mfma_f32_16x16x32_bf16 v[48:51], v[206:209], v[152:155], v[48:51]
	v_mfma_f32_16x16x32_bf16 v[44:47], v[198:201], v[182:185], v[44:47]
	v_mfma_f32_16x16x32_bf16 v[40:43], v[206:209], v[182:185], v[40:43]
	v_mfma_f32_16x16x32_bf16 v[36:39], v[198:201], v[190:193], v[36:39]
	v_mfma_f32_16x16x32_bf16 v[32:35], v[206:209], v[190:193], v[32:35]
	v_mfma_f32_16x16x32_bf16 v[60:63], v[202:205], v[148:151], v[60:63]
	v_mfma_f32_16x16x32_bf16 v[56:59], v[210:213], v[148:151], v[56:59]
	v_mfma_f32_16x16x32_bf16 v[52:55], v[202:205], v[156:159], v[52:55]
	v_mfma_f32_16x16x32_bf16 v[48:51], v[210:213], v[156:159], v[48:51]
	v_mfma_f32_16x16x32_bf16 v[44:47], v[202:205], v[186:189], v[44:47]
	v_mfma_f32_16x16x32_bf16 v[40:43], v[210:213], v[186:189], v[40:43]
	v_mfma_f32_16x16x32_bf16 v[36:39], v[202:205], v[194:197], v[36:39]
	v_mfma_f32_16x16x32_bf16 v[32:35], v[210:213], v[194:197], v[32:35]
	s_setprio 0
	s_mov_b32 m0, s38
	v_lshl_add_u64 v[214:215], s[8:9], 0, v[176:177]
	s_barrier
	ds_read_b128 v[144:147], v171 offset:16384
	ds_read_b128 v[148:151], v171 offset:17408
	ds_read_b128 v[152:155], v171 offset:18432
	ds_read_b128 v[156:159], v171 offset:19456
	ds_read_b128 v[182:185], v171 offset:20480
	ds_read_b128 v[186:189], v171 offset:21504
	ds_read_b128 v[190:193], v171 offset:22528
	ds_read_b128 v[194:197], v171 offset:23552
	global_load_lds_dwordx4 v[214:215], off
	v_lshl_add_u64 v[216:217], s[8:9], 0, v[174:175]
	s_mov_b32 m0, s39
	s_nop 0
	global_load_lds_dwordx4 v[216:217], off
	s_barrier
	s_waitcnt lgkmcnt(0)
	s_setprio 1
	s_waitcnt lgkmcnt(0)
	v_mfma_f32_16x16x32_bf16 v[92:95], v[128:131], v[144:147], v[92:95]
	v_mfma_f32_16x16x32_bf16 v[88:91], v[136:139], v[144:147], v[88:91]
	v_mfma_f32_16x16x32_bf16 v[84:87], v[128:131], v[152:155], v[84:87]
	v_mfma_f32_16x16x32_bf16 v[80:83], v[136:139], v[152:155], v[80:83]
	v_mfma_f32_16x16x32_bf16 v[76:79], v[128:131], v[182:185], v[76:79]
	v_mfma_f32_16x16x32_bf16 v[72:75], v[136:139], v[182:185], v[72:75]
	v_mfma_f32_16x16x32_bf16 v[68:71], v[128:131], v[190:193], v[68:71]
	v_mfma_f32_16x16x32_bf16 v[64:67], v[136:139], v[190:193], v[64:67]
	v_mfma_f32_16x16x32_bf16 v[92:95], v[132:135], v[148:151], v[92:95]
	v_mfma_f32_16x16x32_bf16 v[88:91], v[140:143], v[148:151], v[88:91]
	v_mfma_f32_16x16x32_bf16 v[84:87], v[132:135], v[156:159], v[84:87]
	v_mfma_f32_16x16x32_bf16 v[80:83], v[140:143], v[156:159], v[80:83]
	v_mfma_f32_16x16x32_bf16 v[76:79], v[132:135], v[186:189], v[76:79]
	v_mfma_f32_16x16x32_bf16 v[72:75], v[140:143], v[186:189], v[72:75]
	v_mfma_f32_16x16x32_bf16 v[68:71], v[132:135], v[194:197], v[68:71]
	v_mfma_f32_16x16x32_bf16 v[64:67], v[140:143], v[194:197], v[64:67]
	s_setprio 0
	s_barrier
	s_add_u32 s16, s62, 0x100000
	s_addc_u32 s17, s63, 0
	s_add_i32 s18, s18, s37
	v_lshl_add_u64 v[128:129], s[16:17], 0, v[160:161]
	s_mov_b32 m0, s18
	s_nop 0
	global_load_lds_dwordx4 v[128:129], off
	v_lshl_add_u64 v[128:129], s[16:17], 0, v[172:173]
	s_add_i32 m0, s18, 0x2000
	s_nop 0
	global_load_lds_dwordx4 v[128:129], off
	s_waitcnt vmcnt(6)
	s_barrier
	s_setprio 1
	v_mfma_f32_16x16x32_bf16 v[28:31], v[198:201], v[144:147], v[28:31]
	v_mfma_f32_16x16x32_bf16 v[24:27], v[206:209], v[144:147], v[24:27]
	v_mfma_f32_16x16x32_bf16 v[20:23], v[198:201], v[152:155], v[20:23]
	v_mfma_f32_16x16x32_bf16 v[16:19], v[206:209], v[152:155], v[16:19]
	v_mfma_f32_16x16x32_bf16 v[12:15], v[198:201], v[182:185], v[12:15]
	v_mfma_f32_16x16x32_bf16 v[8:11], v[206:209], v[182:185], v[8:11]
	v_mfma_f32_16x16x32_bf16 v[4:7], v[198:201], v[190:193], v[4:7]
	v_mfma_f32_16x16x32_bf16 v[0:3], v[206:209], v[190:193], v[0:3]
	v_mfma_f32_16x16x32_bf16 v[28:31], v[202:205], v[148:151], v[28:31]
	v_mfma_f32_16x16x32_bf16 v[24:27], v[210:213], v[148:151], v[24:27]
	v_mfma_f32_16x16x32_bf16 v[20:23], v[202:205], v[156:159], v[20:23]
	v_mfma_f32_16x16x32_bf16 v[16:19], v[210:213], v[156:159], v[16:19]
	v_mfma_f32_16x16x32_bf16 v[12:15], v[202:205], v[186:189], v[12:15]
	v_mfma_f32_16x16x32_bf16 v[8:11], v[210:213], v[186:189], v[8:11]
	v_mfma_f32_16x16x32_bf16 v[4:7], v[202:205], v[194:197], v[4:7]
	v_mfma_f32_16x16x32_bf16 v[0:3], v[210:213], v[194:197], v[0:3]
	s_setprio 0
	s_add_i32 s16, 0, 0x18000
	v_add_u32_e32 v140, s16, v169
	s_barrier
	ds_read_b128 v[128:131], v140
	ds_read_b128 v[132:135], v140 offset:1024
	ds_read_b128 v[136:139], v140 offset:2048
	ds_read_b128 v[140:143], v140 offset:3072
	s_add_u32 s8, s8, 0x100000
	s_addc_u32 s9, s9, 0
	s_mov_b32 m0, s40
	v_lshl_add_u64 v[198:199], s[8:9], 0, v[176:177]
	ds_read_b128 v[144:147], v171 offset:32768
	ds_read_b128 v[148:151], v171 offset:33792
	ds_read_b128 v[152:155], v171 offset:34816
	ds_read_b128 v[156:159], v171 offset:35840
	ds_read_b128 v[182:185], v171 offset:36864
	ds_read_b128 v[186:189], v171 offset:37888
	ds_read_b128 v[190:193], v171 offset:38912
	ds_read_b128 v[194:197], v171 offset:39936
	global_load_lds_dwordx4 v[198:199], off
	v_lshl_add_u64 v[198:199], s[8:9], 0, v[174:175]
	s_mov_b32 m0, s41
	s_nop 0
	global_load_lds_dwordx4 v[198:199], off
	s_waitcnt lgkmcnt(8)
	s_barrier
	s_waitcnt lgkmcnt(0)
	s_setprio 1
	s_waitcnt lgkmcnt(0)
	v_mfma_f32_16x16x32_bf16 v[124:127], v[128:131], v[144:147], v[124:127]
	v_mfma_f32_16x16x32_bf16 v[120:123], v[136:139], v[144:147], v[120:123]
	v_mfma_f32_16x16x32_bf16 v[116:119], v[128:131], v[152:155], v[116:119]
	v_mfma_f32_16x16x32_bf16 v[112:115], v[136:139], v[152:155], v[112:115]
	v_mfma_f32_16x16x32_bf16 v[108:111], v[128:131], v[182:185], v[108:111]
	v_mfma_f32_16x16x32_bf16 v[104:107], v[136:139], v[182:185], v[104:107]
	v_mfma_f32_16x16x32_bf16 v[100:103], v[128:131], v[190:193], v[100:103]
	v_mfma_f32_16x16x32_bf16 v[96:99], v[136:139], v[190:193], v[96:99]
	v_mfma_f32_16x16x32_bf16 v[124:127], v[132:135], v[148:151], v[124:127]
	v_mfma_f32_16x16x32_bf16 v[120:123], v[140:143], v[148:151], v[120:123]
	v_mfma_f32_16x16x32_bf16 v[116:119], v[132:135], v[156:159], v[116:119]
	v_mfma_f32_16x16x32_bf16 v[112:115], v[140:143], v[156:159], v[112:115]
	v_mfma_f32_16x16x32_bf16 v[108:111], v[132:135], v[186:189], v[108:111]
	v_mfma_f32_16x16x32_bf16 v[104:107], v[140:143], v[186:189], v[104:107]
	v_mfma_f32_16x16x32_bf16 v[100:103], v[132:135], v[194:197], v[100:103]
	v_mfma_f32_16x16x32_bf16 v[96:99], v[140:143], v[194:197], v[96:99]
	s_setprio 0
	s_barrier
	s_add_i32 s17, 0, 0x1c000
	s_add_i32 s8, s16, s37
	v_add_u32_e32 v162, s17, v169
	v_lshl_add_u64 v[164:165], v[164:165], 0, s[74:75]
	s_mov_b32 m0, s8
	ds_read_b128 v[198:201], v162
	ds_read_b128 v[202:205], v162 offset:1024
	ds_read_b128 v[206:209], v162 offset:2048
	ds_read_b128 v[210:213], v162 offset:3072
	global_load_lds_dwordx4 v[164:165], off
	v_lshl_add_u64 v[164:165], v[166:167], 0, s[74:75]
	s_add_i32 m0, s8, 0x2000
	s_nop 0
	global_load_lds_dwordx4 v[164:165], off
	s_barrier
	s_waitcnt lgkmcnt(0)
	s_setprio 1
	s_waitcnt lgkmcnt(0)
	v_mfma_f32_16x16x32_bf16 v[60:63], v[198:201], v[144:147], v[60:63]
	v_mfma_f32_16x16x32_bf16 v[56:59], v[206:209], v[144:147], v[56:59]
	v_mfma_f32_16x16x32_bf16 v[52:55], v[198:201], v[152:155], v[52:55]
	v_mfma_f32_16x16x32_bf16 v[48:51], v[206:209], v[152:155], v[48:51]
	v_mfma_f32_16x16x32_bf16 v[44:47], v[198:201], v[182:185], v[44:47]
	v_mfma_f32_16x16x32_bf16 v[40:43], v[206:209], v[182:185], v[40:43]
	v_mfma_f32_16x16x32_bf16 v[36:39], v[198:201], v[190:193], v[36:39]
	v_mfma_f32_16x16x32_bf16 v[32:35], v[206:209], v[190:193], v[32:35]
	v_mfma_f32_16x16x32_bf16 v[60:63], v[202:205], v[148:151], v[60:63]
	v_mfma_f32_16x16x32_bf16 v[56:59], v[210:213], v[148:151], v[56:59]
	v_mfma_f32_16x16x32_bf16 v[52:55], v[202:205], v[156:159], v[52:55]
	v_mfma_f32_16x16x32_bf16 v[48:51], v[210:213], v[156:159], v[48:51]
	v_mfma_f32_16x16x32_bf16 v[44:47], v[202:205], v[186:189], v[44:47]
	v_mfma_f32_16x16x32_bf16 v[40:43], v[210:213], v[186:189], v[40:43]
	v_mfma_f32_16x16x32_bf16 v[36:39], v[202:205], v[194:197], v[36:39]
	v_mfma_f32_16x16x32_bf16 v[32:35], v[210:213], v[194:197], v[32:35]
	s_setprio 0
	s_mov_b32 m0, s42
	v_lshl_add_u64 v[164:165], v[214:215], 0, s[74:75]
	s_barrier
	ds_read_b128 v[144:147], v171 offset:49152
	ds_read_b128 v[148:151], v171 offset:50176
	ds_read_b128 v[152:155], v171 offset:51200
	ds_read_b128 v[156:159], v171 offset:52224
	ds_read_b128 v[182:185], v171 offset:53248
	ds_read_b128 v[186:189], v171 offset:54272
	ds_read_b128 v[190:193], v171 offset:55296
	ds_read_b128 v[194:197], v171 offset:56320
	global_load_lds_dwordx4 v[164:165], off
	v_lshl_add_u64 v[164:165], v[216:217], 0, s[74:75]
	s_mov_b32 m0, s43
	s_nop 0
	global_load_lds_dwordx4 v[164:165], off
	s_barrier
	s_waitcnt lgkmcnt(0)
	s_setprio 1
	s_waitcnt lgkmcnt(0)
	v_mfma_f32_16x16x32_bf16 v[92:95], v[128:131], v[144:147], v[92:95]
	v_mfma_f32_16x16x32_bf16 v[88:91], v[136:139], v[144:147], v[88:91]
	v_mfma_f32_16x16x32_bf16 v[84:87], v[128:131], v[152:155], v[84:87]
	v_mfma_f32_16x16x32_bf16 v[80:83], v[136:139], v[152:155], v[80:83]
	v_mfma_f32_16x16x32_bf16 v[76:79], v[128:131], v[182:185], v[76:79]
	v_mfma_f32_16x16x32_bf16 v[72:75], v[136:139], v[182:185], v[72:75]
	v_mfma_f32_16x16x32_bf16 v[68:71], v[128:131], v[190:193], v[68:71]
	v_mfma_f32_16x16x32_bf16 v[64:67], v[136:139], v[190:193], v[64:67]
	v_mfma_f32_16x16x32_bf16 v[92:95], v[132:135], v[148:151], v[92:95]
	v_mfma_f32_16x16x32_bf16 v[88:91], v[140:143], v[148:151], v[88:91]
	v_mfma_f32_16x16x32_bf16 v[84:87], v[132:135], v[156:159], v[84:87]
	v_mfma_f32_16x16x32_bf16 v[80:83], v[140:143], v[156:159], v[80:83]
	v_mfma_f32_16x16x32_bf16 v[76:79], v[132:135], v[186:189], v[76:79]
	v_mfma_f32_16x16x32_bf16 v[72:75], v[140:143], v[186:189], v[72:75]
	v_mfma_f32_16x16x32_bf16 v[68:71], v[132:135], v[194:197], v[68:71]
	v_mfma_f32_16x16x32_bf16 v[64:67], v[140:143], v[194:197], v[64:67]
	s_setprio 0
	s_barrier
	s_add_u32 s8, s62, 0x100080
	s_addc_u32 s9, s63, 0
	s_add_i32 s16, s17, s37
	v_lshl_add_u64 v[128:129], s[8:9], 0, v[160:161]
	s_mov_b32 m0, s16
	s_nop 0
	global_load_lds_dwordx4 v[128:129], off
	v_lshl_add_u64 v[128:129], s[8:9], 0, v[172:173]
	s_add_i32 m0, s16, 0x2000
	s_nop 0
	global_load_lds_dwordx4 v[128:129], off
	s_waitcnt vmcnt(6)
	s_barrier
	s_setprio 1
	v_mfma_f32_16x16x32_bf16 v[28:31], v[198:201], v[144:147], v[28:31]
	v_mfma_f32_16x16x32_bf16 v[24:27], v[206:209], v[144:147], v[24:27]
	v_mfma_f32_16x16x32_bf16 v[20:23], v[198:201], v[152:155], v[20:23]
	v_mfma_f32_16x16x32_bf16 v[16:19], v[206:209], v[152:155], v[16:19]
	v_mfma_f32_16x16x32_bf16 v[12:15], v[198:201], v[182:185], v[12:15]
	v_mfma_f32_16x16x32_bf16 v[8:11], v[206:209], v[182:185], v[8:11]
	v_mfma_f32_16x16x32_bf16 v[4:7], v[198:201], v[190:193], v[4:7]
	v_mfma_f32_16x16x32_bf16 v[0:3], v[206:209], v[190:193], v[0:3]
	v_mfma_f32_16x16x32_bf16 v[28:31], v[202:205], v[148:151], v[28:31]
	v_mfma_f32_16x16x32_bf16 v[24:27], v[210:213], v[148:151], v[24:27]
	v_mfma_f32_16x16x32_bf16 v[20:23], v[202:205], v[156:159], v[20:23]
	v_mfma_f32_16x16x32_bf16 v[16:19], v[210:213], v[156:159], v[16:19]
	v_mfma_f32_16x16x32_bf16 v[12:15], v[202:205], v[186:189], v[12:15]
	v_mfma_f32_16x16x32_bf16 v[8:11], v[210:213], v[186:189], v[8:11]
	v_mfma_f32_16x16x32_bf16 v[4:7], v[202:205], v[194:197], v[4:7]
	v_mfma_f32_16x16x32_bf16 v[0:3], v[210:213], v[194:197], v[0:3]
	s_setprio 0
	s_add_i32 s15, s15, 2
	s_add_u32 s60, s60, 0x100
	s_addc_u32 s61, s61, 0
	s_add_u32 s13, s13, 0x100
	s_addc_u32 s14, s14, 0
	s_cmp_gt_u32 s15, 61
	s_barrier
	s_cbranch_scc0 .LBB0_110
	v_lshl_add_u32 v210, s65, 8, v168
	v_or_b32_e32 v132, 16, v210
	v_ashrrev_i32_e32 v133, 31, v132
	v_lshlrev_b64 v[212:213], 11, v[132:133]
	v_or_b32_e32 v132, 32, v210
	s_lshr_b32 s1, s65, 5
	v_ashrrev_i32_e32 v133, 31, v132
	v_lshl_or_b32 v128, s10, 8, v170
	s_mul_i32 s8, s1, 0x1800
	v_lshlrev_b64 v[208:209], 11, v[132:133]
	v_or_b32_e32 v132, 48, v210
	s_ashr_i32 s9, s8, 31
	v_ashrrev_i32_e32 v129, 31, v128
	v_readlane_b32 s12, v249, 12
	v_ashrrev_i32_e32 v133, 31, v132
	v_lshlrev_b64 v[182:183], 1, v[128:129]
	v_readlane_b32 s13, v249, 13
	v_readlane_b32 s14, v249, 14
	v_readlane_b32 s15, v249, 15
	v_ashrrev_i32_e32 v211, 31, v210
	v_lshlrev_b64 v[206:207], 11, v[132:133]
	v_add_u32_e32 v132, 0x90, v210
	s_lshl_b64 s[8:9], s[8:9], 2
	v_readlane_b32 s1, v250, 8
	v_lshl_add_u64 v[130:131], s[12:13], 0, v[182:183]
	v_lshlrev_b64 v[164:165], 11, v[210:211]
	s_mov_b64 s[14:15], 0x40000
	v_ashrrev_i32_e32 v133, 31, v132
	s_add_u32 s8, s1, s8
	v_readlane_b32 s1, v250, 9
	v_lshl_add_u64 v[184:185], v[130:131], 0, v[164:165]
	v_lshl_add_u64 v[204:205], v[164:165], 0, s[14:15]
	v_lshlrev_b64 v[200:201], 11, v[132:133]
	s_addc_u32 s9, s1, s9
	global_load_dwordx4 v[214:217], v[184:185], off
	v_lshl_add_u64 v[186:187], v[130:131], 0, v[212:213]
	v_lshl_add_u64 v[188:189], v[130:131], 0, v[208:209]
	v_lshl_add_u64 v[190:191], v[130:131], 0, v[206:207]
	v_lshl_add_u64 v[192:193], v[130:131], 0, v[204:205]
	v_lshl_add_u64 v[194:195], v[130:131], 0, v[200:201]
	v_lshl_add_u64 v[198:199], v[128:129], 2, s[8:9]
	global_load_dwordx4 v[156:159], v[186:187], off
	global_load_dwordx4 v[152:155], v[188:189], off
	global_load_dwordx4 v[148:151], v[190:191], off
	global_load_dwordx4 v[144:147], v[192:193], off
	global_load_dwordx4 v[136:139], v[194:195], off
	global_load_dwordx4 v[128:131], v[198:199], off offset:16
	global_load_dwordx4 v[132:135], v[198:199], off
	v_add_u32_e32 v140, 0xa0, v210
	v_ashrrev_i32_e32 v141, 31, v140
	v_lshlrev_b64 v[202:203], 11, v[140:141]
	v_lshl_add_u64 v[140:141], s[12:13], 0, v[202:203]
	v_readlane_b32 s8, v250, 5
	v_lshl_add_u64 v[196:197], v[140:141], 0, v[182:183]
	v_readlane_b32 s9, v250, 6
	global_load_dwordx4 v[140:143], v[196:197], off
	v_readlane_b32 s18, v249, 18
	s_and_b64 vcc, exec, s[2:3]
	s_mov_b32 s10, s0
	s_mov_b32 s65, s4
	s_mov_b64 s[20:21], s[6:7]
	v_readlane_b32 s62, v255, 4
	v_readlane_b32 s16, v249, 16
	v_readlane_b32 s17, v249, 17
	v_readlane_b32 s19, v249, 19
	v_readlane_b32 s63, v255, 5
	s_waitcnt vmcnt(0)
	v_lshlrev_b32_e32 v166, 16, v214
	v_and_b32_e32 v167, 0xffff0000, v214
	v_lshlrev_b32_e32 v218, 16, v216
	v_and_b32_e32 v219, 0xffff0000, v216
	v_lshlrev_b32_e32 v216, 16, v217
	v_and_b32_e32 v217, 0xffff0000, v217
	v_lshlrev_b32_e32 v214, 16, v215
	v_and_b32_e32 v215, 0xffff0000, v215
	v_pk_fma_f32 v[124:125], v[124:125], v[132:133], v[166:167]
	v_pk_fma_f32 v[166:167], v[122:123], v[130:131], v[216:217]
	v_pk_fma_f32 v[122:123], v[120:121], v[128:129], v[218:219]
	v_cvt_pk_bf16_f32 v120, v124, v125
	v_lshl_add_u64 v[124:125], s[8:9], 0, v[164:165]
	v_lshl_add_u64 v[124:125], v[124:125], 0, v[182:183]
	v_pk_fma_f32 v[126:127], v[126:127], v[134:135], v[214:215]
	v_lshlrev_b32_e32 v164, 16, v156
	v_cvt_pk_bf16_f32 v121, v126, v127
	v_cvt_pk_bf16_f32 v122, v122, v123
	v_cvt_pk_bf16_f32 v123, v166, v167
	global_store_dwordx4 v[124:125], v[120:123], off sc1
	v_and_b32_e32 v165, 0xffff0000, v156
	v_lshlrev_b32_e32 v166, 16, v158
	v_add_u32_e32 v120, 0xb0, v210
	v_ashrrev_i32_e32 v121, 31, v120
	v_lshlrev_b64 v[210:211], 11, v[120:121]
	v_lshl_add_u64 v[120:121], s[12:13], 0, v[210:211]
	v_lshl_add_u64 v[126:127], v[120:121], 0, v[182:183]
	global_load_dwordx4 v[120:123], v[126:127], off
	v_and_b32_e32 v167, 0xffff0000, v158
	v_lshlrev_b32_e32 v156, 16, v157
	v_and_b32_e32 v157, 0xffff0000, v157
	v_lshlrev_b32_e32 v158, 16, v159
	v_and_b32_e32 v159, 0xffff0000, v159
	v_pk_fma_f32 v[116:117], v[116:117], v[132:133], v[164:165]
	v_pk_fma_f32 v[112:113], v[112:113], v[128:129], v[166:167]
	v_pk_fma_f32 v[118:119], v[118:119], v[134:135], v[156:157]
	v_pk_fma_f32 v[156:157], v[114:115], v[130:131], v[158:159]
	v_cvt_pk_bf16_f32 v114, v116, v117
	v_cvt_pk_bf16_f32 v115, v118, v119
	v_cvt_pk_bf16_f32 v116, v112, v113
	v_lshl_add_u64 v[112:113], s[8:9], 0, v[212:213]
	v_lshl_add_u64 v[112:113], v[112:113], 0, v[182:183]
	v_cvt_pk_bf16_f32 v117, v156, v157
	global_store_dwordx4 v[112:113], v[114:117], off sc1
	v_lshlrev_b32_e32 v118, 16, v154
	v_and_b32_e32 v119, 0xffff0000, v154
	v_lshlrev_b32_e32 v114, 16, v152
	v_and_b32_e32 v115, 0xffff0000, v152
	v_lshlrev_b32_e32 v116, 16, v153
	v_and_b32_e32 v117, 0xffff0000, v153
	v_lshlrev_b32_e32 v152, 16, v155
	v_and_b32_e32 v153, 0xffff0000, v155
	v_pk_fma_f32 v[108:109], v[108:109], v[132:133], v[114:115]
	v_pk_fma_f32 v[104:105], v[104:105], v[128:129], v[118:119]
	v_pk_fma_f32 v[110:111], v[110:111], v[134:135], v[116:117]
	v_pk_fma_f32 v[114:115], v[106:107], v[130:131], v[152:153]
	v_cvt_pk_bf16_f32 v106, v108, v109
	v_cvt_pk_bf16_f32 v107, v110, v111
	v_cvt_pk_bf16_f32 v108, v104, v105
	v_lshl_add_u64 v[104:105], s[8:9], 0, v[208:209]
	v_lshl_add_u64 v[104:105], v[104:105], 0, v[182:183]
	v_cvt_pk_bf16_f32 v109, v114, v115
	global_store_dwordx4 v[104:105], v[106:109], off sc1
	v_lshlrev_b32_e32 v110, 16, v150
	v_and_b32_e32 v111, 0xffff0000, v150
	v_lshlrev_b32_e32 v106, 16, v148
	v_and_b32_e32 v107, 0xffff0000, v148
	v_lshlrev_b32_e32 v108, 16, v149
	v_and_b32_e32 v109, 0xffff0000, v149
	v_lshlrev_b32_e32 v114, 16, v151
	v_and_b32_e32 v115, 0xffff0000, v151
	v_pk_fma_f32 v[100:101], v[100:101], v[132:133], v[106:107]
	v_pk_fma_f32 v[96:97], v[96:97], v[128:129], v[110:111]
	v_pk_fma_f32 v[102:103], v[102:103], v[134:135], v[108:109]
	v_pk_fma_f32 v[106:107], v[98:99], v[130:131], v[114:115]
	v_cvt_pk_bf16_f32 v98, v100, v101
	v_cvt_pk_bf16_f32 v99, v102, v103
	v_cvt_pk_bf16_f32 v100, v96, v97
	v_lshl_add_u64 v[96:97], s[8:9], 0, v[206:207]
	v_lshl_add_u64 v[96:97], v[96:97], 0, v[182:183]
	v_cvt_pk_bf16_f32 v101, v106, v107
	global_store_dwordx4 v[96:97], v[98:101], off sc1
	v_lshlrev_b32_e32 v102, 16, v146
	v_and_b32_e32 v103, 0xffff0000, v146
	v_lshlrev_b32_e32 v98, 16, v144
	v_and_b32_e32 v99, 0xffff0000, v144
	v_lshlrev_b32_e32 v100, 16, v145
	v_and_b32_e32 v101, 0xffff0000, v145
	v_lshlrev_b32_e32 v106, 16, v147
	v_and_b32_e32 v107, 0xffff0000, v147
	v_pk_fma_f32 v[92:93], v[92:93], v[132:133], v[98:99]
	v_pk_fma_f32 v[94:95], v[94:95], v[134:135], v[100:101]
	v_pk_fma_f32 v[98:99], v[90:91], v[130:131], v[106:107]
	v_pk_fma_f32 v[90:91], v[88:89], v[128:129], v[102:103]
	v_cvt_pk_bf16_f32 v88, v92, v93
	v_lshl_add_u64 v[92:93], s[8:9], 0, v[204:205]
	v_cvt_pk_bf16_f32 v89, v94, v95
	v_lshl_add_u64 v[94:95], v[92:93], 0, v[182:183]
	v_cvt_pk_bf16_f32 v90, v90, v91
	v_cvt_pk_bf16_f32 v91, v98, v99
	global_store_dwordx4 v[94:95], v[88:91], off sc1
	v_lshlrev_b32_e32 v92, 16, v138
	v_and_b32_e32 v93, 0xffff0000, v138
	v_lshlrev_b32_e32 v88, 16, v136
	v_and_b32_e32 v89, 0xffff0000, v136
	v_lshlrev_b32_e32 v98, 16, v139
	v_and_b32_e32 v99, 0xffff0000, v139
	v_pk_fma_f32 v[84:85], v[84:85], v[132:133], v[88:89]
	v_lshlrev_b32_e32 v90, 16, v137
	v_and_b32_e32 v91, 0xffff0000, v137
	v_pk_fma_f32 v[88:89], v[82:83], v[130:131], v[98:99]
	v_pk_fma_f32 v[82:83], v[80:81], v[128:129], v[92:93]
	v_cvt_pk_bf16_f32 v80, v84, v85
	v_lshl_add_u64 v[84:85], s[8:9], 0, v[200:201]
	v_pk_fma_f32 v[86:87], v[86:87], v[134:135], v[90:91]
	v_lshl_add_u64 v[92:93], v[84:85], 0, v[182:183]
	v_cvt_pk_bf16_f32 v81, v86, v87
	v_cvt_pk_bf16_f32 v82, v82, v83
	v_cvt_pk_bf16_f32 v83, v88, v89
	global_store_dwordx4 v[92:93], v[80:83], off sc1
	v_lshlrev_b32_e32 v84, 16, v142
	v_and_b32_e32 v85, 0xffff0000, v142
	v_lshlrev_b32_e32 v80, 16, v140
	v_and_b32_e32 v81, 0xffff0000, v140
	v_lshlrev_b32_e32 v86, 16, v143
	v_and_b32_e32 v87, 0xffff0000, v143
	v_pk_fma_f32 v[76:77], v[76:77], v[132:133], v[80:81]
	v_lshlrev_b32_e32 v82, 16, v141
	v_and_b32_e32 v83, 0xffff0000, v141
	v_pk_fma_f32 v[80:81], v[74:75], v[130:131], v[86:87]
	v_pk_fma_f32 v[74:75], v[72:73], v[128:129], v[84:85]
	v_cvt_pk_bf16_f32 v72, v76, v77
	v_lshl_add_u64 v[76:77], s[8:9], 0, v[202:203]
	v_pk_fma_f32 v[78:79], v[78:79], v[134:135], v[82:83]
	v_lshl_add_u64 v[88:89], v[76:77], 0, v[182:183]
	v_cvt_pk_bf16_f32 v73, v78, v79
	v_cvt_pk_bf16_f32 v74, v74, v75
	v_cvt_pk_bf16_f32 v75, v80, v81
	global_store_dwordx4 v[88:89], v[72:75], off sc1
	s_waitcnt vmcnt(6)
	v_lshlrev_b32_e32 v76, 16, v122
	v_and_b32_e32 v77, 0xffff0000, v122
	v_lshlrev_b32_e32 v72, 16, v120
	v_and_b32_e32 v73, 0xffff0000, v120
	v_lshlrev_b32_e32 v78, 16, v123
	v_and_b32_e32 v79, 0xffff0000, v123
	v_pk_fma_f32 v[68:69], v[68:69], v[132:133], v[72:73]
	v_pk_fma_f32 v[72:73], v[66:67], v[130:131], v[78:79]
	v_pk_fma_f32 v[66:67], v[64:65], v[128:129], v[76:77]
	v_cvt_pk_bf16_f32 v64, v68, v69
	v_lshl_add_u64 v[68:69], s[8:9], 0, v[210:211]
	v_lshlrev_b32_e32 v74, 16, v121
	v_and_b32_e32 v75, 0xffff0000, v121
	v_lshl_add_u64 v[90:91], v[68:69], 0, v[182:183]
	v_pk_fma_f32 v[70:71], v[70:71], v[134:135], v[74:75]
	s_mov_b64 s[8:9], s[58:59]
	v_cvt_pk_bf16_f32 v65, v70, v71
	v_cvt_pk_bf16_f32 v66, v66, v67
	v_cvt_pk_bf16_f32 v67, v72, v73
	global_store_dwordx4 v[90:91], v[64:67], off sc1
	global_load_dwordx4 v[98:101], v[184:185], off offset:256
	global_load_dwordx4 v[106:109], v[186:187], off offset:256
	global_load_dwordx4 v[114:117], v[188:189], off offset:256
	global_load_dwordx4 v[84:87], v[190:191], off offset:256
	global_load_dwordx4 v[80:83], v[192:193], off offset:256
	global_load_dwordx4 v[76:79], v[194:195], off offset:256
	global_load_dwordx4 v[64:67], v[198:199], off offset:528
	global_load_dwordx4 v[68:71], v[198:199], off offset:512
	global_load_dwordx4 v[72:75], v[196:197], off offset:256
	s_waitcnt vmcnt(0)
	v_lshlrev_b32_e32 v102, 16, v98
	v_and_b32_e32 v103, 0xffff0000, v98
	v_lshlrev_b32_e32 v98, 16, v99
	v_and_b32_e32 v99, 0xffff0000, v99
	v_lshlrev_b32_e32 v110, 16, v100
	v_and_b32_e32 v111, 0xffff0000, v100
	v_lshlrev_b32_e32 v100, 16, v101
	v_and_b32_e32 v101, 0xffff0000, v101
	v_pk_fma_f32 v[62:63], v[62:63], v[70:71], v[98:99]
	v_pk_fma_f32 v[98:99], v[58:59], v[66:67], v[100:101]
	v_pk_fma_f32 v[58:59], v[56:57], v[64:65], v[110:111]
	v_pk_fma_f32 v[60:61], v[60:61], v[68:69], v[102:103]
	v_lshlrev_b32_e32 v100, 16, v109
	v_cvt_pk_bf16_f32 v56, v60, v61
	v_cvt_pk_bf16_f32 v57, v62, v63
	v_cvt_pk_bf16_f32 v58, v58, v59
	v_cvt_pk_bf16_f32 v59, v98, v99
	global_store_dwordx4 v[124:125], v[56:59], off offset:256 sc1
	global_load_dwordx4 v[56:59], v[126:127], off offset:256
	v_lshlrev_b32_e32 v60, 16, v106
	v_and_b32_e32 v61, 0xffff0000, v106
	v_lshlrev_b32_e32 v98, 16, v108
	v_and_b32_e32 v99, 0xffff0000, v108
	v_and_b32_e32 v101, 0xffff0000, v109
	v_lshlrev_b32_e32 v62, 16, v107
	v_and_b32_e32 v63, 0xffff0000, v107
	v_pk_fma_f32 v[52:53], v[52:53], v[68:69], v[60:61]
	v_pk_fma_f32 v[60:61], v[50:51], v[66:67], v[100:101]
	v_pk_fma_f32 v[50:51], v[48:49], v[64:65], v[98:99]
	v_pk_fma_f32 v[54:55], v[54:55], v[70:71], v[62:63]
	v_cvt_pk_bf16_f32 v48, v52, v53
	v_lshlrev_b32_e32 v52, 16, v116
	v_cvt_pk_bf16_f32 v49, v54, v55
	v_cvt_pk_bf16_f32 v50, v50, v51
	v_cvt_pk_bf16_f32 v51, v60, v61
	global_store_dwordx4 v[112:113], v[48:51], off offset:256 sc1
	v_and_b32_e32 v53, 0xffff0000, v116
	v_lshlrev_b32_e32 v54, 16, v117
	v_lshlrev_b32_e32 v48, 16, v114
	v_and_b32_e32 v49, 0xffff0000, v114
	v_lshlrev_b32_e32 v50, 16, v115
	v_and_b32_e32 v51, 0xffff0000, v115
	v_and_b32_e32 v55, 0xffff0000, v117
	v_pk_fma_f32 v[46:47], v[46:47], v[70:71], v[50:51]
	v_pk_fma_f32 v[44:45], v[44:45], v[68:69], v[48:49]
	v_pk_fma_f32 v[48:49], v[42:43], v[66:67], v[54:55]
	v_pk_fma_f32 v[42:43], v[40:41], v[64:65], v[52:53]
	v_cvt_pk_bf16_f32 v40, v44, v45
	v_cvt_pk_bf16_f32 v41, v46, v47
	v_lshlrev_b32_e32 v44, 16, v86
	v_cvt_pk_bf16_f32 v42, v42, v43
	v_cvt_pk_bf16_f32 v43, v48, v49
	global_store_dwordx4 v[104:105], v[40:43], off offset:256 sc1
	v_and_b32_e32 v45, 0xffff0000, v86
	v_lshlrev_b32_e32 v46, 16, v87
	v_lshlrev_b32_e32 v40, 16, v84
	v_and_b32_e32 v41, 0xffff0000, v84
	v_and_b32_e32 v47, 0xffff0000, v87
	v_lshlrev_b32_e32 v42, 16, v85
	v_and_b32_e32 v43, 0xffff0000, v85
	v_pk_fma_f32 v[36:37], v[36:37], v[68:69], v[40:41]
	v_pk_fma_f32 v[40:41], v[34:35], v[66:67], v[46:47]
	v_pk_fma_f32 v[34:35], v[32:33], v[64:65], v[44:45]
	v_pk_fma_f32 v[38:39], v[38:39], v[70:71], v[42:43]
	v_cvt_pk_bf16_f32 v32, v36, v37
	v_lshlrev_b32_e32 v36, 16, v82
	v_cvt_pk_bf16_f32 v33, v38, v39
	v_cvt_pk_bf16_f32 v34, v34, v35
	v_cvt_pk_bf16_f32 v35, v40, v41
	global_store_dwordx4 v[96:97], v[32:35], off offset:256 sc1
	v_and_b32_e32 v37, 0xffff0000, v82
	v_lshlrev_b32_e32 v38, 16, v83
	v_lshlrev_b32_e32 v32, 16, v80
	v_and_b32_e32 v33, 0xffff0000, v80
	v_lshlrev_b32_e32 v34, 16, v81
	v_and_b32_e32 v35, 0xffff0000, v81
	v_and_b32_e32 v39, 0xffff0000, v83
	v_pk_fma_f32 v[30:31], v[30:31], v[70:71], v[34:35]
	v_pk_fma_f32 v[28:29], v[28:29], v[68:69], v[32:33]
	v_pk_fma_f32 v[32:33], v[26:27], v[66:67], v[38:39]
	v_pk_fma_f32 v[26:27], v[24:25], v[64:65], v[36:37]
	v_cvt_pk_bf16_f32 v24, v28, v29
	v_cvt_pk_bf16_f32 v25, v30, v31
	v_lshlrev_b32_e32 v28, 16, v78
	v_cvt_pk_bf16_f32 v26, v26, v27
	v_cvt_pk_bf16_f32 v27, v32, v33
	global_store_dwordx4 v[94:95], v[24:27], off offset:256 sc1
	v_and_b32_e32 v29, 0xffff0000, v78
	v_lshlrev_b32_e32 v30, 16, v79
	v_lshlrev_b32_e32 v24, 16, v76
	v_and_b32_e32 v25, 0xffff0000, v76
	v_and_b32_e32 v31, 0xffff0000, v79
	v_lshlrev_b32_e32 v26, 16, v77
	v_and_b32_e32 v27, 0xffff0000, v77
	v_pk_fma_f32 v[20:21], v[20:21], v[68:69], v[24:25]
	v_pk_fma_f32 v[24:25], v[18:19], v[66:67], v[30:31]
	v_pk_fma_f32 v[18:19], v[16:17], v[64:65], v[28:29]
	v_pk_fma_f32 v[22:23], v[22:23], v[70:71], v[26:27]
	v_cvt_pk_bf16_f32 v16, v20, v21
	v_lshlrev_b32_e32 v20, 16, v74
	v_cvt_pk_bf16_f32 v17, v22, v23
	v_cvt_pk_bf16_f32 v18, v18, v19
	v_cvt_pk_bf16_f32 v19, v24, v25
	global_store_dwordx4 v[92:93], v[16:19], off offset:256 sc1
	v_and_b32_e32 v21, 0xffff0000, v74
	v_lshlrev_b32_e32 v22, 16, v75
	v_lshlrev_b32_e32 v16, 16, v72
	v_and_b32_e32 v17, 0xffff0000, v72
	v_lshlrev_b32_e32 v18, 16, v73
	v_and_b32_e32 v19, 0xffff0000, v73
	v_and_b32_e32 v23, 0xffff0000, v75
	v_pk_fma_f32 v[14:15], v[14:15], v[70:71], v[18:19]
	v_pk_fma_f32 v[12:13], v[12:13], v[68:69], v[16:17]
	v_pk_fma_f32 v[16:17], v[10:11], v[66:67], v[22:23]
	v_pk_fma_f32 v[10:11], v[8:9], v[64:65], v[20:21]
	v_cvt_pk_bf16_f32 v8, v12, v13
	v_cvt_pk_bf16_f32 v9, v14, v15
	s_waitcnt vmcnt(5)
	v_lshlrev_b32_e32 v12, 16, v58
	v_cvt_pk_bf16_f32 v10, v10, v11
	v_cvt_pk_bf16_f32 v11, v16, v17
	global_store_dwordx4 v[88:89], v[8:11], off offset:256 sc1
	v_and_b32_e32 v13, 0xffff0000, v58
	v_lshlrev_b32_e32 v14, 16, v59
	v_lshlrev_b32_e32 v8, 16, v56
	v_and_b32_e32 v9, 0xffff0000, v56
	v_and_b32_e32 v15, 0xffff0000, v59
	v_lshlrev_b32_e32 v10, 16, v57
	v_and_b32_e32 v11, 0xffff0000, v57
	v_pk_fma_f32 v[4:5], v[4:5], v[68:69], v[8:9]
	v_pk_fma_f32 v[8:9], v[2:3], v[66:67], v[14:15]
	v_pk_fma_f32 v[2:3], v[0:1], v[64:65], v[12:13]
	v_pk_fma_f32 v[6:7], v[6:7], v[70:71], v[10:11]
	v_cvt_pk_bf16_f32 v0, v4, v5
	s_nop 0
	v_cvt_pk_bf16_f32 v1, v6, v7
	v_cvt_pk_bf16_f32 v2, v2, v3
	v_cvt_pk_bf16_f32 v3, v8, v9
	global_store_dwordx4 v[90:91], v[0:3], off offset:256 sc1
	s_cbranch_vccz .LBB0_103
	s_waitcnt vmcnt(0)
	s_mov_b32 s90, s62
	s_cmpk_gt_u32 s36, 0xff
	s_cbranch_scc1 .LBB0_114
	s_barrier

.LBB0_130:
	s_add_u32 s8, s60, 0xfffc0080
	s_addc_u32 s9, s61, -1
	s_add_i32 s16, 0, 0x10000
	v_add_u32_e32 v150, s16, v168
	ds_read_b128 v[128:131], v150
	ds_read_b128 v[132:135], v150 offset:1024
	ds_read_b128 v[146:149], v150 offset:2048
	ds_read_b128 v[150:153], v150 offset:3072
	s_cmp_eq_u32 s15, 12
	s_cselect_b32 s9, s5, s9
	s_cselect_b32 s8, s10, s8
	s_cselect_b32 s63, s1, s14
	s_cselect_b32 s62, s12, s13
	v_lshl_add_u64 v[164:165], s[60:61], 0, v[142:143]
	s_add_i32 m0, s38, 0xc000
	ds_read_b128 v[154:157], v170
	ds_read_b128 v[172:175], v170 offset:1024
	ds_read_b128 v[176:179], v170 offset:2048
	ds_read_b128 v[180:183], v170 offset:3072
	ds_read_b128 v[184:187], v170 offset:4096
	ds_read_b128 v[188:191], v170 offset:5120
	ds_read_b128 v[192:195], v170 offset:6144
	ds_read_b128 v[196:199], v170 offset:7168
	global_load_lds_dwordx4 v[164:165], off
	v_lshl_add_u64 v[164:165], s[60:61], 0, v[144:145]
	s_add_i32 m0, s38, 0xe000
	s_nop 0
	global_load_lds_dwordx4 v[164:165], off
	s_waitcnt lgkmcnt(8)
	s_barrier
	s_waitcnt lgkmcnt(0)
	s_setprio 1
	s_waitcnt lgkmcnt(0)
	v_mfma_f32_16x16x32_bf16 v[124:127], v[128:131], v[154:157], v[124:127]
	v_mfma_f32_16x16x32_bf16 v[120:123], v[146:149], v[154:157], v[120:123]
	v_mfma_f32_16x16x32_bf16 v[116:119], v[128:131], v[176:179], v[116:119]
	v_mfma_f32_16x16x32_bf16 v[112:115], v[146:149], v[176:179], v[112:115]
	v_mfma_f32_16x16x32_bf16 v[108:111], v[128:131], v[184:187], v[108:111]
	v_mfma_f32_16x16x32_bf16 v[104:107], v[146:149], v[184:187], v[104:107]
	v_mfma_f32_16x16x32_bf16 v[100:103], v[128:131], v[192:195], v[100:103]
	v_mfma_f32_16x16x32_bf16 v[96:99], v[146:149], v[192:195], v[96:99]
	v_mfma_f32_16x16x32_bf16 v[124:127], v[132:135], v[172:175], v[124:127]
	v_mfma_f32_16x16x32_bf16 v[120:123], v[150:153], v[172:175], v[120:123]
	v_mfma_f32_16x16x32_bf16 v[116:119], v[132:135], v[180:183], v[116:119]
	v_mfma_f32_16x16x32_bf16 v[112:115], v[150:153], v[180:183], v[112:115]
	v_mfma_f32_16x16x32_bf16 v[108:111], v[132:135], v[188:191], v[108:111]
	v_mfma_f32_16x16x32_bf16 v[104:107], v[150:153], v[188:191], v[104:107]
	v_mfma_f32_16x16x32_bf16 v[100:103], v[132:135], v[196:199], v[100:103]
	v_mfma_f32_16x16x32_bf16 v[96:99], v[150:153], v[196:199], v[96:99]
	s_setprio 0
	s_barrier
	s_add_i32 s18, 0, 0x14000
	s_add_i32 s16, s16, s37
	v_add_u32_e32 v158, s18, v168
	v_lshl_add_u64 v[164:165], s[62:63], 0, v[160:161]
	s_mov_b32 m0, s16
	ds_read_b128 v[200:203], v158
	ds_read_b128 v[204:207], v158 offset:1024
	ds_read_b128 v[208:211], v158 offset:2048
	ds_read_b128 v[212:215], v158 offset:3072
	global_load_lds_dwordx4 v[164:165], off
	v_lshl_add_u64 v[166:167], s[62:63], 0, v[136:137]
	s_add_i32 m0, s16, 0x2000
	s_nop 0
	global_load_lds_dwordx4 v[166:167], off
	s_barrier
	s_waitcnt lgkmcnt(0)
	s_setprio 1
	s_waitcnt lgkmcnt(0)
	v_mfma_f32_16x16x32_bf16 v[68:71], v[200:203], v[154:157], v[68:71]
	v_mfma_f32_16x16x32_bf16 v[64:67], v[208:211], v[154:157], v[64:67]
	v_mfma_f32_16x16x32_bf16 v[52:55], v[200:203], v[176:179], v[52:55]
	v_mfma_f32_16x16x32_bf16 v[48:51], v[208:211], v[176:179], v[48:51]
	v_mfma_f32_16x16x32_bf16 v[44:47], v[200:203], v[184:187], v[44:47]
	v_mfma_f32_16x16x32_bf16 v[40:43], v[208:211], v[184:187], v[40:43]
	v_mfma_f32_16x16x32_bf16 v[36:39], v[200:203], v[192:195], v[36:39]
	v_mfma_f32_16x16x32_bf16 v[32:35], v[208:211], v[192:195], v[32:35]
	v_mfma_f32_16x16x32_bf16 v[68:71], v[204:207], v[172:175], v[68:71]
	v_mfma_f32_16x16x32_bf16 v[64:67], v[212:215], v[172:175], v[64:67]
	v_mfma_f32_16x16x32_bf16 v[52:55], v[204:207], v[180:183], v[52:55]
	v_mfma_f32_16x16x32_bf16 v[48:51], v[212:215], v[180:183], v[48:51]
	v_mfma_f32_16x16x32_bf16 v[44:47], v[204:207], v[188:191], v[44:47]
	v_mfma_f32_16x16x32_bf16 v[40:43], v[212:215], v[188:191], v[40:43]
	v_mfma_f32_16x16x32_bf16 v[36:39], v[204:207], v[196:199], v[36:39]
	v_mfma_f32_16x16x32_bf16 v[32:35], v[212:215], v[196:199], v[32:35]
	s_setprio 0
	s_mov_b32 m0, s38
	v_lshl_add_u64 v[216:217], s[8:9], 0, v[140:141]
	s_barrier
	ds_read_b128 v[154:157], v170 offset:16384
	ds_read_b128 v[172:175], v170 offset:17408
	ds_read_b128 v[176:179], v170 offset:18432
	ds_read_b128 v[180:183], v170 offset:19456
	ds_read_b128 v[184:187], v170 offset:20480
	ds_read_b128 v[188:191], v170 offset:21504
	ds_read_b128 v[192:195], v170 offset:22528
	ds_read_b128 v[196:199], v170 offset:23552
	global_load_lds_dwordx4 v[216:217], off
	v_lshl_add_u64 v[218:219], s[8:9], 0, v[138:139]
	s_mov_b32 m0, s39
	s_nop 0
	global_load_lds_dwordx4 v[218:219], off
	s_barrier
	s_waitcnt lgkmcnt(0)
	s_setprio 1
	s_waitcnt lgkmcnt(0)
	v_mfma_f32_16x16x32_bf16 v[92:95], v[128:131], v[154:157], v[92:95]
	v_mfma_f32_16x16x32_bf16 v[88:91], v[146:149], v[154:157], v[88:91]
	v_mfma_f32_16x16x32_bf16 v[84:87], v[128:131], v[176:179], v[84:87]
	v_mfma_f32_16x16x32_bf16 v[80:83], v[146:149], v[176:179], v[80:83]
	v_mfma_f32_16x16x32_bf16 v[76:79], v[128:131], v[184:187], v[76:79]
	v_mfma_f32_16x16x32_bf16 v[72:75], v[146:149], v[184:187], v[72:75]
	v_mfma_f32_16x16x32_bf16 v[60:63], v[128:131], v[192:195], v[60:63]
	v_mfma_f32_16x16x32_bf16 v[56:59], v[146:149], v[192:195], v[56:59]
	v_mfma_f32_16x16x32_bf16 v[92:95], v[132:135], v[172:175], v[92:95]
	v_mfma_f32_16x16x32_bf16 v[88:91], v[150:153], v[172:175], v[88:91]
	v_mfma_f32_16x16x32_bf16 v[84:87], v[132:135], v[180:183], v[84:87]
	v_mfma_f32_16x16x32_bf16 v[80:83], v[150:153], v[180:183], v[80:83]
	v_mfma_f32_16x16x32_bf16 v[76:79], v[132:135], v[188:191], v[76:79]
	v_mfma_f32_16x16x32_bf16 v[72:75], v[150:153], v[188:191], v[72:75]
	v_mfma_f32_16x16x32_bf16 v[60:63], v[132:135], v[196:199], v[60:63]
	v_mfma_f32_16x16x32_bf16 v[56:59], v[150:153], v[196:199], v[56:59]
	s_setprio 0
	s_barrier
	s_add_u32 s16, s62, 0x40000
	s_addc_u32 s17, s63, 0
	s_add_i32 s18, s18, s37
	v_lshl_add_u64 v[128:129], s[16:17], 0, v[160:161]
	s_mov_b32 m0, s18
	s_nop 0
	global_load_lds_dwordx4 v[128:129], off
	v_lshl_add_u64 v[128:129], s[16:17], 0, v[136:137]
	s_add_i32 m0, s18, 0x2000
	s_nop 0
	global_load_lds_dwordx4 v[128:129], off
	s_waitcnt vmcnt(6)
	s_barrier
	s_setprio 1
	v_mfma_f32_16x16x32_bf16 v[28:31], v[200:203], v[154:157], v[28:31]
	v_mfma_f32_16x16x32_bf16 v[24:27], v[208:211], v[154:157], v[24:27]
	v_mfma_f32_16x16x32_bf16 v[20:23], v[200:203], v[176:179], v[20:23]
	v_mfma_f32_16x16x32_bf16 v[16:19], v[208:211], v[176:179], v[16:19]
	v_mfma_f32_16x16x32_bf16 v[12:15], v[200:203], v[184:187], v[12:15]
	v_mfma_f32_16x16x32_bf16 v[8:11], v[208:211], v[184:187], v[8:11]
	v_mfma_f32_16x16x32_bf16 v[4:7], v[200:203], v[192:195], v[4:7]
	v_mfma_f32_16x16x32_bf16 v[0:3], v[208:211], v[192:195], v[0:3]
	v_mfma_f32_16x16x32_bf16 v[28:31], v[204:207], v[172:175], v[28:31]
	v_mfma_f32_16x16x32_bf16 v[24:27], v[212:215], v[172:175], v[24:27]
	v_mfma_f32_16x16x32_bf16 v[20:23], v[204:207], v[180:183], v[20:23]
	v_mfma_f32_16x16x32_bf16 v[16:19], v[212:215], v[180:183], v[16:19]
	v_mfma_f32_16x16x32_bf16 v[12:15], v[204:207], v[188:191], v[12:15]
	v_mfma_f32_16x16x32_bf16 v[8:11], v[212:215], v[188:191], v[8:11]
	v_mfma_f32_16x16x32_bf16 v[4:7], v[204:207], v[196:199], v[4:7]
	v_mfma_f32_16x16x32_bf16 v[0:3], v[212:215], v[196:199], v[0:3]
	s_setprio 0
	s_add_i32 s16, 0, 0x18000
	v_add_u32_e32 v150, s16, v168
	s_barrier
	ds_read_b128 v[128:131], v150
	ds_read_b128 v[132:135], v150 offset:1024
	ds_read_b128 v[146:149], v150 offset:2048
	ds_read_b128 v[150:153], v150 offset:3072
	s_add_u32 s8, s8, 0x40000
	s_addc_u32 s9, s9, 0
	s_mov_b32 m0, s40
	v_lshl_add_u64 v[200:201], s[8:9], 0, v[140:141]
	ds_read_b128 v[154:157], v170 offset:32768
	ds_read_b128 v[172:175], v170 offset:33792
	ds_read_b128 v[176:179], v170 offset:34816
	ds_read_b128 v[180:183], v170 offset:35840
	ds_read_b128 v[184:187], v170 offset:36864
	ds_read_b128 v[188:191], v170 offset:37888
	ds_read_b128 v[192:195], v170 offset:38912
	ds_read_b128 v[196:199], v170 offset:39936
	global_load_lds_dwordx4 v[200:201], off
	v_lshl_add_u64 v[200:201], s[8:9], 0, v[138:139]
	s_mov_b32 m0, s41
	s_nop 0
	global_load_lds_dwordx4 v[200:201], off
	s_waitcnt lgkmcnt(8)
	s_barrier
	s_waitcnt lgkmcnt(0)
	s_setprio 1
	s_waitcnt lgkmcnt(0)
	v_mfma_f32_16x16x32_bf16 v[124:127], v[128:131], v[154:157], v[124:127]
	v_mfma_f32_16x16x32_bf16 v[120:123], v[146:149], v[154:157], v[120:123]
	v_mfma_f32_16x16x32_bf16 v[116:119], v[128:131], v[176:179], v[116:119]
	v_mfma_f32_16x16x32_bf16 v[112:115], v[146:149], v[176:179], v[112:115]
	v_mfma_f32_16x16x32_bf16 v[108:111], v[128:131], v[184:187], v[108:111]
	v_mfma_f32_16x16x32_bf16 v[104:107], v[146:149], v[184:187], v[104:107]
	v_mfma_f32_16x16x32_bf16 v[100:103], v[128:131], v[192:195], v[100:103]
	v_mfma_f32_16x16x32_bf16 v[96:99], v[146:149], v[192:195], v[96:99]
	v_mfma_f32_16x16x32_bf16 v[124:127], v[132:135], v[172:175], v[124:127]
	v_mfma_f32_16x16x32_bf16 v[120:123], v[150:153], v[172:175], v[120:123]
	v_mfma_f32_16x16x32_bf16 v[116:119], v[132:135], v[180:183], v[116:119]
	v_mfma_f32_16x16x32_bf16 v[112:115], v[150:153], v[180:183], v[112:115]
	v_mfma_f32_16x16x32_bf16 v[108:111], v[132:135], v[188:191], v[108:111]
	v_mfma_f32_16x16x32_bf16 v[104:107], v[150:153], v[188:191], v[104:107]
	v_mfma_f32_16x16x32_bf16 v[100:103], v[132:135], v[196:199], v[100:103]
	v_mfma_f32_16x16x32_bf16 v[96:99], v[150:153], v[196:199], v[96:99]
	s_setprio 0
	s_barrier
	s_add_i32 s17, 0, 0x1c000
	s_add_i32 s8, s16, s37
	v_add_u32_e32 v158, s17, v168
	v_lshl_add_u64 v[164:165], v[164:165], 0, s[74:75]
	s_mov_b32 m0, s8
	ds_read_b128 v[200:203], v158
	ds_read_b128 v[204:207], v158 offset:1024
	ds_read_b128 v[208:211], v158 offset:2048
	ds_read_b128 v[212:215], v158 offset:3072
	global_load_lds_dwordx4 v[164:165], off
	v_lshl_add_u64 v[164:165], v[166:167], 0, s[74:75]
	s_add_i32 m0, s8, 0x2000
	s_nop 0
	global_load_lds_dwordx4 v[164:165], off
	s_barrier
	s_waitcnt lgkmcnt(0)
	s_setprio 1
	s_waitcnt lgkmcnt(0)
	v_mfma_f32_16x16x32_bf16 v[68:71], v[200:203], v[154:157], v[68:71]
	v_mfma_f32_16x16x32_bf16 v[64:67], v[208:211], v[154:157], v[64:67]
	v_mfma_f32_16x16x32_bf16 v[52:55], v[200:203], v[176:179], v[52:55]
	v_mfma_f32_16x16x32_bf16 v[48:51], v[208:211], v[176:179], v[48:51]
	v_mfma_f32_16x16x32_bf16 v[44:47], v[200:203], v[184:187], v[44:47]
	v_mfma_f32_16x16x32_bf16 v[40:43], v[208:211], v[184:187], v[40:43]
	v_mfma_f32_16x16x32_bf16 v[36:39], v[200:203], v[192:195], v[36:39]
	v_mfma_f32_16x16x32_bf16 v[32:35], v[208:211], v[192:195], v[32:35]
	v_mfma_f32_16x16x32_bf16 v[68:71], v[204:207], v[172:175], v[68:71]
	v_mfma_f32_16x16x32_bf16 v[64:67], v[212:215], v[172:175], v[64:67]
	v_mfma_f32_16x16x32_bf16 v[52:55], v[204:207], v[180:183], v[52:55]
	v_mfma_f32_16x16x32_bf16 v[48:51], v[212:215], v[180:183], v[48:51]
	v_mfma_f32_16x16x32_bf16 v[44:47], v[204:207], v[188:191], v[44:47]
	v_mfma_f32_16x16x32_bf16 v[40:43], v[212:215], v[188:191], v[40:43]
	v_mfma_f32_16x16x32_bf16 v[36:39], v[204:207], v[196:199], v[36:39]
	v_mfma_f32_16x16x32_bf16 v[32:35], v[212:215], v[196:199], v[32:35]
	s_setprio 0
	s_mov_b32 m0, s42
	v_lshl_add_u64 v[164:165], v[216:217], 0, s[74:75]
	s_barrier
	ds_read_b128 v[154:157], v170 offset:49152
	ds_read_b128 v[172:175], v170 offset:50176
	ds_read_b128 v[176:179], v170 offset:51200
	ds_read_b128 v[180:183], v170 offset:52224
	ds_read_b128 v[184:187], v170 offset:53248
	ds_read_b128 v[188:191], v170 offset:54272
	ds_read_b128 v[192:195], v170 offset:55296
	ds_read_b128 v[196:199], v170 offset:56320
	global_load_lds_dwordx4 v[164:165], off
	v_lshl_add_u64 v[164:165], v[218:219], 0, s[74:75]
	s_mov_b32 m0, s43
	s_nop 0
	global_load_lds_dwordx4 v[164:165], off
	s_barrier
	s_waitcnt lgkmcnt(0)
	s_setprio 1
	s_waitcnt lgkmcnt(0)
	v_mfma_f32_16x16x32_bf16 v[92:95], v[128:131], v[154:157], v[92:95]
	v_mfma_f32_16x16x32_bf16 v[88:91], v[146:149], v[154:157], v[88:91]
	v_mfma_f32_16x16x32_bf16 v[84:87], v[128:131], v[176:179], v[84:87]
	v_mfma_f32_16x16x32_bf16 v[80:83], v[146:149], v[176:179], v[80:83]
	v_mfma_f32_16x16x32_bf16 v[76:79], v[128:131], v[184:187], v[76:79]
	v_mfma_f32_16x16x32_bf16 v[72:75], v[146:149], v[184:187], v[72:75]
	v_mfma_f32_16x16x32_bf16 v[60:63], v[128:131], v[192:195], v[60:63]
	v_mfma_f32_16x16x32_bf16 v[56:59], v[146:149], v[192:195], v[56:59]
	v_mfma_f32_16x16x32_bf16 v[92:95], v[132:135], v[172:175], v[92:95]
	v_mfma_f32_16x16x32_bf16 v[88:91], v[150:153], v[172:175], v[88:91]
	v_mfma_f32_16x16x32_bf16 v[84:87], v[132:135], v[180:183], v[84:87]
	v_mfma_f32_16x16x32_bf16 v[80:83], v[150:153], v[180:183], v[80:83]
	v_mfma_f32_16x16x32_bf16 v[76:79], v[132:135], v[188:191], v[76:79]
	v_mfma_f32_16x16x32_bf16 v[72:75], v[150:153], v[188:191], v[72:75]
	v_mfma_f32_16x16x32_bf16 v[60:63], v[132:135], v[196:199], v[60:63]
	v_mfma_f32_16x16x32_bf16 v[56:59], v[150:153], v[196:199], v[56:59]
	s_setprio 0
	s_barrier
	s_add_u32 s8, s62, 0x40080
	s_addc_u32 s9, s63, 0
	s_add_i32 s16, s17, s37
	v_lshl_add_u64 v[128:129], s[8:9], 0, v[160:161]
	s_mov_b32 m0, s16
	s_nop 0
	global_load_lds_dwordx4 v[128:129], off
	v_lshl_add_u64 v[128:129], s[8:9], 0, v[136:137]
	s_add_i32 m0, s16, 0x2000
	s_nop 0
	global_load_lds_dwordx4 v[128:129], off
	s_waitcnt vmcnt(6)
	s_barrier
	s_setprio 1
	v_mfma_f32_16x16x32_bf16 v[28:31], v[200:203], v[154:157], v[28:31]
	v_mfma_f32_16x16x32_bf16 v[24:27], v[208:211], v[154:157], v[24:27]
	v_mfma_f32_16x16x32_bf16 v[20:23], v[200:203], v[176:179], v[20:23]
	v_mfma_f32_16x16x32_bf16 v[16:19], v[208:211], v[176:179], v[16:19]
	v_mfma_f32_16x16x32_bf16 v[12:15], v[200:203], v[184:187], v[12:15]
	v_mfma_f32_16x16x32_bf16 v[8:11], v[208:211], v[184:187], v[8:11]
	v_mfma_f32_16x16x32_bf16 v[4:7], v[200:203], v[192:195], v[4:7]
	v_mfma_f32_16x16x32_bf16 v[0:3], v[208:211], v[192:195], v[0:3]
	v_mfma_f32_16x16x32_bf16 v[28:31], v[204:207], v[172:175], v[28:31]
	v_mfma_f32_16x16x32_bf16 v[24:27], v[212:215], v[172:175], v[24:27]
	v_mfma_f32_16x16x32_bf16 v[20:23], v[204:207], v[180:183], v[20:23]
	v_mfma_f32_16x16x32_bf16 v[16:19], v[212:215], v[180:183], v[16:19]
	v_mfma_f32_16x16x32_bf16 v[12:15], v[204:207], v[188:191], v[12:15]
	v_mfma_f32_16x16x32_bf16 v[8:11], v[212:215], v[188:191], v[8:11]
	v_mfma_f32_16x16x32_bf16 v[4:7], v[204:207], v[196:199], v[4:7]
	v_mfma_f32_16x16x32_bf16 v[0:3], v[212:215], v[196:199], v[0:3]
	s_setprio 0
	s_add_i32 s15, s15, 2
	s_add_u32 s60, s60, 0x100
	s_addc_u32 s61, s61, 0
	s_add_u32 s13, s13, 0x100
	s_addc_u32 s14, s14, 0
	s_cmp_gt_u32 s15, 13
	s_barrier
	s_cbranch_scc0 .LBB0_130
	v_lshl_add_u32 v146, s65, 8, v159
	v_readlane_b32 s8, v250, 14
	v_ashrrev_i32_e32 v147, 31, v146
	v_readlane_b32 s9, v250, 15
	v_readlane_b32 s1, v250, 16
	v_lshl_or_b32 v156, s66, 8, v169
	v_lshl_add_u64 v[128:129], v[146:147], 3, s[8:9]
	global_load_dwordx2 v[130:131], v[128:129], off
	global_load_dwordx2 v[218:219], v[128:129], off offset:128
	global_load_dwordx2 v[220:221], v[128:129], off offset:256
	global_load_dwordx2 v[222:223], v[128:129], off offset:384
	global_load_dwordx2 v[224:225], v[128:129], off offset:1024
	global_load_dwordx2 v[226:227], v[128:129], off offset:1152
	global_load_dwordx2 v[228:229], v[128:129], off offset:1280
	global_load_dwordx2 v[230:231], v[128:129], off offset:1408
	s_ashr_i32 s8, s65, 5
	s_ashr_i32 s9, s8, 31
	s_lshl_b64 s[8:9], s[8:9], 14
	s_add_u32 s8, s1, s8
	v_readlane_b32 s1, v250, 17
	v_ashrrev_i32_e32 v157, 31, v156
	s_addc_u32 s9, s1, s9
	v_lshl_add_u64 v[164:165], v[156:157], 2, s[8:9]
	global_load_dwordx4 v[232:235], v[164:165], off offset:16
	global_load_dwordx4 v[236:239], v[164:165], off
	v_readlane_b32 s8, v253, 29
	v_readlane_b32 s9, v253, 30
	s_mov_b32 s1, 0x100000
	s_mov_b32 s66, s0
	s_mov_b32 s65, s4
	s_mov_b64 s[20:21], s[6:7]
	v_readlane_b32 s62, v255, 4
	v_readlane_b32 s63, v255, 5
	s_waitcnt vmcnt(0)
	v_ffbh_u32_e32 v132, v131
	v_min_u32_e32 v132, 32, v132
	v_lshlrev_b64 v[130:131], v132, v[130:131]
	v_min_u32_e32 v130, 1, v130
	v_or_b32_e32 v130, v131, v130
	v_cvt_f32_u32_e32 v130, v130
	v_sub_u32_e32 v131, 32, v132
	v_ldexp_f32 v130, v130, v131
	v_mul_f32_e32 v130, 0x37800000, v130
	v_fmamk_f32 v158, v130, 0x3a800000, v240
	v_mov_b32_e32 v130, v218
	v_mov_b32_e32 v131, v219
	v_cmp_gt_f32_e32 vcc, s53, v158
	v_mul_f32_e32 v162, 0x4b800000, v158
	v_ffbh_u32_e32 v132, v131
	v_min_u32_e32 v132, 32, v132
	v_lshlrev_b64 v[130:131], v132, v[130:131]
	v_min_u32_e32 v130, 1, v130
	v_or_b32_e32 v130, v131, v130
	v_cvt_f32_u32_e32 v130, v130
	v_sub_u32_e32 v131, 32, v132
	v_cndmask_b32_e32 v158, v158, v162, vcc
	v_rsq_f32_e32 v158, v158
	v_ldexp_f32 v130, v130, v131
	v_mul_f32_e32 v130, 0x37800000, v130
	v_fmamk_f32 v171, v130, 0x3a800000, v240
	v_mov_b32_e32 v130, v220
	v_mov_b32_e32 v131, v221
	v_mul_f32_e32 v162, 0x45800000, v158
	v_cndmask_b32_e32 v184, v158, v162, vcc
	v_cmp_gt_f32_e32 vcc, s53, v171
	v_mul_f32_e32 v158, 0x4b800000, v171
	v_ffbh_u32_e32 v132, v131
	v_min_u32_e32 v132, 32, v132
	v_lshlrev_b64 v[130:131], v132, v[130:131]
	v_min_u32_e32 v130, 1, v130
	v_or_b32_e32 v130, v131, v130
	v_cvt_f32_u32_e32 v130, v130
	v_sub_u32_e32 v131, 32, v132
	v_cndmask_b32_e32 v158, v171, v158, vcc
	v_rsq_f32_e32 v158, v158
	v_ldexp_f32 v130, v130, v131
	v_mul_f32_e32 v130, 0x37800000, v130
	v_fmamk_f32 v172, v130, 0x3a800000, v240
	v_mov_b32_e32 v130, v222
	v_mov_b32_e32 v131, v223
	v_mul_f32_e32 v162, 0x45800000, v158
	v_cndmask_b32_e32 v182, v158, v162, vcc
	v_cmp_gt_f32_e32 vcc, s53, v172
	v_mul_f32_e32 v158, 0x4b800000, v172
	v_ffbh_u32_e32 v132, v131
	v_min_u32_e32 v132, 32, v132
	v_lshlrev_b64 v[130:131], v132, v[130:131]
	v_min_u32_e32 v130, 1, v130
	v_or_b32_e32 v130, v131, v130
	v_cvt_f32_u32_e32 v130, v130
	v_sub_u32_e32 v131, 32, v132
	v_cndmask_b32_e32 v158, v172, v158, vcc
	v_rsq_f32_e32 v158, v158
	v_ldexp_f32 v130, v130, v131
	v_mul_f32_e32 v130, 0x37800000, v130
	v_fmamk_f32 v173, v130, 0x3a800000, v240
	v_mov_b32_e32 v130, v224
	v_mov_b32_e32 v131, v225
	v_mul_f32_e32 v162, 0x45800000, v158
	v_cndmask_b32_e32 v180, v158, v162, vcc
	v_cmp_gt_f32_e32 vcc, s53, v173
	v_mul_f32_e32 v158, 0x4b800000, v173
	v_ffbh_u32_e32 v132, v131
	v_min_u32_e32 v132, 32, v132
	v_lshlrev_b64 v[130:131], v132, v[130:131]
	v_min_u32_e32 v130, 1, v130
	v_or_b32_e32 v130, v131, v130
	v_cvt_f32_u32_e32 v130, v130
	v_sub_u32_e32 v131, 32, v132
	v_cndmask_b32_e32 v158, v173, v158, vcc
	v_rsq_f32_e32 v158, v158
	v_ldexp_f32 v130, v130, v131
	v_mul_f32_e32 v130, 0x37800000, v130
	v_fmamk_f32 v174, v130, 0x3a800000, v240
	v_mov_b32_e32 v130, v226
	v_mov_b32_e32 v131, v227
	v_mul_f32_e32 v162, 0x45800000, v158
	v_cndmask_b32_e32 v178, v158, v162, vcc
	v_cmp_gt_f32_e32 vcc, s53, v174
	v_mul_f32_e32 v158, 0x4b800000, v174
	v_ffbh_u32_e32 v132, v131
	v_min_u32_e32 v132, 32, v132
	v_lshlrev_b64 v[130:131], v132, v[130:131]
	v_min_u32_e32 v130, 1, v130
	v_or_b32_e32 v130, v131, v130
	v_cvt_f32_u32_e32 v130, v130
	v_sub_u32_e32 v131, 32, v132
	v_cndmask_b32_e32 v158, v174, v158, vcc
	v_rsq_f32_e32 v158, v158
	v_ldexp_f32 v130, v130, v131
	v_mul_f32_e32 v130, 0x37800000, v130
	v_fmamk_f32 v175, v130, 0x3a800000, v240
	v_mov_b32_e32 v130, v228
	v_mov_b32_e32 v131, v229
	v_mul_f32_e32 v162, 0x45800000, v158
	v_mov_b32_e32 v128, v230
	v_mov_b32_e32 v129, v231
	v_cndmask_b32_e32 v176, v158, v162, vcc
	v_cmp_gt_f32_e32 vcc, s53, v175
	v_mul_f32_e32 v158, 0x4b800000, v175
	v_ffbh_u32_e32 v132, v131
	v_min_u32_e32 v132, 32, v132
	v_lshlrev_b64 v[130:131], v132, v[130:131]
	v_min_u32_e32 v130, 1, v130
	v_or_b32_e32 v130, v131, v130
	v_cvt_f32_u32_e32 v130, v130
	v_sub_u32_e32 v131, 32, v132
	v_cndmask_b32_e32 v158, v175, v158, vcc
	v_rsq_f32_e32 v158, v158
	v_ldexp_f32 v130, v130, v131
	v_mul_f32_e32 v130, 0x37800000, v130
	v_fmamk_f32 v177, v130, 0x3a800000, v240
	v_ffbh_u32_e32 v130, v129
	v_min_u32_e32 v130, 32, v130
	v_lshlrev_b64 v[128:129], v130, v[128:129]
	v_min_u32_e32 v128, 1, v128
	v_or_b32_e32 v128, v129, v128
	v_cvt_f32_u32_e32 v128, v128
	v_sub_u32_e32 v129, 32, v130
	v_mul_f32_e32 v162, 0x45800000, v158
	v_cndmask_b32_e32 v174, v158, v162, vcc
	v_ldexp_f32 v128, v128, v129
	v_mul_f32_e32 v128, 0x37800000, v128
	v_fmamk_f32 v179, v128, 0x3a800000, v240
	v_mov_b32_e32 v128, v232
	v_mov_b32_e32 v129, v233
	v_mov_b32_e32 v130, v234
	v_mov_b32_e32 v131, v235
	v_mov_b32_e32 v132, v236
	v_mov_b32_e32 v133, v237
	v_mov_b32_e32 v134, v238
	v_mov_b32_e32 v135, v239
	v_cmp_gt_f32_e32 vcc, s53, v177
	v_mul_f32_e32 v158, 0x4b800000, v177
	s_waitcnt vmcnt(0)
	v_pk_add_f32 v[148:149], v[130:131], 0 op_sel_hi:[1,0]
	v_pk_add_f32 v[152:153], v[134:135], 0 op_sel_hi:[1,0]
	v_pk_add_f32 v[154:155], v[132:133], 0 op_sel_hi:[1,0]
	v_pk_add_f32 v[150:151], v[128:129], 0 op_sel_hi:[1,0]
	global_load_dwordx4 v[128:131], v[164:165], off offset:528
	global_load_dwordx4 v[132:135], v[164:165], off offset:512
	v_cndmask_b32_e32 v158, v177, v158, vcc
	v_rsq_f32_e32 v158, v158
	v_pk_fma_f32 v[122:123], v[122:123], v[184:185], v[148:149] op_sel_hi:[1,0,1]
	v_pk_fma_f32 v[126:127], v[126:127], v[184:185], v[152:153] op_sel_hi:[1,0,1]
	v_pk_fma_f32 v[124:125], v[124:125], v[184:185], v[154:155] op_sel_hi:[1,0,1]
	v_mul_f32_e32 v162, 0x45800000, v158
	v_cndmask_b32_e32 v172, v158, v162, vcc
	v_cmp_gt_f32_e32 vcc, s53, v179
	v_mul_f32_e32 v158, 0x4b800000, v179
	v_pk_fma_f32 v[120:121], v[120:121], v[184:185], v[150:151] op_sel_hi:[1,0,1]
	v_cndmask_b32_e32 v158, v179, v158, vcc
	v_rsq_f32_e32 v158, v158
	v_max_f32_e32 v122, 0, v122
	v_max_f32_e32 v124, 0, v124
	v_max_f32_e32 v120, 0, v120
	v_mul_f32_e32 v162, 0x45800000, v158
	v_cndmask_b32_e32 v158, v158, v162, vcc
	v_max_f32_e32 v121, 0, v121
	v_mul_f32_e32 v162, v122, v122
	v_max_f32_e32 v122, 0, v127
	v_mul_f32_e32 v124, v124, v124
	v_mul_f32_e32 v120, v120, v120
	v_max_f32_e32 v125, 0, v125
	v_mul_f32_e32 v121, v121, v121
	v_max_f32_e32 v126, 0, v126
	v_mul_f32_e32 v127, v122, v122
	v_max_f32_e32 v122, 0, v123
	v_mul_f32_e32 v125, v125, v125
	v_mul_f32_e32 v126, v126, v126
	v_mul_f32_e32 v164, v122, v122
	v_cvt_pk_bf16_f32 v122, v124, v125
	v_cvt_pk_bf16_f32 v123, v126, v127
	v_cvt_pk_bf16_f32 v124, v120, v121
	v_lshlrev_b64 v[120:121], 13, v[146:147]
	v_lshl_add_u64 v[120:121], s[8:9], 0, v[120:121]
	v_lshlrev_b64 v[126:127], 1, v[156:157]
	v_pk_fma_f32 v[114:115], v[114:115], v[182:183], v[148:149] op_sel_hi:[1,0,1]
	v_lshl_add_u64 v[120:121], v[120:121], 0, v[126:127]
	v_pk_fma_f32 v[118:119], v[118:119], v[182:183], v[152:153] op_sel_hi:[1,0,1]
	v_pk_fma_f32 v[116:117], v[116:117], v[182:183], v[154:155] op_sel_hi:[1,0,1]
	v_pk_fma_f32 v[112:113], v[112:113], v[182:183], v[150:151] op_sel_hi:[1,0,1]
	v_max_f32_e32 v114, 0, v114
	v_cvt_pk_bf16_f32 v125, v162, v164
	global_store_dwordx4 v[120:121], v[122:125], off sc1
	v_max_f32_e32 v116, 0, v116
	v_max_f32_e32 v112, 0, v112
	v_mul_f32_e32 v122, v114, v114
	v_max_f32_e32 v114, 0, v119
	v_mul_f32_e32 v116, v116, v116
	v_mul_f32_e32 v112, v112, v112
	v_max_f32_e32 v117, 0, v117
	v_max_f32_e32 v113, 0, v113
	v_max_f32_e32 v118, 0, v118
	v_mul_f32_e32 v119, v114, v114
	v_max_f32_e32 v114, 0, v115
	v_mul_f32_e32 v117, v117, v117
	v_mul_f32_e32 v113, v113, v113
	v_mul_f32_e32 v118, v118, v118
	v_mul_f32_e32 v123, v114, v114
	v_cvt_pk_bf16_f32 v114, v116, v117
	v_cvt_pk_bf16_f32 v115, v118, v119
	v_cvt_pk_bf16_f32 v116, v112, v113
	v_or_b32_e32 v112, 16, v146
	v_ashrrev_i32_e32 v113, 31, v112
	v_lshlrev_b64 v[112:113], 13, v[112:113]
	v_lshl_add_u64 v[112:113], s[8:9], 0, v[112:113]
	v_pk_fma_f32 v[106:107], v[106:107], v[180:181], v[148:149] op_sel_hi:[1,0,1]
	v_lshl_add_u64 v[112:113], v[112:113], 0, v[126:127]
	v_pk_fma_f32 v[110:111], v[110:111], v[180:181], v[152:153] op_sel_hi:[1,0,1]
	v_pk_fma_f32 v[108:109], v[108:109], v[180:181], v[154:155] op_sel_hi:[1,0,1]
	v_pk_fma_f32 v[104:105], v[104:105], v[180:181], v[150:151] op_sel_hi:[1,0,1]
	v_max_f32_e32 v106, 0, v106
	v_cvt_pk_bf16_f32 v117, v122, v123
	global_store_dwordx4 v[112:113], v[114:117], off sc1
	v_max_f32_e32 v108, 0, v108
	v_max_f32_e32 v104, 0, v104
	v_mul_f32_e32 v114, v106, v106
	v_max_f32_e32 v106, 0, v111
	v_mul_f32_e32 v108, v108, v108
	v_mul_f32_e32 v104, v104, v104
	v_max_f32_e32 v109, 0, v109
	v_max_f32_e32 v105, 0, v105
	v_max_f32_e32 v110, 0, v110
	v_mul_f32_e32 v111, v106, v106
	v_max_f32_e32 v106, 0, v107
	v_mul_f32_e32 v109, v109, v109
	v_mul_f32_e32 v105, v105, v105
	v_mul_f32_e32 v110, v110, v110
	v_mul_f32_e32 v115, v106, v106
	v_cvt_pk_bf16_f32 v106, v108, v109
	v_cvt_pk_bf16_f32 v107, v110, v111
	v_cvt_pk_bf16_f32 v108, v104, v105
	v_or_b32_e32 v104, 32, v146
	v_ashrrev_i32_e32 v105, 31, v104
	v_lshlrev_b64 v[104:105], 13, v[104:105]
	v_lshl_add_u64 v[104:105], s[8:9], 0, v[104:105]
	v_pk_fma_f32 v[98:99], v[98:99], v[178:179], v[148:149] op_sel_hi:[1,0,1]
	v_lshl_add_u64 v[104:105], v[104:105], 0, v[126:127]
	v_pk_fma_f32 v[102:103], v[102:103], v[178:179], v[152:153] op_sel_hi:[1,0,1]
	v_pk_fma_f32 v[100:101], v[100:101], v[178:179], v[154:155] op_sel_hi:[1,0,1]
	v_pk_fma_f32 v[96:97], v[96:97], v[178:179], v[150:151] op_sel_hi:[1,0,1]
	v_max_f32_e32 v98, 0, v98
	v_cvt_pk_bf16_f32 v109, v114, v115
	global_store_dwordx4 v[104:105], v[106:109], off sc1
	v_max_f32_e32 v100, 0, v100
	v_max_f32_e32 v96, 0, v96
	v_mul_f32_e32 v106, v98, v98
	v_max_f32_e32 v98, 0, v103
	v_mul_f32_e32 v100, v100, v100
	v_mul_f32_e32 v96, v96, v96
	v_max_f32_e32 v101, 0, v101
	v_max_f32_e32 v97, 0, v97
	v_max_f32_e32 v102, 0, v102
	v_mul_f32_e32 v103, v98, v98
	v_max_f32_e32 v98, 0, v99
	v_mul_f32_e32 v101, v101, v101
	v_mul_f32_e32 v97, v97, v97
	v_mul_f32_e32 v102, v102, v102
	v_mul_f32_e32 v107, v98, v98
	v_cvt_pk_bf16_f32 v98, v100, v101
	v_cvt_pk_bf16_f32 v99, v102, v103
	v_cvt_pk_bf16_f32 v100, v96, v97
	v_or_b32_e32 v96, 48, v146
	v_ashrrev_i32_e32 v97, 31, v96
	v_lshlrev_b64 v[96:97], 13, v[96:97]
	v_lshl_add_u64 v[96:97], s[8:9], 0, v[96:97]
	v_pk_fma_f32 v[90:91], v[90:91], v[176:177], v[148:149] op_sel_hi:[1,0,1]
	v_lshl_add_u64 v[96:97], v[96:97], 0, v[126:127]
	v_pk_fma_f32 v[94:95], v[94:95], v[176:177], v[152:153] op_sel_hi:[1,0,1]
	v_max_f32_e32 v90, 0, v90
	v_cvt_pk_bf16_f32 v101, v106, v107
	global_store_dwordx4 v[96:97], v[98:101], off sc1
	v_pk_fma_f32 v[92:93], v[92:93], v[176:177], v[154:155] op_sel_hi:[1,0,1]
	v_max_f32_e32 v94, 0, v94
	v_mul_f32_e32 v98, v90, v90
	v_max_f32_e32 v90, 0, v95
	v_max_f32_e32 v92, 0, v92
	v_max_f32_e32 v93, 0, v93
	v_mul_f32_e32 v94, v94, v94
	v_mul_f32_e32 v95, v90, v90
	v_max_f32_e32 v90, 0, v91
	v_pk_fma_f32 v[88:89], v[88:89], v[176:177], v[150:151] op_sel_hi:[1,0,1]
	v_mul_f32_e32 v92, v92, v92
	v_mul_f32_e32 v93, v93, v93
	v_mul_f32_e32 v99, v90, v90
	v_cvt_pk_bf16_f32 v90, v92, v93
	v_cvt_pk_bf16_f32 v91, v94, v95
	v_add_co_u32_e32 v94, vcc, s1, v120
	v_pk_fma_f32 v[82:83], v[82:83], v[174:175], v[148:149] op_sel_hi:[1,0,1]
	v_max_f32_e32 v88, 0, v88
	v_max_f32_e32 v89, 0, v89
	v_addc_co_u32_e32 v95, vcc, 0, v121, vcc
	v_pk_fma_f32 v[86:87], v[86:87], v[174:175], v[152:153] op_sel_hi:[1,0,1]
	v_max_f32_e32 v82, 0, v82
	v_mul_f32_e32 v88, v88, v88
	v_mul_f32_e32 v89, v89, v89
	v_cvt_pk_bf16_f32 v92, v88, v89
	v_cvt_pk_bf16_f32 v93, v98, v99
	global_store_dwordx4 v[94:95], v[90:93], off sc1
	v_pk_fma_f32 v[84:85], v[84:85], v[174:175], v[154:155] op_sel_hi:[1,0,1]
	v_max_f32_e32 v86, 0, v86
	v_mul_f32_e32 v90, v82, v82
	v_max_f32_e32 v82, 0, v87
	v_max_f32_e32 v84, 0, v84
	v_max_f32_e32 v85, 0, v85
	v_mul_f32_e32 v86, v86, v86
	v_mul_f32_e32 v87, v82, v82
	v_max_f32_e32 v82, 0, v83
	s_mov_b32 s1, 0x120000
	v_pk_fma_f32 v[80:81], v[80:81], v[174:175], v[150:151] op_sel_hi:[1,0,1]
	v_mul_f32_e32 v84, v84, v84
	v_mul_f32_e32 v85, v85, v85
	v_mul_f32_e32 v91, v82, v82
	v_cvt_pk_bf16_f32 v82, v84, v85
	v_cvt_pk_bf16_f32 v83, v86, v87
	v_add_co_u32_e32 v86, vcc, s1, v120
	v_pk_fma_f32 v[74:75], v[74:75], v[172:173], v[148:149] op_sel_hi:[1,0,1]
	v_max_f32_e32 v80, 0, v80
	v_max_f32_e32 v81, 0, v81
	v_addc_co_u32_e32 v87, vcc, 0, v121, vcc
	v_pk_fma_f32 v[78:79], v[78:79], v[172:173], v[152:153] op_sel_hi:[1,0,1]
	v_max_f32_e32 v74, 0, v74
	v_mul_f32_e32 v80, v80, v80
	v_mul_f32_e32 v81, v81, v81
	v_cvt_pk_bf16_f32 v84, v80, v81
	v_cvt_pk_bf16_f32 v85, v90, v91
	global_store_dwordx4 v[86:87], v[82:85], off sc1
	v_pk_fma_f32 v[76:77], v[76:77], v[172:173], v[154:155] op_sel_hi:[1,0,1]
	v_max_f32_e32 v78, 0, v78
	v_mul_f32_e32 v82, v74, v74
	v_max_f32_e32 v74, 0, v79
	v_max_f32_e32 v76, 0, v76
	v_max_f32_e32 v77, 0, v77
	v_mul_f32_e32 v78, v78, v78
	v_mul_f32_e32 v79, v74, v74
	v_max_f32_e32 v74, 0, v75
	s_mov_b32 s1, 0x140000
	v_pk_fma_f32 v[72:73], v[72:73], v[172:173], v[150:151] op_sel_hi:[1,0,1]
	v_mul_f32_e32 v76, v76, v76
	v_mul_f32_e32 v77, v77, v77
	v_mul_f32_e32 v83, v74, v74
	v_cvt_pk_bf16_f32 v74, v76, v77
	v_cvt_pk_bf16_f32 v75, v78, v79
	v_add_co_u32_e32 v78, vcc, s1, v120
	v_pk_fma_f32 v[58:59], v[58:59], v[158:159], v[148:149] op_sel_hi:[1,0,1]
	v_max_f32_e32 v72, 0, v72
	v_max_f32_e32 v73, 0, v73
	v_addc_co_u32_e32 v79, vcc, 0, v121, vcc
	v_pk_fma_f32 v[62:63], v[62:63], v[158:159], v[152:153] op_sel_hi:[1,0,1]
	v_max_f32_e32 v58, 0, v58
	v_mul_f32_e32 v72, v72, v72
	v_mul_f32_e32 v73, v73, v73
	v_cvt_pk_bf16_f32 v76, v72, v73
	v_cvt_pk_bf16_f32 v77, v82, v83
	global_store_dwordx4 v[78:79], v[74:77], off sc1
	v_pk_fma_f32 v[60:61], v[60:61], v[158:159], v[154:155] op_sel_hi:[1,0,1]
	v_max_f32_e32 v62, 0, v62
	v_mul_f32_e32 v74, v58, v58
	v_max_f32_e32 v58, 0, v63
	v_max_f32_e32 v60, 0, v60
	v_max_f32_e32 v61, 0, v61
	v_mul_f32_e32 v62, v62, v62
	v_mul_f32_e32 v63, v58, v58
	v_max_f32_e32 v58, 0, v59
	s_mov_b32 s1, 0x160000
	v_pk_fma_f32 v[56:57], v[56:57], v[158:159], v[150:151] op_sel_hi:[1,0,1]
	v_mul_f32_e32 v60, v60, v60
	v_mul_f32_e32 v61, v61, v61
	v_mul_f32_e32 v75, v58, v58
	v_cvt_pk_bf16_f32 v58, v60, v61
	v_cvt_pk_bf16_f32 v59, v62, v63
	v_add_co_u32_e32 v62, vcc, s1, v120
	s_waitcnt vmcnt(7)
	v_pk_add_f32 v[134:135], v[134:135], 0 op_sel_hi:[1,0]
	v_max_f32_e32 v56, 0, v56
	v_max_f32_e32 v57, 0, v57
	v_addc_co_u32_e32 v63, vcc, 0, v121, vcc
	v_pk_add_f32 v[130:131], v[130:131], 0 op_sel_hi:[1,0]
	v_mul_f32_e32 v56, v56, v56
	v_mul_f32_e32 v57, v57, v57
	v_cvt_pk_bf16_f32 v60, v56, v57
	v_cvt_pk_bf16_f32 v61, v74, v75
	global_store_dwordx4 v[62:63], v[58:61], off sc1
	v_pk_fma_f32 v[62:63], v[66:67], v[184:185], v[130:131] op_sel_hi:[1,0,1]
	v_pk_add_f32 v[132:133], v[132:133], 0 op_sel_hi:[1,0]
	v_pk_fma_f32 v[58:59], v[70:71], v[184:185], v[134:135] op_sel_hi:[1,0,1]
	v_pk_add_f32 v[128:129], v[128:129], 0 op_sel_hi:[1,0]
	v_max_f32_e32 v58, 0, v58
	v_mul_f32_e32 v66, v58, v58
	v_max_f32_e32 v58, 0, v62
	v_pk_fma_f32 v[60:61], v[68:69], v[184:185], v[132:133] op_sel_hi:[1,0,1]
	v_mul_f32_e32 v62, v58, v58
	v_max_f32_e32 v58, 0, v59
	v_pk_fma_f32 v[64:65], v[64:65], v[184:185], v[128:129] op_sel_hi:[1,0,1]
	v_max_f32_e32 v60, 0, v60
	v_max_f32_e32 v61, 0, v61
	v_mul_f32_e32 v59, v58, v58
	v_max_f32_e32 v58, 0, v63
	v_pk_fma_f32 v[48:49], v[48:49], v[182:183], v[128:129] op_sel_hi:[1,0,1]
	v_mul_f32_e32 v60, v60, v60
	v_max_f32_e32 v64, 0, v64
	v_mul_f32_e32 v61, v61, v61
	v_max_f32_e32 v65, 0, v65
	v_mul_f32_e32 v63, v58, v58
	v_cvt_pk_bf16_f32 v58, v60, v61
	v_pk_fma_f32 v[52:53], v[52:53], v[182:183], v[132:133] op_sel_hi:[1,0,1]
	v_pk_fma_f32 v[50:51], v[50:51], v[182:183], v[130:131] op_sel_hi:[1,0,1]
	v_max_f32_e32 v48, 0, v48
	v_mul_f32_e32 v64, v64, v64
	v_mul_f32_e32 v65, v65, v65
	v_cvt_pk_bf16_f32 v59, v66, v59
	v_cvt_pk_bf16_f32 v60, v64, v65
	v_cvt_pk_bf16_f32 v61, v62, v63
	global_store_dwordx4 v[120:121], v[58:61], off offset:256 sc1
	v_pk_fma_f32 v[54:55], v[54:55], v[182:183], v[134:135] op_sel_hi:[1,0,1]
	v_max_f32_e32 v49, 0, v49
	v_mul_f32_e32 v58, v48, v48
	v_max_f32_e32 v48, 0, v53
	v_max_f32_e32 v50, 0, v50
	v_max_f32_e32 v52, 0, v52
	v_mul_f32_e32 v48, v48, v48
	v_mul_f32_e32 v53, v49, v49
	v_max_f32_e32 v49, 0, v54
	v_mul_f32_e32 v54, v50, v50
	v_max_f32_e32 v50, 0, v55
	v_max_f32_e32 v51, 0, v51
	v_pk_fma_f32 v[40:41], v[40:41], v[180:181], v[128:129] op_sel_hi:[1,0,1]
	v_mul_f32_e32 v52, v52, v52
	v_mul_f32_e32 v49, v49, v49
	v_mul_f32_e32 v50, v50, v50
	v_mul_f32_e32 v51, v51, v51
	v_cvt_pk_bf16_f32 v48, v52, v48
	v_pk_fma_f32 v[44:45], v[44:45], v[180:181], v[132:133] op_sel_hi:[1,0,1]
	v_pk_fma_f32 v[42:43], v[42:43], v[180:181], v[130:131] op_sel_hi:[1,0,1]
	v_max_f32_e32 v40, 0, v40
	v_cvt_pk_bf16_f32 v49, v49, v50
	v_cvt_pk_bf16_f32 v50, v58, v53
	v_cvt_pk_bf16_f32 v51, v54, v51
	global_store_dwordx4 v[112:113], v[48:51], off offset:256 sc1
	v_pk_fma_f32 v[46:47], v[46:47], v[180:181], v[134:135] op_sel_hi:[1,0,1]
	v_max_f32_e32 v41, 0, v41
	v_mul_f32_e32 v48, v40, v40
	v_max_f32_e32 v40, 0, v45
	v_max_f32_e32 v42, 0, v42
	v_max_f32_e32 v44, 0, v44
	v_mul_f32_e32 v40, v40, v40
	v_mul_f32_e32 v45, v41, v41
	v_max_f32_e32 v41, 0, v46
	v_mul_f32_e32 v46, v42, v42
	v_max_f32_e32 v42, 0, v47
	v_max_f32_e32 v43, 0, v43
	v_pk_fma_f32 v[32:33], v[32:33], v[178:179], v[128:129] op_sel_hi:[1,0,1]
	v_mul_f32_e32 v44, v44, v44
	v_mul_f32_e32 v41, v41, v41
	v_mul_f32_e32 v42, v42, v42
	v_mul_f32_e32 v43, v43, v43
	v_cvt_pk_bf16_f32 v40, v44, v40
	v_pk_fma_f32 v[36:37], v[36:37], v[178:179], v[132:133] op_sel_hi:[1,0,1]
	v_pk_fma_f32 v[34:35], v[34:35], v[178:179], v[130:131] op_sel_hi:[1,0,1]
	v_max_f32_e32 v32, 0, v32
	v_cvt_pk_bf16_f32 v41, v41, v42
	v_cvt_pk_bf16_f32 v42, v48, v45
	v_cvt_pk_bf16_f32 v43, v46, v43
	global_store_dwordx4 v[104:105], v[40:43], off offset:256 sc1
	v_pk_fma_f32 v[38:39], v[38:39], v[178:179], v[134:135] op_sel_hi:[1,0,1]
	v_max_f32_e32 v33, 0, v33
	v_mul_f32_e32 v40, v32, v32
	v_max_f32_e32 v32, 0, v37
	v_max_f32_e32 v34, 0, v34
	v_max_f32_e32 v36, 0, v36
	v_mul_f32_e32 v32, v32, v32
	v_mul_f32_e32 v37, v33, v33
	v_max_f32_e32 v33, 0, v38
	v_mul_f32_e32 v38, v34, v34
	v_max_f32_e32 v34, 0, v39
	v_max_f32_e32 v35, 0, v35
	v_pk_fma_f32 v[24:25], v[24:25], v[176:177], v[128:129] op_sel_hi:[1,0,1]
	v_mul_f32_e32 v36, v36, v36
	v_mul_f32_e32 v33, v33, v33
	v_mul_f32_e32 v34, v34, v34
	v_mul_f32_e32 v35, v35, v35
	v_cvt_pk_bf16_f32 v32, v36, v32
	v_pk_fma_f32 v[28:29], v[28:29], v[176:177], v[132:133] op_sel_hi:[1,0,1]
	v_pk_fma_f32 v[26:27], v[26:27], v[176:177], v[130:131] op_sel_hi:[1,0,1]
	v_max_f32_e32 v24, 0, v24
	v_cvt_pk_bf16_f32 v33, v33, v34
	v_cvt_pk_bf16_f32 v34, v40, v37
	v_cvt_pk_bf16_f32 v35, v38, v35
	global_store_dwordx4 v[96:97], v[32:35], off offset:256 sc1
	v_pk_fma_f32 v[30:31], v[30:31], v[176:177], v[134:135] op_sel_hi:[1,0,1]
	v_max_f32_e32 v25, 0, v25
	v_mul_f32_e32 v32, v24, v24
	v_max_f32_e32 v24, 0, v29
	v_max_f32_e32 v26, 0, v26
	s_mov_b64 s[8:9], 0x100000
	v_max_f32_e32 v28, 0, v28
	v_mul_f32_e32 v24, v24, v24
	v_mul_f32_e32 v29, v25, v25
	v_max_f32_e32 v25, 0, v30
	v_mul_f32_e32 v30, v26, v26
	v_max_f32_e32 v26, 0, v31
	v_max_f32_e32 v27, 0, v27
	v_pk_fma_f32 v[16:17], v[16:17], v[174:175], v[128:129] op_sel_hi:[1,0,1]
	v_lshl_add_u64 v[88:89], v[120:121], 0, s[8:9]
	v_mul_f32_e32 v28, v28, v28
	v_mul_f32_e32 v25, v25, v25
	v_mul_f32_e32 v26, v26, v26
	v_mul_f32_e32 v27, v27, v27
	v_cvt_pk_bf16_f32 v24, v28, v24
	v_pk_fma_f32 v[20:21], v[20:21], v[174:175], v[132:133] op_sel_hi:[1,0,1]
	v_pk_fma_f32 v[18:19], v[18:19], v[174:175], v[130:131] op_sel_hi:[1,0,1]
	v_max_f32_e32 v16, 0, v16
	v_cvt_pk_bf16_f32 v25, v25, v26
	v_cvt_pk_bf16_f32 v26, v32, v29
	v_cvt_pk_bf16_f32 v27, v30, v27
	global_store_dwordx4 v[88:89], v[24:27], off offset:256 sc1
	v_pk_fma_f32 v[22:23], v[22:23], v[174:175], v[134:135] op_sel_hi:[1,0,1]
	v_max_f32_e32 v17, 0, v17
	v_mul_f32_e32 v24, v16, v16
	v_max_f32_e32 v16, 0, v21
	v_max_f32_e32 v18, 0, v18
	s_mov_b64 s[8:9], 0x120000
	v_max_f32_e32 v20, 0, v20
	v_mul_f32_e32 v16, v16, v16
	v_mul_f32_e32 v21, v17, v17
	v_max_f32_e32 v17, 0, v22
	v_mul_f32_e32 v22, v18, v18
	v_max_f32_e32 v18, 0, v23
	v_max_f32_e32 v19, 0, v19
	v_pk_fma_f32 v[8:9], v[8:9], v[172:173], v[128:129] op_sel_hi:[1,0,1]
	v_lshl_add_u64 v[80:81], v[120:121], 0, s[8:9]
	v_mul_f32_e32 v20, v20, v20
	v_mul_f32_e32 v17, v17, v17
	v_mul_f32_e32 v18, v18, v18
	v_mul_f32_e32 v19, v19, v19
	v_cvt_pk_bf16_f32 v16, v20, v16
	v_pk_fma_f32 v[12:13], v[12:13], v[172:173], v[132:133] op_sel_hi:[1,0,1]
	v_pk_fma_f32 v[10:11], v[10:11], v[172:173], v[130:131] op_sel_hi:[1,0,1]
	v_max_f32_e32 v8, 0, v8
	v_cvt_pk_bf16_f32 v17, v17, v18
	v_cvt_pk_bf16_f32 v18, v24, v21
	v_cvt_pk_bf16_f32 v19, v22, v19
	global_store_dwordx4 v[80:81], v[16:19], off offset:256 sc1
	v_pk_fma_f32 v[14:15], v[14:15], v[172:173], v[134:135] op_sel_hi:[1,0,1]
	v_max_f32_e32 v9, 0, v9
	v_mul_f32_e32 v16, v8, v8
	v_max_f32_e32 v8, 0, v13
	v_max_f32_e32 v10, 0, v10
	s_mov_b64 s[8:9], 0x140000
	v_max_f32_e32 v12, 0, v12
	v_mul_f32_e32 v8, v8, v8
	v_mul_f32_e32 v13, v9, v9
	v_max_f32_e32 v9, 0, v14
	v_mul_f32_e32 v14, v10, v10
	v_max_f32_e32 v10, 0, v15
	v_max_f32_e32 v11, 0, v11
	v_pk_fma_f32 v[2:3], v[2:3], v[158:159], v[130:131] op_sel_hi:[1,0,1]
	v_pk_fma_f32 v[0:1], v[0:1], v[158:159], v[128:129] op_sel_hi:[1,0,1]
	v_lshl_add_u64 v[72:73], v[120:121], 0, s[8:9]
	v_mul_f32_e32 v12, v12, v12
	v_mul_f32_e32 v9, v9, v9
	v_mul_f32_e32 v10, v10, v10
	v_mul_f32_e32 v11, v11, v11
	v_cvt_pk_bf16_f32 v8, v12, v8
	v_pk_fma_f32 v[6:7], v[6:7], v[158:159], v[134:135] op_sel_hi:[1,0,1]
	v_pk_fma_f32 v[4:5], v[4:5], v[158:159], v[132:133] op_sel_hi:[1,0,1]
	v_max_f32_e32 v0, 0, v0
	v_max_f32_e32 v1, 0, v1
	v_max_f32_e32 v2, 0, v2
	s_mov_b64 s[8:9], 0x160000
	v_cvt_pk_bf16_f32 v9, v9, v10
	v_cvt_pk_bf16_f32 v10, v16, v13
	v_cvt_pk_bf16_f32 v11, v14, v11
	global_store_dwordx4 v[72:73], v[8:11], off offset:256 sc1
	v_max_f32_e32 v3, 0, v3
	v_lshl_add_u64 v[56:57], v[120:121], 0, s[8:9]
	v_mul_f32_e32 v8, v0, v0
	v_max_f32_e32 v0, 0, v5
	v_mul_f32_e32 v5, v1, v1
	v_max_f32_e32 v1, 0, v6
	v_mul_f32_e32 v6, v2, v2
	v_max_f32_e32 v2, 0, v7
	v_max_f32_e32 v4, 0, v4
	v_mul_f32_e32 v0, v0, v0
	v_mul_f32_e32 v1, v1, v1
	v_mul_f32_e32 v2, v2, v2
	v_mul_f32_e32 v3, v3, v3
	s_and_b64 vcc, exec, s[2:3]
	s_mov_b64 s[8:9], s[58:59]
	v_mul_f32_e32 v4, v4, v4
	v_cvt_pk_bf16_f32 v0, v4, v0
	v_cvt_pk_bf16_f32 v1, v1, v2
	v_cvt_pk_bf16_f32 v2, v8, v5
	v_cvt_pk_bf16_f32 v3, v6, v3
	global_store_dwordx4 v[56:57], v[0:3], off offset:256 sc1
	s_cbranch_vccz .LBB0_123
	s_waitcnt vmcnt(0)
	s_mov_b32 s90, s62
	s_cmpk_gt_u32 s36, 0xff
	s_cbranch_scc1 .LBB0_134
	s_barrier

.LBB0_251:
	s_add_u32 s13, s64, s8
	s_addc_u32 s16, s65, 0
	s_add_u32 s9, s13, 0x100
	s_addc_u32 s17, s16, 0
	s_and_b64 s[14:15], s[62:63], exec
	s_cselect_b32 s21, s5, s17
	s_cselect_b32 s20, s50, s9
	s_add_u32 s8, s60, s8
	s_addc_u32 s9, s61, 0
	s_add_u32 s14, s8, 0x100
	s_addc_u32 s15, s9, 0
	s_add_i32 s19, 0, 0x10000
	s_and_b64 s[8:9], s[62:63], exec
	s_cselect_b32 s9, s1, s15
	s_cselect_b32 s8, s12, s14
	s_add_u32 s36, s13, 0x10080
	s_addc_u32 s37, s16, 0
	s_add_i32 s25, s19, s39
	s_add_i32 m0, s40, 0xc000
	s_add_i32 s26, s40, 0xe000
	s_add_i32 s24, 0, 0x14000
	s_add_i32 s23, s25, 0x2000
	s_add_u32 vcc_lo, s8, 0x10000
	v_add_u32_e32 v150, s19, v135
	s_addc_u32 vcc_hi, s9, 0
	s_add_i32 s18, s24, s39
	ds_read_b128 v[138:141], v150
	ds_read_b128 v[142:145], v150 offset:1024
	ds_read_b128 v[146:149], v150 offset:2048
	ds_read_b128 v[150:153], v150 offset:3072
	s_add_i32 s17, s18, 0x2000
	s_add_i32 s16, 0, 0x18000
	s_add_u32 s92, s20, 0x10000
	s_addc_u32 s93, s21, 0
	s_add_i32 s15, s16, s39
	s_add_i32 s14, 0, 0x1c000
	s_add_i32 s13, s15, 0x2000
	s_add_u32 s62, s8, 0x10080
	s_addc_u32 s63, s9, 0
	s_add_i32 s22, s14, s39
	s_add_i32 s19, s22, 0x2000
	v_lshl_add_u64 v[158:159], s[36:37], 0, v[132:133]
	ds_read_b128 v[154:157], v137
	ds_read_b128 v[168:171], v137 offset:1024
	ds_read_b128 v[172:175], v137 offset:2048
	ds_read_b128 v[176:179], v137 offset:3072
	ds_read_b128 v[180:183], v137 offset:4096
	ds_read_b128 v[184:187], v137 offset:5120
	ds_read_b128 v[188:191], v137 offset:6144
	ds_read_b128 v[192:195], v137 offset:7168
	global_load_lds_dwordx4 v[158:159], off
	v_lshl_add_u64 v[158:159], s[36:37], 0, v[130:131]
	s_mov_b32 m0, s26
	s_nop 0
	global_load_lds_dwordx4 v[158:159], off
	s_waitcnt lgkmcnt(8)
	s_barrier
	s_waitcnt lgkmcnt(0)
	s_setprio 1
	s_waitcnt lgkmcnt(0)
	v_mfma_f32_16x16x32_bf16 v[124:127], v[138:141], v[154:157], v[124:127]
	v_mfma_f32_16x16x32_bf16 v[120:123], v[146:149], v[154:157], v[120:123]
	v_mfma_f32_16x16x32_bf16 v[116:119], v[138:141], v[172:175], v[116:119]
	v_mfma_f32_16x16x32_bf16 v[112:115], v[146:149], v[172:175], v[112:115]
	v_mfma_f32_16x16x32_bf16 v[108:111], v[138:141], v[180:183], v[108:111]
	v_mfma_f32_16x16x32_bf16 v[104:107], v[146:149], v[180:183], v[104:107]
	v_mfma_f32_16x16x32_bf16 v[100:103], v[138:141], v[188:191], v[100:103]
	v_mfma_f32_16x16x32_bf16 v[96:99], v[146:149], v[188:191], v[96:99]
	v_mfma_f32_16x16x32_bf16 v[124:127], v[142:145], v[168:171], v[124:127]
	v_mfma_f32_16x16x32_bf16 v[120:123], v[150:153], v[168:171], v[120:123]
	v_mfma_f32_16x16x32_bf16 v[116:119], v[142:145], v[176:179], v[116:119]
	v_mfma_f32_16x16x32_bf16 v[112:115], v[150:153], v[176:179], v[112:115]
	v_mfma_f32_16x16x32_bf16 v[108:111], v[142:145], v[184:187], v[108:111]
	v_mfma_f32_16x16x32_bf16 v[104:107], v[150:153], v[184:187], v[104:107]
	v_mfma_f32_16x16x32_bf16 v[100:103], v[142:145], v[192:195], v[100:103]
	v_mfma_f32_16x16x32_bf16 v[96:99], v[150:153], v[192:195], v[96:99]
	s_setprio 0
	s_barrier
	v_add_u32_e32 v158, s24, v135
	s_mov_b32 m0, s25
	ds_read_b128 v[196:199], v158
	ds_read_b128 v[200:203], v158 offset:1024
	ds_read_b128 v[204:207], v158 offset:2048
	ds_read_b128 v[208:211], v158 offset:3072
	v_lshl_add_u64 v[158:159], s[8:9], 0, v[160:161]
	global_load_lds_dwordx4 v[158:159], off
	v_lshl_add_u64 v[212:213], s[8:9], 0, v[128:129]
	s_mov_b32 m0, s23
	s_nop 0
	global_load_lds_dwordx4 v[212:213], off
	s_barrier
	s_waitcnt lgkmcnt(0)
	s_setprio 1
	s_waitcnt lgkmcnt(0)
	v_mfma_f32_16x16x32_bf16 v[68:71], v[196:199], v[154:157], v[68:71]
	v_mfma_f32_16x16x32_bf16 v[64:67], v[204:207], v[154:157], v[64:67]
	v_mfma_f32_16x16x32_bf16 v[52:55], v[196:199], v[172:175], v[52:55]
	v_mfma_f32_16x16x32_bf16 v[48:51], v[204:207], v[172:175], v[48:51]
	v_mfma_f32_16x16x32_bf16 v[44:47], v[196:199], v[180:183], v[44:47]
	v_mfma_f32_16x16x32_bf16 v[40:43], v[204:207], v[180:183], v[40:43]
	v_mfma_f32_16x16x32_bf16 v[36:39], v[196:199], v[188:191], v[36:39]
	v_mfma_f32_16x16x32_bf16 v[32:35], v[204:207], v[188:191], v[32:35]
	v_mfma_f32_16x16x32_bf16 v[68:71], v[200:203], v[168:171], v[68:71]
	v_mfma_f32_16x16x32_bf16 v[64:67], v[208:211], v[168:171], v[64:67]
	v_mfma_f32_16x16x32_bf16 v[52:55], v[200:203], v[176:179], v[52:55]
	v_mfma_f32_16x16x32_bf16 v[48:51], v[208:211], v[176:179], v[48:51]
	v_mfma_f32_16x16x32_bf16 v[44:47], v[200:203], v[184:187], v[44:47]
	v_mfma_f32_16x16x32_bf16 v[40:43], v[208:211], v[184:187], v[40:43]
	v_mfma_f32_16x16x32_bf16 v[36:39], v[200:203], v[192:195], v[36:39]
	v_mfma_f32_16x16x32_bf16 v[32:35], v[208:211], v[192:195], v[32:35]
	s_setprio 0
	s_mov_b32 m0, s40
	v_lshl_add_u64 v[214:215], s[20:21], 0, v[132:133]
	s_barrier
	ds_read_b128 v[154:157], v137 offset:16384
	ds_read_b128 v[168:171], v137 offset:17408
	ds_read_b128 v[172:175], v137 offset:18432
	ds_read_b128 v[176:179], v137 offset:19456
	ds_read_b128 v[180:183], v137 offset:20480
	ds_read_b128 v[184:187], v137 offset:21504
	ds_read_b128 v[188:191], v137 offset:22528
	ds_read_b128 v[192:195], v137 offset:23552
	global_load_lds_dwordx4 v[214:215], off
	v_lshl_add_u64 v[216:217], s[20:21], 0, v[130:131]
	s_mov_b32 m0, s41
	s_nop 0
	global_load_lds_dwordx4 v[216:217], off
	s_barrier
	s_waitcnt lgkmcnt(0)
	s_setprio 1
	s_waitcnt lgkmcnt(0)
	v_mfma_f32_16x16x32_bf16 v[92:95], v[138:141], v[154:157], v[92:95]
	v_mfma_f32_16x16x32_bf16 v[88:91], v[146:149], v[154:157], v[88:91]
	v_mfma_f32_16x16x32_bf16 v[84:87], v[138:141], v[172:175], v[84:87]
	v_mfma_f32_16x16x32_bf16 v[80:83], v[146:149], v[172:175], v[80:83]
	v_mfma_f32_16x16x32_bf16 v[76:79], v[138:141], v[180:183], v[76:79]
	v_mfma_f32_16x16x32_bf16 v[72:75], v[146:149], v[180:183], v[72:75]
	v_mfma_f32_16x16x32_bf16 v[60:63], v[138:141], v[188:191], v[60:63]
	v_mfma_f32_16x16x32_bf16 v[56:59], v[146:149], v[188:191], v[56:59]
	v_mfma_f32_16x16x32_bf16 v[92:95], v[142:145], v[168:171], v[92:95]
	v_mfma_f32_16x16x32_bf16 v[88:91], v[150:153], v[168:171], v[88:91]
	v_mfma_f32_16x16x32_bf16 v[84:87], v[142:145], v[176:179], v[84:87]
	v_mfma_f32_16x16x32_bf16 v[80:83], v[150:153], v[176:179], v[80:83]
	v_mfma_f32_16x16x32_bf16 v[76:79], v[142:145], v[184:187], v[76:79]
	v_mfma_f32_16x16x32_bf16 v[72:75], v[150:153], v[184:187], v[72:75]
	v_mfma_f32_16x16x32_bf16 v[60:63], v[142:145], v[192:195], v[60:63]
	v_mfma_f32_16x16x32_bf16 v[56:59], v[150:153], v[192:195], v[56:59]
	s_setprio 0
	s_barrier
	s_mov_b32 m0, s18
	v_lshl_add_u64 v[138:139], vcc, 0, v[160:161]
	global_load_lds_dwordx4 v[138:139], off
	v_lshl_add_u64 v[138:139], vcc, 0, v[128:129]
	s_mov_b32 m0, s17
	s_nop 0
	global_load_lds_dwordx4 v[138:139], off
	s_waitcnt vmcnt(6)
	s_barrier
	s_setprio 1
	v_mfma_f32_16x16x32_bf16 v[28:31], v[196:199], v[154:157], v[28:31]
	v_mfma_f32_16x16x32_bf16 v[24:27], v[204:207], v[154:157], v[24:27]
	v_mfma_f32_16x16x32_bf16 v[20:23], v[196:199], v[172:175], v[20:23]
	v_mfma_f32_16x16x32_bf16 v[16:19], v[204:207], v[172:175], v[16:19]
	v_mfma_f32_16x16x32_bf16 v[12:15], v[196:199], v[180:183], v[12:15]
	v_mfma_f32_16x16x32_bf16 v[8:11], v[204:207], v[180:183], v[8:11]
	v_mfma_f32_16x16x32_bf16 v[4:7], v[196:199], v[188:191], v[4:7]
	v_mfma_f32_16x16x32_bf16 v[0:3], v[204:207], v[188:191], v[0:3]
	v_mfma_f32_16x16x32_bf16 v[28:31], v[200:203], v[168:171], v[28:31]
	v_mfma_f32_16x16x32_bf16 v[24:27], v[208:211], v[168:171], v[24:27]
	v_mfma_f32_16x16x32_bf16 v[20:23], v[200:203], v[176:179], v[20:23]
	v_mfma_f32_16x16x32_bf16 v[16:19], v[208:211], v[176:179], v[16:19]
	v_mfma_f32_16x16x32_bf16 v[12:15], v[200:203], v[184:187], v[12:15]
	v_mfma_f32_16x16x32_bf16 v[8:11], v[208:211], v[184:187], v[8:11]
	v_mfma_f32_16x16x32_bf16 v[4:7], v[200:203], v[192:195], v[4:7]
	v_mfma_f32_16x16x32_bf16 v[0:3], v[208:211], v[192:195], v[0:3]
	s_setprio 0
	v_add_u32_e32 v150, s16, v135
	s_barrier
	ds_read_b128 v[138:141], v150
	ds_read_b128 v[142:145], v150 offset:1024
	ds_read_b128 v[146:149], v150 offset:2048
	ds_read_b128 v[150:153], v150 offset:3072
	s_mov_b32 m0, s42
	v_lshl_add_u64 v[196:197], s[92:93], 0, v[132:133]
	ds_read_b128 v[154:157], v137 offset:32768
	ds_read_b128 v[168:171], v137 offset:33792
	ds_read_b128 v[172:175], v137 offset:34816
	ds_read_b128 v[176:179], v137 offset:35840
	ds_read_b128 v[180:183], v137 offset:36864
	ds_read_b128 v[184:187], v137 offset:37888
	ds_read_b128 v[188:191], v137 offset:38912
	ds_read_b128 v[192:195], v137 offset:39936
	global_load_lds_dwordx4 v[196:197], off
	v_lshl_add_u64 v[196:197], s[92:93], 0, v[130:131]
	s_mov_b32 m0, s43
	s_nop 0
	global_load_lds_dwordx4 v[196:197], off
	s_waitcnt lgkmcnt(8)
	s_barrier
	s_waitcnt lgkmcnt(0)
	s_setprio 1
	s_waitcnt lgkmcnt(0)
	v_mfma_f32_16x16x32_bf16 v[124:127], v[138:141], v[154:157], v[124:127]
	v_mfma_f32_16x16x32_bf16 v[120:123], v[146:149], v[154:157], v[120:123]
	v_mfma_f32_16x16x32_bf16 v[116:119], v[138:141], v[172:175], v[116:119]
	v_mfma_f32_16x16x32_bf16 v[112:115], v[146:149], v[172:175], v[112:115]
	v_mfma_f32_16x16x32_bf16 v[108:111], v[138:141], v[180:183], v[108:111]
	v_mfma_f32_16x16x32_bf16 v[104:107], v[146:149], v[180:183], v[104:107]
	v_mfma_f32_16x16x32_bf16 v[100:103], v[138:141], v[188:191], v[100:103]
	v_mfma_f32_16x16x32_bf16 v[96:99], v[146:149], v[188:191], v[96:99]
	v_mfma_f32_16x16x32_bf16 v[124:127], v[142:145], v[168:171], v[124:127]
	v_mfma_f32_16x16x32_bf16 v[120:123], v[150:153], v[168:171], v[120:123]
	v_mfma_f32_16x16x32_bf16 v[116:119], v[142:145], v[176:179], v[116:119]
	v_mfma_f32_16x16x32_bf16 v[112:115], v[150:153], v[176:179], v[112:115]
	v_mfma_f32_16x16x32_bf16 v[108:111], v[142:145], v[184:187], v[108:111]
	v_mfma_f32_16x16x32_bf16 v[104:107], v[150:153], v[184:187], v[104:107]
	v_mfma_f32_16x16x32_bf16 v[100:103], v[142:145], v[192:195], v[100:103]
	v_mfma_f32_16x16x32_bf16 v[96:99], v[150:153], v[192:195], v[96:99]
	s_setprio 0
	s_barrier
	s_mov_b32 m0, s15
	v_add_u32_e32 v164, s14, v135
	v_lshl_add_u64 v[158:159], v[158:159], 0, s[74:75]
	ds_read_b128 v[196:199], v164
	ds_read_b128 v[200:203], v164 offset:1024
	ds_read_b128 v[204:207], v164 offset:2048
	ds_read_b128 v[208:211], v164 offset:3072
	global_load_lds_dwordx4 v[158:159], off
	v_lshl_add_u64 v[158:159], v[212:213], 0, s[74:75]
	s_mov_b32 m0, s13
	s_nop 0
	global_load_lds_dwordx4 v[158:159], off
	s_barrier
	s_waitcnt lgkmcnt(0)
	s_setprio 1
	s_waitcnt lgkmcnt(0)
	v_mfma_f32_16x16x32_bf16 v[68:71], v[196:199], v[154:157], v[68:71]
	v_mfma_f32_16x16x32_bf16 v[64:67], v[204:207], v[154:157], v[64:67]
	v_mfma_f32_16x16x32_bf16 v[52:55], v[196:199], v[172:175], v[52:55]
	v_mfma_f32_16x16x32_bf16 v[48:51], v[204:207], v[172:175], v[48:51]
	v_mfma_f32_16x16x32_bf16 v[44:47], v[196:199], v[180:183], v[44:47]
	v_mfma_f32_16x16x32_bf16 v[40:43], v[204:207], v[180:183], v[40:43]
	v_mfma_f32_16x16x32_bf16 v[36:39], v[196:199], v[188:191], v[36:39]
	v_mfma_f32_16x16x32_bf16 v[32:35], v[204:207], v[188:191], v[32:35]
	v_mfma_f32_16x16x32_bf16 v[68:71], v[200:203], v[168:171], v[68:71]
	v_mfma_f32_16x16x32_bf16 v[64:67], v[208:211], v[168:171], v[64:67]
	v_mfma_f32_16x16x32_bf16 v[52:55], v[200:203], v[176:179], v[52:55]
	v_mfma_f32_16x16x32_bf16 v[48:51], v[208:211], v[176:179], v[48:51]
	v_mfma_f32_16x16x32_bf16 v[44:47], v[200:203], v[184:187], v[44:47]
	v_mfma_f32_16x16x32_bf16 v[40:43], v[208:211], v[184:187], v[40:43]
	v_mfma_f32_16x16x32_bf16 v[36:39], v[200:203], v[192:195], v[36:39]
	v_mfma_f32_16x16x32_bf16 v[32:35], v[208:211], v[192:195], v[32:35]
	s_setprio 0
	s_mov_b32 m0, s81
	v_lshl_add_u64 v[158:159], v[214:215], 0, s[74:75]
	s_barrier
	ds_read_b128 v[154:157], v137 offset:49152
	ds_read_b128 v[168:171], v137 offset:50176
	ds_read_b128 v[172:175], v137 offset:51200
	ds_read_b128 v[176:179], v137 offset:52224
	ds_read_b128 v[180:183], v137 offset:53248
	ds_read_b128 v[184:187], v137 offset:54272
	ds_read_b128 v[188:191], v137 offset:55296
	ds_read_b128 v[192:195], v137 offset:56320
	global_load_lds_dwordx4 v[158:159], off
	v_lshl_add_u64 v[158:159], v[216:217], 0, s[74:75]
	s_mov_b32 m0, s96
	s_nop 0
	global_load_lds_dwordx4 v[158:159], off
	s_barrier
	s_waitcnt lgkmcnt(0)
	s_setprio 1
	s_waitcnt lgkmcnt(0)
	v_mfma_f32_16x16x32_bf16 v[92:95], v[138:141], v[154:157], v[92:95]
	v_mfma_f32_16x16x32_bf16 v[88:91], v[146:149], v[154:157], v[88:91]
	v_mfma_f32_16x16x32_bf16 v[84:87], v[138:141], v[172:175], v[84:87]
	v_mfma_f32_16x16x32_bf16 v[80:83], v[146:149], v[172:175], v[80:83]
	v_mfma_f32_16x16x32_bf16 v[76:79], v[138:141], v[180:183], v[76:79]
	v_mfma_f32_16x16x32_bf16 v[72:75], v[146:149], v[180:183], v[72:75]
	v_mfma_f32_16x16x32_bf16 v[60:63], v[138:141], v[188:191], v[60:63]
	v_mfma_f32_16x16x32_bf16 v[56:59], v[146:149], v[188:191], v[56:59]
	v_mfma_f32_16x16x32_bf16 v[92:95], v[142:145], v[168:171], v[92:95]
	v_mfma_f32_16x16x32_bf16 v[88:91], v[150:153], v[168:171], v[88:91]
	v_mfma_f32_16x16x32_bf16 v[84:87], v[142:145], v[176:179], v[84:87]
	v_mfma_f32_16x16x32_bf16 v[80:83], v[150:153], v[176:179], v[80:83]
	v_mfma_f32_16x16x32_bf16 v[76:79], v[142:145], v[184:187], v[76:79]
	v_mfma_f32_16x16x32_bf16 v[72:75], v[150:153], v[184:187], v[72:75]
	v_mfma_f32_16x16x32_bf16 v[60:63], v[142:145], v[192:195], v[60:63]
	v_mfma_f32_16x16x32_bf16 v[56:59], v[150:153], v[192:195], v[56:59]
	s_setprio 0
	s_barrier
	s_mov_b32 m0, s22
	v_lshl_add_u64 v[138:139], s[62:63], 0, v[160:161]
	global_load_lds_dwordx4 v[138:139], off
	v_lshl_add_u64 v[138:139], s[62:63], 0, v[128:129]
	s_mov_b32 m0, s19
	s_nop 0
	global_load_lds_dwordx4 v[138:139], off
	s_waitcnt vmcnt(6)
	s_barrier
	s_setprio 1
	v_mfma_f32_16x16x32_bf16 v[28:31], v[196:199], v[154:157], v[28:31]
	v_mfma_f32_16x16x32_bf16 v[24:27], v[204:207], v[154:157], v[24:27]
	v_mfma_f32_16x16x32_bf16 v[20:23], v[196:199], v[172:175], v[20:23]
	v_mfma_f32_16x16x32_bf16 v[16:19], v[204:207], v[172:175], v[16:19]
	v_mfma_f32_16x16x32_bf16 v[12:15], v[196:199], v[180:183], v[12:15]
	v_mfma_f32_16x16x32_bf16 v[8:11], v[204:207], v[180:183], v[8:11]
	v_mfma_f32_16x16x32_bf16 v[4:7], v[196:199], v[188:191], v[4:7]
	v_mfma_f32_16x16x32_bf16 v[0:3], v[204:207], v[188:191], v[0:3]
	v_mfma_f32_16x16x32_bf16 v[28:31], v[200:203], v[168:171], v[28:31]
	v_mfma_f32_16x16x32_bf16 v[24:27], v[208:211], v[168:171], v[24:27]
	v_mfma_f32_16x16x32_bf16 v[20:23], v[200:203], v[176:179], v[20:23]
	v_mfma_f32_16x16x32_bf16 v[16:19], v[208:211], v[176:179], v[16:19]
	v_mfma_f32_16x16x32_bf16 v[12:15], v[200:203], v[184:187], v[12:15]
	v_mfma_f32_16x16x32_bf16 v[8:11], v[208:211], v[184:187], v[8:11]
	v_mfma_f32_16x16x32_bf16 v[4:7], v[200:203], v[192:195], v[4:7]
	v_mfma_f32_16x16x32_bf16 v[0:3], v[208:211], v[192:195], v[0:3]
	s_setprio 0
	s_movk_i32 s8, 0x100
	s_andn2_b64 vcc, exec, s[66:67]
	s_mov_b64 s[62:63], -1
	s_mov_b64 s[66:67], 0
	s_barrier
	s_cbranch_vccz .LBB0_251
	v_lshl_add_u32 v138, s83, 8, v134
	v_lshl_or_b32 v140, s10, 8, v136
	v_pk_add_f32 v[124:125], v[124:125], 0 op_sel_hi:[1,0]
	v_pk_add_f32 v[120:121], v[120:121], 0 op_sel_hi:[1,0]
	v_ashrrev_i32_e32 v139, 31, v138
	v_ashrrev_i32_e32 v141, 31, v140
	v_pk_add_f32 v[126:127], v[126:127], 0 op_sel_hi:[1,0]
	v_pk_add_f32 v[142:143], v[122:123], 0 op_sel_hi:[1,0]
	v_cvt_pk_bf16_f32 v122, v124, v125
	v_cvt_pk_bf16_f32 v123, v126, v127
	v_cvt_pk_bf16_f32 v124, v120, v121
	v_lshlrev_b64 v[120:121], 14, v[138:139]
	v_lshl_add_u64 v[120:121], s[28:29], 0, v[120:121]
	v_lshlrev_b64 v[126:127], 1, v[140:141]
	v_lshl_add_u64 v[120:121], v[120:121], 0, v[126:127]
	v_pk_add_f32 v[116:117], v[116:117], 0 op_sel_hi:[1,0]
	v_cvt_pk_bf16_f32 v125, v142, v143
	global_store_dwordx4 v[120:121], v[122:125], off sc1
	v_pk_add_f32 v[118:119], v[118:119], 0 op_sel_hi:[1,0]
	v_pk_add_f32 v[108:109], v[108:109], 0 op_sel_hi:[1,0]
	v_pk_add_f32 v[122:123], v[114:115], 0 op_sel_hi:[1,0]
	v_pk_add_f32 v[114:115], v[112:113], 0 op_sel_hi:[1,0]
	v_cvt_pk_bf16_f32 v112, v116, v117
	v_or_b32_e32 v116, 16, v138
	v_ashrrev_i32_e32 v117, 31, v116
	v_lshlrev_b64 v[116:117], 14, v[116:117]
	v_lshl_add_u64 v[116:117], s[28:29], 0, v[116:117]
	v_cvt_pk_bf16_f32 v113, v118, v119
	v_lshl_add_u64 v[116:117], v[116:117], 0, v[126:127]
	v_cvt_pk_bf16_f32 v114, v114, v115
	v_cvt_pk_bf16_f32 v115, v122, v123
	global_store_dwordx4 v[116:117], v[112:115], off sc1
	v_pk_add_f32 v[110:111], v[110:111], 0 op_sel_hi:[1,0]
	v_pk_add_f32 v[100:101], v[100:101], 0 op_sel_hi:[1,0]
	v_pk_add_f32 v[112:113], v[106:107], 0 op_sel_hi:[1,0]
	v_pk_add_f32 v[106:107], v[104:105], 0 op_sel_hi:[1,0]
	v_cvt_pk_bf16_f32 v104, v108, v109
	v_or_b32_e32 v108, 32, v138
	v_ashrrev_i32_e32 v109, 31, v108
	v_lshlrev_b64 v[108:109], 14, v[108:109]
	v_lshl_add_u64 v[108:109], s[28:29], 0, v[108:109]
	v_cvt_pk_bf16_f32 v105, v110, v111
	v_lshl_add_u64 v[108:109], v[108:109], 0, v[126:127]
	v_cvt_pk_bf16_f32 v106, v106, v107
	v_cvt_pk_bf16_f32 v107, v112, v113
	global_store_dwordx4 v[108:109], v[104:107], off sc1
	v_pk_add_f32 v[102:103], v[102:103], 0 op_sel_hi:[1,0]
	v_pk_add_f32 v[94:95], v[94:95], 0 op_sel_hi:[1,0]
	v_pk_add_f32 v[104:105], v[98:99], 0 op_sel_hi:[1,0]
	v_pk_add_f32 v[98:99], v[96:97], 0 op_sel_hi:[1,0]
	v_cvt_pk_bf16_f32 v96, v100, v101
	v_or_b32_e32 v100, 48, v138
	v_ashrrev_i32_e32 v101, 31, v100
	v_lshlrev_b64 v[100:101], 14, v[100:101]
	v_lshl_add_u64 v[100:101], s[28:29], 0, v[100:101]
	v_cvt_pk_bf16_f32 v97, v102, v103
	v_lshl_add_u64 v[100:101], v[100:101], 0, v[126:127]
	s_mov_b32 s1, 0x200000
	v_cvt_pk_bf16_f32 v98, v98, v99
	v_cvt_pk_bf16_f32 v99, v104, v105
	global_store_dwordx4 v[100:101], v[96:99], off sc1
	v_pk_add_f32 v[92:93], v[92:93], 0 op_sel_hi:[1,0]
	v_pk_add_f32 v[86:87], v[86:87], 0 op_sel_hi:[1,0]
	v_pk_add_f32 v[96:97], v[90:91], 0 op_sel_hi:[1,0]
	v_pk_add_f32 v[90:91], v[88:89], 0 op_sel_hi:[1,0]
	v_cvt_pk_bf16_f32 v88, v92, v93
	v_cvt_pk_bf16_f32 v89, v94, v95
	v_add_co_u32_e32 v94, vcc, s1, v120
	s_mov_b32 s1, 0x240000
	s_nop 0
	v_addc_co_u32_e32 v95, vcc, 0, v121, vcc
	v_cvt_pk_bf16_f32 v90, v90, v91
	v_cvt_pk_bf16_f32 v91, v96, v97
	global_store_dwordx4 v[94:95], v[88:91], off sc1
	v_pk_add_f32 v[84:85], v[84:85], 0 op_sel_hi:[1,0]
	v_pk_add_f32 v[78:79], v[78:79], 0 op_sel_hi:[1,0]
	v_pk_add_f32 v[88:89], v[82:83], 0 op_sel_hi:[1,0]
	v_pk_add_f32 v[82:83], v[80:81], 0 op_sel_hi:[1,0]
	v_cvt_pk_bf16_f32 v80, v84, v85
	v_cvt_pk_bf16_f32 v81, v86, v87
	v_add_co_u32_e32 v86, vcc, s1, v120
	s_mov_b32 s1, 0x280000
	s_nop 0
	v_addc_co_u32_e32 v87, vcc, 0, v121, vcc
	v_cvt_pk_bf16_f32 v82, v82, v83
	v_cvt_pk_bf16_f32 v83, v88, v89
	global_store_dwordx4 v[86:87], v[80:83], off sc1
	v_pk_add_f32 v[76:77], v[76:77], 0 op_sel_hi:[1,0]
	v_pk_add_f32 v[62:63], v[62:63], 0 op_sel_hi:[1,0]
	v_pk_add_f32 v[80:81], v[74:75], 0 op_sel_hi:[1,0]
	v_pk_add_f32 v[74:75], v[72:73], 0 op_sel_hi:[1,0]
	v_cvt_pk_bf16_f32 v72, v76, v77
	v_cvt_pk_bf16_f32 v73, v78, v79
	v_add_co_u32_e32 v78, vcc, s1, v120
	s_mov_b32 s1, 0x2c0000
	s_nop 0
	v_addc_co_u32_e32 v79, vcc, 0, v121, vcc
	v_cvt_pk_bf16_f32 v74, v74, v75
	v_cvt_pk_bf16_f32 v75, v80, v81
	global_store_dwordx4 v[78:79], v[72:75], off sc1
	v_pk_add_f32 v[60:61], v[60:61], 0 op_sel_hi:[1,0]
	v_pk_add_f32 v[64:65], v[64:65], 0 op_sel_hi:[1,0]
	v_pk_add_f32 v[72:73], v[58:59], 0 op_sel_hi:[1,0]
	v_pk_add_f32 v[58:59], v[56:57], 0 op_sel_hi:[1,0]
	v_cvt_pk_bf16_f32 v56, v60, v61
	v_cvt_pk_bf16_f32 v57, v62, v63
	v_add_co_u32_e32 v62, vcc, s1, v120
	v_cvt_pk_bf16_f32 v58, v58, v59
	v_cvt_pk_bf16_f32 v59, v72, v73
	v_pk_add_f32 v[54:55], v[54:55], 0 op_sel_hi:[1,0]
	s_nop 0
	v_addc_co_u32_e32 v63, vcc, 0, v121, vcc
	global_store_dwordx4 v[62:63], v[56:59], off sc1
	v_pk_add_f32 v[62:63], v[66:67], 0 op_sel_hi:[1,0]
	v_pk_add_f32 v[52:53], v[52:53], 0 op_sel_hi:[1,0]
	v_pk_add_f32 v[56:57], v[68:69], 0 op_sel_hi:[1,0]
	v_pk_add_f32 v[58:59], v[70:71], 0 op_sel_hi:[1,0]
	v_cvt_pk_bf16_f32 v56, v56, v57
	v_pk_add_f32 v[46:47], v[46:47], 0 op_sel_hi:[1,0]
	v_cvt_pk_bf16_f32 v57, v58, v59
	v_cvt_pk_bf16_f32 v58, v64, v65
	v_cvt_pk_bf16_f32 v59, v62, v63
	global_store_dwordx4 v[120:121], v[56:59], off offset:256 sc1
	v_pk_add_f32 v[44:45], v[44:45], 0 op_sel_hi:[1,0]
	s_mov_b64 s[8:9], 0x200000
	v_pk_add_f32 v[56:57], v[50:51], 0 op_sel_hi:[1,0]
	v_pk_add_f32 v[50:51], v[48:49], 0 op_sel_hi:[1,0]
	v_cvt_pk_bf16_f32 v48, v52, v53
	v_cvt_pk_bf16_f32 v49, v54, v55
	v_pk_add_f32 v[38:39], v[38:39], 0 op_sel_hi:[1,0]
	v_cvt_pk_bf16_f32 v50, v50, v51
	v_cvt_pk_bf16_f32 v51, v56, v57
	global_store_dwordx4 v[116:117], v[48:51], off offset:256 sc1
	v_pk_add_f32 v[36:37], v[36:37], 0 op_sel_hi:[1,0]
	v_lshl_add_u64 v[92:93], v[120:121], 0, s[8:9]
	v_pk_add_f32 v[48:49], v[42:43], 0 op_sel_hi:[1,0]
	v_pk_add_f32 v[42:43], v[40:41], 0 op_sel_hi:[1,0]
	v_cvt_pk_bf16_f32 v40, v44, v45
	v_cvt_pk_bf16_f32 v41, v46, v47
	s_mov_b64 s[8:9], 0x240000
	v_cvt_pk_bf16_f32 v42, v42, v43
	v_cvt_pk_bf16_f32 v43, v48, v49
	global_store_dwordx4 v[108:109], v[40:43], off offset:256 sc1
	v_pk_add_f32 v[30:31], v[30:31], 0 op_sel_hi:[1,0]
	v_pk_add_f32 v[28:29], v[28:29], 0 op_sel_hi:[1,0]
	v_pk_add_f32 v[40:41], v[34:35], 0 op_sel_hi:[1,0]
	v_pk_add_f32 v[34:35], v[32:33], 0 op_sel_hi:[1,0]
	v_cvt_pk_bf16_f32 v32, v36, v37
	v_cvt_pk_bf16_f32 v33, v38, v39
	v_lshl_add_u64 v[84:85], v[120:121], 0, s[8:9]
	v_cvt_pk_bf16_f32 v34, v34, v35
	v_cvt_pk_bf16_f32 v35, v40, v41
	global_store_dwordx4 v[100:101], v[32:35], off offset:256 sc1
	s_mov_b64 s[8:9], 0x280000
	v_pk_add_f32 v[22:23], v[22:23], 0 op_sel_hi:[1,0]
	v_pk_add_f32 v[32:33], v[26:27], 0 op_sel_hi:[1,0]
	v_pk_add_f32 v[26:27], v[24:25], 0 op_sel_hi:[1,0]
	v_cvt_pk_bf16_f32 v24, v28, v29
	v_cvt_pk_bf16_f32 v25, v30, v31
	v_pk_add_f32 v[20:21], v[20:21], 0 op_sel_hi:[1,0]
	v_cvt_pk_bf16_f32 v26, v26, v27
	v_cvt_pk_bf16_f32 v27, v32, v33
	global_store_dwordx4 v[92:93], v[24:27], off offset:256 sc1
	v_lshl_add_u64 v[76:77], v[120:121], 0, s[8:9]
	s_mov_b64 s[8:9], 0x2c0000
	v_pk_add_f32 v[24:25], v[18:19], 0 op_sel_hi:[1,0]
	v_pk_add_f32 v[18:19], v[16:17], 0 op_sel_hi:[1,0]
	v_cvt_pk_bf16_f32 v16, v20, v21
	v_cvt_pk_bf16_f32 v17, v22, v23
	v_pk_add_f32 v[14:15], v[14:15], 0 op_sel_hi:[1,0]
	v_cvt_pk_bf16_f32 v18, v18, v19
	v_cvt_pk_bf16_f32 v19, v24, v25
	global_store_dwordx4 v[84:85], v[16:19], off offset:256 sc1
	v_pk_add_f32 v[12:13], v[12:13], 0 op_sel_hi:[1,0]
	v_readlane_b32 s36, v251, 28
	v_pk_add_f32 v[16:17], v[10:11], 0 op_sel_hi:[1,0]
	v_pk_add_f32 v[10:11], v[8:9], 0 op_sel_hi:[1,0]
	v_cvt_pk_bf16_f32 v8, v12, v13
	v_cvt_pk_bf16_f32 v9, v14, v15
	v_lshl_add_u64 v[60:61], v[120:121], 0, s[8:9]
	v_cvt_pk_bf16_f32 v10, v10, v11
	v_cvt_pk_bf16_f32 v11, v16, v17
	global_store_dwordx4 v[76:77], v[8:11], off offset:256 sc1
	s_and_b64 vcc, exec, s[2:3]
	s_mov_b32 s10, s0
	v_pk_add_f32 v[8:9], v[2:3], 0 op_sel_hi:[1,0]
	v_pk_add_f32 v[2:3], v[0:1], 0 op_sel_hi:[1,0]
	s_mov_b32 s83, s4
	s_mov_b64 s[60:61], s[58:59]
	s_mov_b64 s[64:65], s[6:7]
	v_readlane_b32 s2, v249, 22
	v_readlane_b32 s22, v255, 2
	v_readlane_b32 s62, v255, 4
	v_readlane_b32 s93, v250, 12
	v_readlane_b32 s92, v255, 6
	v_readlane_b32 s37, v251, 29
	v_pk_add_f32 v[6:7], v[6:7], 0 op_sel_hi:[1,0]
	v_pk_add_f32 v[4:5], v[4:5], 0 op_sel_hi:[1,0]
	v_readlane_b32 s3, v249, 23
	v_cvt_pk_bf16_f32 v0, v4, v5
	v_cvt_pk_bf16_f32 v1, v6, v7
	v_cvt_pk_bf16_f32 v2, v2, v3
	v_cvt_pk_bf16_f32 v3, v8, v9
	global_store_dwordx4 v[60:61], v[0:3], off offset:256 sc1
	v_readlane_b32 s23, v255, 3
	v_readlane_b32 s63, v255, 5
	s_cbranch_vccz .LBB0_244
	s_waitcnt vmcnt(0)
	s_mov_b32 s90, s62
	s_cmpk_gt_u32 s38, 0xff
	s_mov_b32 s83, s27
	s_mov_b32 s87, s56
	s_mov_b32 s81, s57
	s_cbranch_scc1 .LBB0_255
	s_barrier

.LBB0_350:
	s_add_u32 s8, s60, 0xfffc0080
	s_addc_u32 s9, s61, -1
	s_add_i32 s16, 0, 0x10000
	v_add_u32_e32 v150, s16, v168
	ds_read_b128 v[128:131], v150
	ds_read_b128 v[132:135], v150 offset:1024
	ds_read_b128 v[146:149], v150 offset:2048
	ds_read_b128 v[150:153], v150 offset:3072
	s_cmp_eq_u32 s15, 12
	s_cselect_b32 s9, s5, s9
	s_cselect_b32 s8, s10, s8
	s_cselect_b32 s63, s1, s14
	s_cselect_b32 s62, s12, s13
	v_lshl_add_u64 v[200:201], s[60:61], 0, v[142:143]
	s_add_i32 m0, s38, 0xc000
	ds_read_b128 v[154:157], v170
	ds_read_b128 v[172:175], v170 offset:1024
	ds_read_b128 v[176:179], v170 offset:2048
	ds_read_b128 v[180:183], v170 offset:3072
	ds_read_b128 v[184:187], v170 offset:4096
	ds_read_b128 v[188:191], v170 offset:5120
	ds_read_b128 v[192:195], v170 offset:6144
	ds_read_b128 v[196:199], v170 offset:7168
	global_load_lds_dwordx4 v[200:201], off
	v_lshl_add_u64 v[200:201], s[60:61], 0, v[144:145]
	s_add_i32 m0, s38, 0xe000
	s_nop 0
	global_load_lds_dwordx4 v[200:201], off
	s_waitcnt lgkmcnt(8)
	s_barrier
	s_waitcnt lgkmcnt(0)
	s_setprio 1
	s_waitcnt lgkmcnt(0)
	v_mfma_f32_16x16x32_bf16 v[124:127], v[128:131], v[154:157], v[124:127]
	v_mfma_f32_16x16x32_bf16 v[120:123], v[146:149], v[154:157], v[120:123]
	v_mfma_f32_16x16x32_bf16 v[116:119], v[128:131], v[176:179], v[116:119]
	v_mfma_f32_16x16x32_bf16 v[112:115], v[146:149], v[176:179], v[112:115]
	v_mfma_f32_16x16x32_bf16 v[108:111], v[128:131], v[184:187], v[108:111]
	v_mfma_f32_16x16x32_bf16 v[104:107], v[146:149], v[184:187], v[104:107]
	v_mfma_f32_16x16x32_bf16 v[100:103], v[128:131], v[192:195], v[100:103]
	v_mfma_f32_16x16x32_bf16 v[96:99], v[146:149], v[192:195], v[96:99]
	v_mfma_f32_16x16x32_bf16 v[124:127], v[132:135], v[172:175], v[124:127]
	v_mfma_f32_16x16x32_bf16 v[120:123], v[150:153], v[172:175], v[120:123]
	v_mfma_f32_16x16x32_bf16 v[116:119], v[132:135], v[180:183], v[116:119]
	v_mfma_f32_16x16x32_bf16 v[112:115], v[150:153], v[180:183], v[112:115]
	v_mfma_f32_16x16x32_bf16 v[108:111], v[132:135], v[188:191], v[108:111]
	v_mfma_f32_16x16x32_bf16 v[104:107], v[150:153], v[188:191], v[104:107]
	v_mfma_f32_16x16x32_bf16 v[100:103], v[132:135], v[196:199], v[100:103]
	v_mfma_f32_16x16x32_bf16 v[96:99], v[150:153], v[196:199], v[96:99]
	s_setprio 0
	s_barrier
	s_add_i32 s18, 0, 0x14000
	s_add_i32 s16, s16, s37
	v_add_u32_e32 v158, s18, v168
	v_lshl_add_u64 v[216:217], s[62:63], 0, v[160:161]
	s_mov_b32 m0, s16
	ds_read_b128 v[200:203], v158
	ds_read_b128 v[204:207], v158 offset:1024
	ds_read_b128 v[208:211], v158 offset:2048
	ds_read_b128 v[212:215], v158 offset:3072
	global_load_lds_dwordx4 v[216:217], off
	v_lshl_add_u64 v[218:219], s[62:63], 0, v[136:137]
	s_add_i32 m0, s16, 0x2000
	s_nop 0
	global_load_lds_dwordx4 v[218:219], off
	s_barrier
	s_waitcnt lgkmcnt(0)
	s_setprio 1
	s_waitcnt lgkmcnt(0)
	v_mfma_f32_16x16x32_bf16 v[68:71], v[200:203], v[154:157], v[68:71]
	v_mfma_f32_16x16x32_bf16 v[64:67], v[208:211], v[154:157], v[64:67]
	v_mfma_f32_16x16x32_bf16 v[52:55], v[200:203], v[176:179], v[52:55]
	v_mfma_f32_16x16x32_bf16 v[48:51], v[208:211], v[176:179], v[48:51]
	v_mfma_f32_16x16x32_bf16 v[44:47], v[200:203], v[184:187], v[44:47]
	v_mfma_f32_16x16x32_bf16 v[40:43], v[208:211], v[184:187], v[40:43]
	v_mfma_f32_16x16x32_bf16 v[36:39], v[200:203], v[192:195], v[36:39]
	v_mfma_f32_16x16x32_bf16 v[32:35], v[208:211], v[192:195], v[32:35]
	v_mfma_f32_16x16x32_bf16 v[68:71], v[204:207], v[172:175], v[68:71]
	v_mfma_f32_16x16x32_bf16 v[64:67], v[212:215], v[172:175], v[64:67]
	v_mfma_f32_16x16x32_bf16 v[52:55], v[204:207], v[180:183], v[52:55]
	v_mfma_f32_16x16x32_bf16 v[48:51], v[212:215], v[180:183], v[48:51]
	v_mfma_f32_16x16x32_bf16 v[44:47], v[204:207], v[188:191], v[44:47]
	v_mfma_f32_16x16x32_bf16 v[40:43], v[212:215], v[188:191], v[40:43]
	v_mfma_f32_16x16x32_bf16 v[36:39], v[204:207], v[196:199], v[36:39]
	v_mfma_f32_16x16x32_bf16 v[32:35], v[212:215], v[196:199], v[32:35]
	s_setprio 0
	s_mov_b32 m0, s38
	v_lshl_add_u64 v[220:221], s[8:9], 0, v[140:141]
	s_barrier
	ds_read_b128 v[154:157], v170 offset:16384
	ds_read_b128 v[172:175], v170 offset:17408
	ds_read_b128 v[176:179], v170 offset:18432
	ds_read_b128 v[180:183], v170 offset:19456
	ds_read_b128 v[184:187], v170 offset:20480
	ds_read_b128 v[188:191], v170 offset:21504
	ds_read_b128 v[192:195], v170 offset:22528
	ds_read_b128 v[196:199], v170 offset:23552
	global_load_lds_dwordx4 v[220:221], off
	v_lshl_add_u64 v[222:223], s[8:9], 0, v[138:139]
	s_mov_b32 m0, s39
	s_nop 0
	global_load_lds_dwordx4 v[222:223], off
	s_barrier
	s_waitcnt lgkmcnt(0)
	s_setprio 1
	s_waitcnt lgkmcnt(0)
	v_mfma_f32_16x16x32_bf16 v[92:95], v[128:131], v[154:157], v[92:95]
	v_mfma_f32_16x16x32_bf16 v[88:91], v[146:149], v[154:157], v[88:91]
	v_mfma_f32_16x16x32_bf16 v[84:87], v[128:131], v[176:179], v[84:87]
	v_mfma_f32_16x16x32_bf16 v[80:83], v[146:149], v[176:179], v[80:83]
	v_mfma_f32_16x16x32_bf16 v[76:79], v[128:131], v[184:187], v[76:79]
	v_mfma_f32_16x16x32_bf16 v[72:75], v[146:149], v[184:187], v[72:75]
	v_mfma_f32_16x16x32_bf16 v[60:63], v[128:131], v[192:195], v[60:63]
	v_mfma_f32_16x16x32_bf16 v[56:59], v[146:149], v[192:195], v[56:59]
	v_mfma_f32_16x16x32_bf16 v[92:95], v[132:135], v[172:175], v[92:95]
	v_mfma_f32_16x16x32_bf16 v[88:91], v[150:153], v[172:175], v[88:91]
	v_mfma_f32_16x16x32_bf16 v[84:87], v[132:135], v[180:183], v[84:87]
	v_mfma_f32_16x16x32_bf16 v[80:83], v[150:153], v[180:183], v[80:83]
	v_mfma_f32_16x16x32_bf16 v[76:79], v[132:135], v[188:191], v[76:79]
	v_mfma_f32_16x16x32_bf16 v[72:75], v[150:153], v[188:191], v[72:75]
	v_mfma_f32_16x16x32_bf16 v[60:63], v[132:135], v[196:199], v[60:63]
	v_mfma_f32_16x16x32_bf16 v[56:59], v[150:153], v[196:199], v[56:59]
	s_setprio 0
	s_barrier
	s_add_u32 s16, s62, 0x40000
	s_addc_u32 s17, s63, 0
	s_add_i32 s18, s18, s37
	v_lshl_add_u64 v[128:129], s[16:17], 0, v[160:161]
	s_mov_b32 m0, s18
	s_nop 0
	global_load_lds_dwordx4 v[128:129], off
	v_lshl_add_u64 v[128:129], s[16:17], 0, v[136:137]
	s_add_i32 m0, s18, 0x2000
	s_nop 0
	global_load_lds_dwordx4 v[128:129], off
	s_waitcnt vmcnt(6)
	s_barrier
	s_setprio 1
	v_mfma_f32_16x16x32_bf16 v[28:31], v[200:203], v[154:157], v[28:31]
	v_mfma_f32_16x16x32_bf16 v[24:27], v[208:211], v[154:157], v[24:27]
	v_mfma_f32_16x16x32_bf16 v[20:23], v[200:203], v[176:179], v[20:23]
	v_mfma_f32_16x16x32_bf16 v[16:19], v[208:211], v[176:179], v[16:19]
	v_mfma_f32_16x16x32_bf16 v[12:15], v[200:203], v[184:187], v[12:15]
	v_mfma_f32_16x16x32_bf16 v[8:11], v[208:211], v[184:187], v[8:11]
	v_mfma_f32_16x16x32_bf16 v[4:7], v[200:203], v[192:195], v[4:7]
	v_mfma_f32_16x16x32_bf16 v[0:3], v[208:211], v[192:195], v[0:3]
	v_mfma_f32_16x16x32_bf16 v[28:31], v[204:207], v[172:175], v[28:31]
	v_mfma_f32_16x16x32_bf16 v[24:27], v[212:215], v[172:175], v[24:27]
	v_mfma_f32_16x16x32_bf16 v[20:23], v[204:207], v[180:183], v[20:23]
	v_mfma_f32_16x16x32_bf16 v[16:19], v[212:215], v[180:183], v[16:19]
	v_mfma_f32_16x16x32_bf16 v[12:15], v[204:207], v[188:191], v[12:15]
	v_mfma_f32_16x16x32_bf16 v[8:11], v[212:215], v[188:191], v[8:11]
	v_mfma_f32_16x16x32_bf16 v[4:7], v[204:207], v[196:199], v[4:7]
	v_mfma_f32_16x16x32_bf16 v[0:3], v[212:215], v[196:199], v[0:3]
	s_setprio 0
	s_add_i32 s16, 0, 0x18000
	v_add_u32_e32 v150, s16, v168
	s_barrier
	ds_read_b128 v[128:131], v150
	ds_read_b128 v[132:135], v150 offset:1024
	ds_read_b128 v[146:149], v150 offset:2048
	ds_read_b128 v[150:153], v150 offset:3072
	s_add_u32 s8, s8, 0x40000
	s_addc_u32 s9, s9, 0
	s_mov_b32 m0, s40
	v_lshl_add_u64 v[200:201], s[8:9], 0, v[140:141]
	ds_read_b128 v[154:157], v170 offset:32768
	ds_read_b128 v[172:175], v170 offset:33792
	ds_read_b128 v[176:179], v170 offset:34816
	ds_read_b128 v[180:183], v170 offset:35840
	ds_read_b128 v[184:187], v170 offset:36864
	ds_read_b128 v[188:191], v170 offset:37888
	ds_read_b128 v[192:195], v170 offset:38912
	ds_read_b128 v[196:199], v170 offset:39936
	global_load_lds_dwordx4 v[200:201], off
	v_lshl_add_u64 v[200:201], s[8:9], 0, v[138:139]
	s_mov_b32 m0, s41
	s_nop 0
	global_load_lds_dwordx4 v[200:201], off
	s_waitcnt lgkmcnt(8)
	s_barrier
	s_waitcnt lgkmcnt(0)
	s_setprio 1
	s_waitcnt lgkmcnt(0)
	v_mfma_f32_16x16x32_bf16 v[124:127], v[128:131], v[154:157], v[124:127]
	v_mfma_f32_16x16x32_bf16 v[120:123], v[146:149], v[154:157], v[120:123]
	v_mfma_f32_16x16x32_bf16 v[116:119], v[128:131], v[176:179], v[116:119]
	v_mfma_f32_16x16x32_bf16 v[112:115], v[146:149], v[176:179], v[112:115]
	v_mfma_f32_16x16x32_bf16 v[108:111], v[128:131], v[184:187], v[108:111]
	v_mfma_f32_16x16x32_bf16 v[104:107], v[146:149], v[184:187], v[104:107]
	v_mfma_f32_16x16x32_bf16 v[100:103], v[128:131], v[192:195], v[100:103]
	v_mfma_f32_16x16x32_bf16 v[96:99], v[146:149], v[192:195], v[96:99]
	v_mfma_f32_16x16x32_bf16 v[124:127], v[132:135], v[172:175], v[124:127]
	v_mfma_f32_16x16x32_bf16 v[120:123], v[150:153], v[172:175], v[120:123]
	v_mfma_f32_16x16x32_bf16 v[116:119], v[132:135], v[180:183], v[116:119]
	v_mfma_f32_16x16x32_bf16 v[112:115], v[150:153], v[180:183], v[112:115]
	v_mfma_f32_16x16x32_bf16 v[108:111], v[132:135], v[188:191], v[108:111]
	v_mfma_f32_16x16x32_bf16 v[104:107], v[150:153], v[188:191], v[104:107]
	v_mfma_f32_16x16x32_bf16 v[100:103], v[132:135], v[196:199], v[100:103]
	v_mfma_f32_16x16x32_bf16 v[96:99], v[150:153], v[196:199], v[96:99]
	s_setprio 0
	s_barrier
	s_add_i32 s17, 0, 0x1c000
	s_add_i32 s8, s16, s37
	v_add_u32_e32 v158, s17, v168
	v_lshl_add_u64 v[216:217], v[216:217], 0, s[74:75]
	s_mov_b32 m0, s8
	ds_read_b128 v[200:203], v158
	ds_read_b128 v[204:207], v158 offset:1024
	ds_read_b128 v[208:211], v158 offset:2048
	ds_read_b128 v[212:215], v158 offset:3072
	global_load_lds_dwordx4 v[216:217], off
	v_lshl_add_u64 v[216:217], v[218:219], 0, s[74:75]
	s_add_i32 m0, s8, 0x2000
	s_nop 0
	global_load_lds_dwordx4 v[216:217], off
	s_barrier
	s_waitcnt lgkmcnt(0)
	s_setprio 1
	s_waitcnt lgkmcnt(0)
	v_mfma_f32_16x16x32_bf16 v[68:71], v[200:203], v[154:157], v[68:71]
	v_mfma_f32_16x16x32_bf16 v[64:67], v[208:211], v[154:157], v[64:67]
	v_mfma_f32_16x16x32_bf16 v[52:55], v[200:203], v[176:179], v[52:55]
	v_mfma_f32_16x16x32_bf16 v[48:51], v[208:211], v[176:179], v[48:51]
	v_mfma_f32_16x16x32_bf16 v[44:47], v[200:203], v[184:187], v[44:47]
	v_mfma_f32_16x16x32_bf16 v[40:43], v[208:211], v[184:187], v[40:43]
	v_mfma_f32_16x16x32_bf16 v[36:39], v[200:203], v[192:195], v[36:39]
	v_mfma_f32_16x16x32_bf16 v[32:35], v[208:211], v[192:195], v[32:35]
	v_mfma_f32_16x16x32_bf16 v[68:71], v[204:207], v[172:175], v[68:71]
	v_mfma_f32_16x16x32_bf16 v[64:67], v[212:215], v[172:175], v[64:67]
	v_mfma_f32_16x16x32_bf16 v[52:55], v[204:207], v[180:183], v[52:55]
	v_mfma_f32_16x16x32_bf16 v[48:51], v[212:215], v[180:183], v[48:51]
	v_mfma_f32_16x16x32_bf16 v[44:47], v[204:207], v[188:191], v[44:47]
	v_mfma_f32_16x16x32_bf16 v[40:43], v[212:215], v[188:191], v[40:43]
	v_mfma_f32_16x16x32_bf16 v[36:39], v[204:207], v[196:199], v[36:39]
	v_mfma_f32_16x16x32_bf16 v[32:35], v[212:215], v[196:199], v[32:35]
	s_setprio 0
	s_mov_b32 m0, s42
	v_lshl_add_u64 v[216:217], v[220:221], 0, s[74:75]
	s_barrier
	ds_read_b128 v[154:157], v170 offset:49152
	ds_read_b128 v[172:175], v170 offset:50176
	ds_read_b128 v[176:179], v170 offset:51200
	ds_read_b128 v[180:183], v170 offset:52224
	ds_read_b128 v[184:187], v170 offset:53248
	ds_read_b128 v[188:191], v170 offset:54272
	ds_read_b128 v[192:195], v170 offset:55296
	ds_read_b128 v[196:199], v170 offset:56320
	global_load_lds_dwordx4 v[216:217], off
	v_lshl_add_u64 v[216:217], v[222:223], 0, s[74:75]
	s_mov_b32 m0, s43
	s_nop 0
	global_load_lds_dwordx4 v[216:217], off
	s_barrier
	s_waitcnt lgkmcnt(0)
	s_setprio 1
	s_waitcnt lgkmcnt(0)
	v_mfma_f32_16x16x32_bf16 v[92:95], v[128:131], v[154:157], v[92:95]
	v_mfma_f32_16x16x32_bf16 v[88:91], v[146:149], v[154:157], v[88:91]
	v_mfma_f32_16x16x32_bf16 v[84:87], v[128:131], v[176:179], v[84:87]
	v_mfma_f32_16x16x32_bf16 v[80:83], v[146:149], v[176:179], v[80:83]
	v_mfma_f32_16x16x32_bf16 v[76:79], v[128:131], v[184:187], v[76:79]
	v_mfma_f32_16x16x32_bf16 v[72:75], v[146:149], v[184:187], v[72:75]
	v_mfma_f32_16x16x32_bf16 v[60:63], v[128:131], v[192:195], v[60:63]
	v_mfma_f32_16x16x32_bf16 v[56:59], v[146:149], v[192:195], v[56:59]
	v_mfma_f32_16x16x32_bf16 v[92:95], v[132:135], v[172:175], v[92:95]
	v_mfma_f32_16x16x32_bf16 v[88:91], v[150:153], v[172:175], v[88:91]
	v_mfma_f32_16x16x32_bf16 v[84:87], v[132:135], v[180:183], v[84:87]
	v_mfma_f32_16x16x32_bf16 v[80:83], v[150:153], v[180:183], v[80:83]
	v_mfma_f32_16x16x32_bf16 v[76:79], v[132:135], v[188:191], v[76:79]
	v_mfma_f32_16x16x32_bf16 v[72:75], v[150:153], v[188:191], v[72:75]
	v_mfma_f32_16x16x32_bf16 v[60:63], v[132:135], v[196:199], v[60:63]
	v_mfma_f32_16x16x32_bf16 v[56:59], v[150:153], v[196:199], v[56:59]
	s_setprio 0
	s_barrier
	s_add_u32 s8, s62, 0x40080
	s_addc_u32 s9, s63, 0
	s_add_i32 s16, s17, s37
	v_lshl_add_u64 v[128:129], s[8:9], 0, v[160:161]
	s_mov_b32 m0, s16
	s_nop 0
	global_load_lds_dwordx4 v[128:129], off
	v_lshl_add_u64 v[128:129], s[8:9], 0, v[136:137]
	s_add_i32 m0, s16, 0x2000
	s_nop 0
	global_load_lds_dwordx4 v[128:129], off
	s_waitcnt vmcnt(6)
	s_barrier
	s_setprio 1
	v_mfma_f32_16x16x32_bf16 v[28:31], v[200:203], v[154:157], v[28:31]
	v_mfma_f32_16x16x32_bf16 v[24:27], v[208:211], v[154:157], v[24:27]
	v_mfma_f32_16x16x32_bf16 v[20:23], v[200:203], v[176:179], v[20:23]
	v_mfma_f32_16x16x32_bf16 v[16:19], v[208:211], v[176:179], v[16:19]
	v_mfma_f32_16x16x32_bf16 v[12:15], v[200:203], v[184:187], v[12:15]
	v_mfma_f32_16x16x32_bf16 v[8:11], v[208:211], v[184:187], v[8:11]
	v_mfma_f32_16x16x32_bf16 v[4:7], v[200:203], v[192:195], v[4:7]
	v_mfma_f32_16x16x32_bf16 v[0:3], v[208:211], v[192:195], v[0:3]
	v_mfma_f32_16x16x32_bf16 v[28:31], v[204:207], v[172:175], v[28:31]
	v_mfma_f32_16x16x32_bf16 v[24:27], v[212:215], v[172:175], v[24:27]
	v_mfma_f32_16x16x32_bf16 v[20:23], v[204:207], v[180:183], v[20:23]
	v_mfma_f32_16x16x32_bf16 v[16:19], v[212:215], v[180:183], v[16:19]
	v_mfma_f32_16x16x32_bf16 v[12:15], v[204:207], v[188:191], v[12:15]
	v_mfma_f32_16x16x32_bf16 v[8:11], v[212:215], v[188:191], v[8:11]
	v_mfma_f32_16x16x32_bf16 v[4:7], v[204:207], v[196:199], v[4:7]
	v_mfma_f32_16x16x32_bf16 v[0:3], v[212:215], v[196:199], v[0:3]
	s_setprio 0
	s_add_i32 s15, s15, 2
	s_add_u32 s60, s60, 0x100
	s_addc_u32 s61, s61, 0
	s_add_u32 s13, s13, 0x100
	s_addc_u32 s14, s14, 0
	s_cmp_gt_u32 s15, 13
	s_barrier
	s_cbranch_scc0 .LBB0_350
	v_lshl_add_u32 v146, s65, 8, v159
	v_readlane_b32 s8, v249, 24
	v_ashrrev_i32_e32 v147, 31, v146
	v_readlane_b32 s9, v249, 25
	v_readlane_b32 s12, v249, 26
	v_lshl_or_b32 v156, s66, 8, v169
	v_lshl_add_u64 v[128:129], v[146:147], 3, s[8:9]
	global_load_dwordx2 v[130:131], v[128:129], off
	global_load_dwordx2 v[218:219], v[128:129], off offset:128
	global_load_dwordx2 v[220:221], v[128:129], off offset:256
	global_load_dwordx2 v[222:223], v[128:129], off offset:384
	global_load_dwordx2 v[224:225], v[128:129], off offset:1024
	global_load_dwordx2 v[226:227], v[128:129], off offset:1152
	global_load_dwordx2 v[228:229], v[128:129], off offset:1280
	global_load_dwordx2 v[230:231], v[128:129], off offset:1408
	s_ashr_i32 s8, s65, 5
	s_ashr_i32 s9, s8, 31
	s_lshl_b64 s[8:9], s[8:9], 14
	v_readlane_b32 s13, v249, 27
	s_add_u32 s8, s12, s8
	v_ashrrev_i32_e32 v157, 31, v156
	s_addc_u32 s9, s13, s9
	v_lshl_add_u64 v[180:181], v[156:157], 2, s[8:9]
	global_load_dwordx4 v[232:235], v[180:181], off offset:16
	global_load_dwordx4 v[236:239], v[180:181], off
	v_readlane_b32 s8, v253, 29
	v_readlane_b32 s9, v253, 30
	s_mov_b32 s1, 0x100000
	s_mov_b32 s66, s0
	s_mov_b32 s65, s4
	s_mov_b64 s[20:21], s[6:7]
	v_readlane_b32 s62, v255, 4
	v_readlane_b32 s63, v255, 5
	s_waitcnt vmcnt(0)
	v_ffbh_u32_e32 v132, v131
	v_min_u32_e32 v132, 32, v132
	v_lshlrev_b64 v[130:131], v132, v[130:131]
	v_min_u32_e32 v130, 1, v130
	v_or_b32_e32 v130, v131, v130
	v_cvt_f32_u32_e32 v130, v130
	v_sub_u32_e32 v131, 32, v132
	v_ldexp_f32 v130, v130, v131
	v_mul_f32_e32 v130, 0x37800000, v130
	v_fmamk_f32 v158, v130, 0x3a800000, v240
	v_mov_b32_e32 v130, v218
	v_mov_b32_e32 v131, v219
	v_cmp_gt_f32_e32 vcc, s53, v158
	v_mul_f32_e32 v164, 0x4b800000, v158
	v_ffbh_u32_e32 v132, v131
	v_min_u32_e32 v132, 32, v132
	v_lshlrev_b64 v[130:131], v132, v[130:131]
	v_min_u32_e32 v130, 1, v130
	v_or_b32_e32 v130, v131, v130
	v_cvt_f32_u32_e32 v130, v130
	v_sub_u32_e32 v131, 32, v132
	v_cndmask_b32_e32 v158, v158, v164, vcc
	v_rsq_f32_e32 v158, v158
	v_ldexp_f32 v130, v130, v131
	v_mul_f32_e32 v130, 0x37800000, v130
	v_fmamk_f32 v171, v130, 0x3a800000, v240
	v_mov_b32_e32 v130, v220
	v_mov_b32_e32 v131, v221
	v_mul_f32_e32 v164, 0x45800000, v158
	v_cndmask_b32_e32 v184, v158, v164, vcc
	v_cmp_gt_f32_e32 vcc, s53, v171
	v_mul_f32_e32 v158, 0x4b800000, v171
	v_ffbh_u32_e32 v132, v131
	v_min_u32_e32 v132, 32, v132
	v_lshlrev_b64 v[130:131], v132, v[130:131]
	v_min_u32_e32 v130, 1, v130
	v_or_b32_e32 v130, v131, v130
	v_cvt_f32_u32_e32 v130, v130
	v_sub_u32_e32 v131, 32, v132
	v_cndmask_b32_e32 v158, v171, v158, vcc
	v_rsq_f32_e32 v158, v158
	v_ldexp_f32 v130, v130, v131
	v_mul_f32_e32 v130, 0x37800000, v130
	v_fmamk_f32 v172, v130, 0x3a800000, v240
	v_mov_b32_e32 v130, v222
	v_mov_b32_e32 v131, v223
	v_mul_f32_e32 v164, 0x45800000, v158
	v_cndmask_b32_e32 v182, v158, v164, vcc
	v_cmp_gt_f32_e32 vcc, s53, v172
	v_mul_f32_e32 v158, 0x4b800000, v172
	v_ffbh_u32_e32 v132, v131
	v_min_u32_e32 v132, 32, v132
	v_lshlrev_b64 v[130:131], v132, v[130:131]
	v_min_u32_e32 v130, 1, v130
	v_or_b32_e32 v130, v131, v130
	v_cvt_f32_u32_e32 v130, v130
	v_sub_u32_e32 v131, 32, v132
	v_cndmask_b32_e32 v158, v172, v158, vcc
	v_rsq_f32_e32 v158, v158
	v_ldexp_f32 v130, v130, v131
	v_mul_f32_e32 v130, 0x37800000, v130
	v_fmamk_f32 v173, v130, 0x3a800000, v240
	v_mov_b32_e32 v130, v224
	v_mov_b32_e32 v131, v225
	v_mul_f32_e32 v164, 0x45800000, v158
	v_ffbh_u32_e32 v132, v131
	v_min_u32_e32 v132, 32, v132
	v_lshlrev_b64 v[130:131], v132, v[130:131]
	v_min_u32_e32 v130, 1, v130
	v_or_b32_e32 v130, v131, v130
	v_cvt_f32_u32_e32 v130, v130
	v_sub_u32_e32 v131, 32, v132
	v_ldexp_f32 v130, v130, v131
	v_mul_f32_e32 v130, 0x37800000, v130
	v_fmamk_f32 v174, v130, 0x3a800000, v240
	v_mov_b32_e32 v130, v226
	v_mov_b32_e32 v131, v227
	v_ffbh_u32_e32 v132, v131
	v_min_u32_e32 v132, 32, v132
	v_lshlrev_b64 v[130:131], v132, v[130:131]
	v_min_u32_e32 v130, 1, v130
	v_or_b32_e32 v130, v131, v130
	v_cvt_f32_u32_e32 v130, v130
	v_sub_u32_e32 v131, 32, v132
	v_ldexp_f32 v130, v130, v131
	v_mul_f32_e32 v130, 0x37800000, v130
	v_fmamk_f32 v175, v130, 0x3a800000, v240
	v_mov_b32_e32 v130, v228
	v_mov_b32_e32 v131, v229
	v_ffbh_u32_e32 v132, v131
	v_mov_b32_e32 v128, v230
	v_mov_b32_e32 v129, v231
	v_min_u32_e32 v132, 32, v132
	v_lshlrev_b64 v[130:131], v132, v[130:131]
	v_min_u32_e32 v130, 1, v130
	v_or_b32_e32 v130, v131, v130
	v_cvt_f32_u32_e32 v130, v130
	v_sub_u32_e32 v131, 32, v132
	v_ldexp_f32 v130, v130, v131
	v_mul_f32_e32 v130, 0x37800000, v130
	v_fmamk_f32 v177, v130, 0x3a800000, v240
	v_ffbh_u32_e32 v130, v129
	v_min_u32_e32 v130, 32, v130
	v_lshlrev_b64 v[128:129], v130, v[128:129]
	v_min_u32_e32 v128, 1, v128
	v_or_b32_e32 v128, v129, v128
	v_cvt_f32_u32_e32 v128, v128
	v_sub_u32_e32 v129, 32, v130
	v_ldexp_f32 v128, v128, v129
	v_mul_f32_e32 v128, 0x37800000, v128
	v_fmamk_f32 v179, v128, 0x3a800000, v240
	v_mov_b32_e32 v128, v232
	v_mov_b32_e32 v129, v233
	v_mov_b32_e32 v130, v234
	v_mov_b32_e32 v131, v235
	v_mov_b32_e32 v132, v236
	v_mov_b32_e32 v133, v237
	v_mov_b32_e32 v134, v238
	v_mov_b32_e32 v135, v239
	s_waitcnt vmcnt(0)
	v_pk_add_f32 v[148:149], v[130:131], 0 op_sel_hi:[1,0]
	v_pk_add_f32 v[152:153], v[134:135], 0 op_sel_hi:[1,0]
	v_pk_add_f32 v[154:155], v[132:133], 0 op_sel_hi:[1,0]
	v_pk_add_f32 v[150:151], v[128:129], 0 op_sel_hi:[1,0]
	global_load_dwordx4 v[128:131], v[180:181], off offset:528
	global_load_dwordx4 v[132:135], v[180:181], off offset:512
	v_cndmask_b32_e32 v180, v158, v164, vcc
	v_cmp_gt_f32_e32 vcc, s53, v173
	v_mul_f32_e32 v158, 0x4b800000, v173
	v_pk_fma_f32 v[122:123], v[122:123], v[184:185], v[148:149] op_sel_hi:[1,0,1]
	v_cndmask_b32_e32 v158, v173, v158, vcc
	v_rsq_f32_e32 v158, v158
	v_pk_fma_f32 v[126:127], v[126:127], v[184:185], v[152:153] op_sel_hi:[1,0,1]
	v_pk_fma_f32 v[124:125], v[124:125], v[184:185], v[154:155] op_sel_hi:[1,0,1]
	v_pk_fma_f32 v[120:121], v[120:121], v[184:185], v[150:151] op_sel_hi:[1,0,1]
	v_mul_f32_e32 v164, 0x45800000, v158
	v_cndmask_b32_e32 v178, v158, v164, vcc
	v_cmp_gt_f32_e32 vcc, s53, v174
	v_mul_f32_e32 v158, 0x4b800000, v174
	v_max_f32_e32 v122, 0, v122
	v_cndmask_b32_e32 v158, v174, v158, vcc
	v_rsq_f32_e32 v158, v158
	v_max_f32_e32 v124, 0, v124
	v_max_f32_e32 v120, 0, v120
	v_max_f32_e32 v121, 0, v121
	v_mul_f32_e32 v164, 0x45800000, v158
	v_cndmask_b32_e32 v176, v158, v164, vcc
	v_cmp_gt_f32_e32 vcc, s53, v175
	v_mul_f32_e32 v158, 0x4b800000, v175
	v_mul_f32_e32 v124, v124, v124
	v_cndmask_b32_e32 v158, v175, v158, vcc
	v_rsq_f32_e32 v158, v158
	v_mul_f32_e32 v120, v120, v120
	v_max_f32_e32 v125, 0, v125
	v_mul_f32_e32 v121, v121, v121
	v_mul_f32_e32 v164, 0x45800000, v158
	v_cndmask_b32_e32 v174, v158, v164, vcc
	v_cmp_gt_f32_e32 vcc, s53, v177
	v_mul_f32_e32 v158, 0x4b800000, v177
	v_max_f32_e32 v126, 0, v126
	v_cndmask_b32_e32 v158, v177, v158, vcc
	v_rsq_f32_e32 v158, v158
	v_mul_f32_e32 v125, v125, v125
	v_mul_f32_e32 v126, v126, v126
	v_pk_fma_f32 v[114:115], v[114:115], v[182:183], v[148:149] op_sel_hi:[1,0,1]
	v_mul_f32_e32 v164, 0x45800000, v158
	v_cndmask_b32_e32 v172, v158, v164, vcc
	v_cmp_gt_f32_e32 vcc, s53, v179
	v_mul_f32_e32 v158, 0x4b800000, v179
	v_pk_fma_f32 v[118:119], v[118:119], v[182:183], v[152:153] op_sel_hi:[1,0,1]
	v_cndmask_b32_e32 v158, v179, v158, vcc
	v_rsq_f32_e32 v158, v158
	v_pk_fma_f32 v[116:117], v[116:117], v[182:183], v[154:155] op_sel_hi:[1,0,1]
	v_pk_fma_f32 v[112:113], v[112:113], v[182:183], v[150:151] op_sel_hi:[1,0,1]
	v_max_f32_e32 v114, 0, v114
	v_mul_f32_e32 v164, 0x45800000, v158
	v_cndmask_b32_e32 v158, v158, v164, vcc
	v_mul_f32_e32 v164, v122, v122
	v_max_f32_e32 v122, 0, v127
	v_mul_f32_e32 v127, v122, v122
	v_max_f32_e32 v122, 0, v123
	v_mul_f32_e32 v165, v122, v122
	v_cvt_pk_bf16_f32 v122, v124, v125
	v_cvt_pk_bf16_f32 v123, v126, v127
	v_cvt_pk_bf16_f32 v124, v120, v121
	v_lshlrev_b64 v[120:121], 13, v[146:147]
	v_lshl_add_u64 v[120:121], s[8:9], 0, v[120:121]
	v_lshlrev_b64 v[126:127], 1, v[156:157]
	v_lshl_add_u64 v[120:121], v[120:121], 0, v[126:127]
	v_cvt_pk_bf16_f32 v125, v164, v165
	global_store_dwordx4 v[120:121], v[122:125], off sc1
	v_max_f32_e32 v116, 0, v116
	v_max_f32_e32 v112, 0, v112
	v_mul_f32_e32 v122, v114, v114
	v_max_f32_e32 v114, 0, v119
	v_mul_f32_e32 v116, v116, v116
	v_mul_f32_e32 v112, v112, v112
	v_max_f32_e32 v117, 0, v117
	v_max_f32_e32 v113, 0, v113
	v_max_f32_e32 v118, 0, v118
	v_mul_f32_e32 v119, v114, v114
	v_max_f32_e32 v114, 0, v115
	v_mul_f32_e32 v117, v117, v117
	v_mul_f32_e32 v113, v113, v113
	v_mul_f32_e32 v118, v118, v118
	v_mul_f32_e32 v123, v114, v114
	v_cvt_pk_bf16_f32 v114, v116, v117
	v_cvt_pk_bf16_f32 v115, v118, v119
	v_cvt_pk_bf16_f32 v116, v112, v113
	v_or_b32_e32 v112, 16, v146
	v_ashrrev_i32_e32 v113, 31, v112
	v_lshlrev_b64 v[112:113], 13, v[112:113]
	v_lshl_add_u64 v[112:113], s[8:9], 0, v[112:113]
	v_pk_fma_f32 v[106:107], v[106:107], v[180:181], v[148:149] op_sel_hi:[1,0,1]
	v_lshl_add_u64 v[112:113], v[112:113], 0, v[126:127]
	v_pk_fma_f32 v[110:111], v[110:111], v[180:181], v[152:153] op_sel_hi:[1,0,1]
	v_pk_fma_f32 v[108:109], v[108:109], v[180:181], v[154:155] op_sel_hi:[1,0,1]
	v_pk_fma_f32 v[104:105], v[104:105], v[180:181], v[150:151] op_sel_hi:[1,0,1]
	v_max_f32_e32 v106, 0, v106
	v_cvt_pk_bf16_f32 v117, v122, v123
	global_store_dwordx4 v[112:113], v[114:117], off sc1
	v_max_f32_e32 v108, 0, v108
	v_max_f32_e32 v104, 0, v104
	v_mul_f32_e32 v114, v106, v106
	v_max_f32_e32 v106, 0, v111
	v_mul_f32_e32 v108, v108, v108
	v_mul_f32_e32 v104, v104, v104
	v_max_f32_e32 v109, 0, v109
	v_max_f32_e32 v105, 0, v105
	v_max_f32_e32 v110, 0, v110
	v_mul_f32_e32 v111, v106, v106
	v_max_f32_e32 v106, 0, v107
	v_mul_f32_e32 v109, v109, v109
	v_mul_f32_e32 v105, v105, v105
	v_mul_f32_e32 v110, v110, v110
	v_mul_f32_e32 v115, v106, v106
	v_cvt_pk_bf16_f32 v106, v108, v109
	v_cvt_pk_bf16_f32 v107, v110, v111
	v_cvt_pk_bf16_f32 v108, v104, v105
	v_or_b32_e32 v104, 32, v146
	v_ashrrev_i32_e32 v105, 31, v104
	v_lshlrev_b64 v[104:105], 13, v[104:105]
	v_lshl_add_u64 v[104:105], s[8:9], 0, v[104:105]
	v_pk_fma_f32 v[98:99], v[98:99], v[178:179], v[148:149] op_sel_hi:[1,0,1]
	v_lshl_add_u64 v[104:105], v[104:105], 0, v[126:127]
	v_pk_fma_f32 v[102:103], v[102:103], v[178:179], v[152:153] op_sel_hi:[1,0,1]
	v_pk_fma_f32 v[100:101], v[100:101], v[178:179], v[154:155] op_sel_hi:[1,0,1]
	v_pk_fma_f32 v[96:97], v[96:97], v[178:179], v[150:151] op_sel_hi:[1,0,1]
	v_max_f32_e32 v98, 0, v98
	v_cvt_pk_bf16_f32 v109, v114, v115
	global_store_dwordx4 v[104:105], v[106:109], off sc1
	v_max_f32_e32 v100, 0, v100
	v_max_f32_e32 v96, 0, v96
	v_mul_f32_e32 v106, v98, v98
	v_max_f32_e32 v98, 0, v103
	v_mul_f32_e32 v100, v100, v100
	v_mul_f32_e32 v96, v96, v96
	v_max_f32_e32 v101, 0, v101
	v_max_f32_e32 v97, 0, v97
	v_max_f32_e32 v102, 0, v102
	v_mul_f32_e32 v103, v98, v98
	v_max_f32_e32 v98, 0, v99
	v_mul_f32_e32 v101, v101, v101
	v_mul_f32_e32 v97, v97, v97
	v_mul_f32_e32 v102, v102, v102
	v_mul_f32_e32 v107, v98, v98
	v_cvt_pk_bf16_f32 v98, v100, v101
	v_cvt_pk_bf16_f32 v99, v102, v103
	v_cvt_pk_bf16_f32 v100, v96, v97
	v_or_b32_e32 v96, 48, v146
	v_ashrrev_i32_e32 v97, 31, v96
	v_lshlrev_b64 v[96:97], 13, v[96:97]
	v_lshl_add_u64 v[96:97], s[8:9], 0, v[96:97]
	v_pk_fma_f32 v[90:91], v[90:91], v[176:177], v[148:149] op_sel_hi:[1,0,1]
	v_lshl_add_u64 v[96:97], v[96:97], 0, v[126:127]
	v_pk_fma_f32 v[94:95], v[94:95], v[176:177], v[152:153] op_sel_hi:[1,0,1]
	v_max_f32_e32 v90, 0, v90
	v_cvt_pk_bf16_f32 v101, v106, v107
	global_store_dwordx4 v[96:97], v[98:101], off sc1
	v_pk_fma_f32 v[92:93], v[92:93], v[176:177], v[154:155] op_sel_hi:[1,0,1]
	v_max_f32_e32 v94, 0, v94
	v_mul_f32_e32 v98, v90, v90
	v_max_f32_e32 v90, 0, v95
	v_max_f32_e32 v92, 0, v92
	v_max_f32_e32 v93, 0, v93
	v_mul_f32_e32 v94, v94, v94
	v_mul_f32_e32 v95, v90, v90
	v_max_f32_e32 v90, 0, v91
	v_pk_fma_f32 v[88:89], v[88:89], v[176:177], v[150:151] op_sel_hi:[1,0,1]
	v_mul_f32_e32 v92, v92, v92
	v_mul_f32_e32 v93, v93, v93
	v_mul_f32_e32 v99, v90, v90
	v_cvt_pk_bf16_f32 v90, v92, v93
	v_cvt_pk_bf16_f32 v91, v94, v95
	v_add_co_u32_e32 v94, vcc, s1, v120
	v_pk_fma_f32 v[82:83], v[82:83], v[174:175], v[148:149] op_sel_hi:[1,0,1]
	v_max_f32_e32 v88, 0, v88
	v_max_f32_e32 v89, 0, v89
	v_addc_co_u32_e32 v95, vcc, 0, v121, vcc
	v_pk_fma_f32 v[86:87], v[86:87], v[174:175], v[152:153] op_sel_hi:[1,0,1]
	v_max_f32_e32 v82, 0, v82
	v_mul_f32_e32 v88, v88, v88
	v_mul_f32_e32 v89, v89, v89
	v_cvt_pk_bf16_f32 v92, v88, v89
	v_cvt_pk_bf16_f32 v93, v98, v99
	global_store_dwordx4 v[94:95], v[90:93], off sc1
	v_pk_fma_f32 v[84:85], v[84:85], v[174:175], v[154:155] op_sel_hi:[1,0,1]
	v_max_f32_e32 v86, 0, v86
	v_mul_f32_e32 v90, v82, v82
	v_max_f32_e32 v82, 0, v87
	v_max_f32_e32 v84, 0, v84
	v_max_f32_e32 v85, 0, v85
	v_mul_f32_e32 v86, v86, v86
	v_mul_f32_e32 v87, v82, v82
	v_max_f32_e32 v82, 0, v83
	s_mov_b32 s1, 0x120000
	v_pk_fma_f32 v[80:81], v[80:81], v[174:175], v[150:151] op_sel_hi:[1,0,1]
	v_mul_f32_e32 v84, v84, v84
	v_mul_f32_e32 v85, v85, v85
	v_mul_f32_e32 v91, v82, v82
	v_cvt_pk_bf16_f32 v82, v84, v85
	v_cvt_pk_bf16_f32 v83, v86, v87
	v_add_co_u32_e32 v86, vcc, s1, v120
	v_pk_fma_f32 v[74:75], v[74:75], v[172:173], v[148:149] op_sel_hi:[1,0,1]
	v_max_f32_e32 v80, 0, v80
	v_max_f32_e32 v81, 0, v81
	v_addc_co_u32_e32 v87, vcc, 0, v121, vcc
	v_pk_fma_f32 v[78:79], v[78:79], v[172:173], v[152:153] op_sel_hi:[1,0,1]
	v_max_f32_e32 v74, 0, v74
	v_mul_f32_e32 v80, v80, v80
	v_mul_f32_e32 v81, v81, v81
	v_cvt_pk_bf16_f32 v84, v80, v81
	v_cvt_pk_bf16_f32 v85, v90, v91
	global_store_dwordx4 v[86:87], v[82:85], off sc1
	v_pk_fma_f32 v[76:77], v[76:77], v[172:173], v[154:155] op_sel_hi:[1,0,1]
	v_max_f32_e32 v78, 0, v78
	v_mul_f32_e32 v82, v74, v74
	v_max_f32_e32 v74, 0, v79
	v_max_f32_e32 v76, 0, v76
	v_max_f32_e32 v77, 0, v77
	v_mul_f32_e32 v78, v78, v78
	v_mul_f32_e32 v79, v74, v74
	v_max_f32_e32 v74, 0, v75
	s_mov_b32 s1, 0x140000
	v_pk_fma_f32 v[72:73], v[72:73], v[172:173], v[150:151] op_sel_hi:[1,0,1]
	v_mul_f32_e32 v76, v76, v76
	v_mul_f32_e32 v77, v77, v77
	v_mul_f32_e32 v83, v74, v74
	v_cvt_pk_bf16_f32 v74, v76, v77
	v_cvt_pk_bf16_f32 v75, v78, v79
	v_add_co_u32_e32 v78, vcc, s1, v120
	v_pk_fma_f32 v[58:59], v[58:59], v[158:159], v[148:149] op_sel_hi:[1,0,1]
	v_max_f32_e32 v72, 0, v72
	v_max_f32_e32 v73, 0, v73
	v_addc_co_u32_e32 v79, vcc, 0, v121, vcc
	v_pk_fma_f32 v[62:63], v[62:63], v[158:159], v[152:153] op_sel_hi:[1,0,1]
	v_max_f32_e32 v58, 0, v58
	v_mul_f32_e32 v72, v72, v72
	v_mul_f32_e32 v73, v73, v73
	v_cvt_pk_bf16_f32 v76, v72, v73
	v_cvt_pk_bf16_f32 v77, v82, v83
	global_store_dwordx4 v[78:79], v[74:77], off sc1
	v_pk_fma_f32 v[60:61], v[60:61], v[158:159], v[154:155] op_sel_hi:[1,0,1]
	v_max_f32_e32 v62, 0, v62
	v_mul_f32_e32 v74, v58, v58
	v_max_f32_e32 v58, 0, v63
	v_max_f32_e32 v60, 0, v60
	v_max_f32_e32 v61, 0, v61
	v_mul_f32_e32 v62, v62, v62
	v_mul_f32_e32 v63, v58, v58
	v_max_f32_e32 v58, 0, v59
	s_mov_b32 s1, 0x160000
	v_pk_fma_f32 v[56:57], v[56:57], v[158:159], v[150:151] op_sel_hi:[1,0,1]
	v_mul_f32_e32 v60, v60, v60
	v_mul_f32_e32 v61, v61, v61
	v_mul_f32_e32 v75, v58, v58
	v_cvt_pk_bf16_f32 v58, v60, v61
	v_cvt_pk_bf16_f32 v59, v62, v63
	v_add_co_u32_e32 v62, vcc, s1, v120
	s_waitcnt vmcnt(7)
	v_pk_add_f32 v[134:135], v[134:135], 0 op_sel_hi:[1,0]
	v_max_f32_e32 v56, 0, v56
	v_max_f32_e32 v57, 0, v57
	v_addc_co_u32_e32 v63, vcc, 0, v121, vcc
	v_pk_add_f32 v[130:131], v[130:131], 0 op_sel_hi:[1,0]
	v_mul_f32_e32 v56, v56, v56
	v_mul_f32_e32 v57, v57, v57
	v_cvt_pk_bf16_f32 v60, v56, v57
	v_cvt_pk_bf16_f32 v61, v74, v75
	global_store_dwordx4 v[62:63], v[58:61], off sc1
	v_pk_fma_f32 v[62:63], v[66:67], v[184:185], v[130:131] op_sel_hi:[1,0,1]
	v_pk_add_f32 v[132:133], v[132:133], 0 op_sel_hi:[1,0]
	v_pk_fma_f32 v[58:59], v[70:71], v[184:185], v[134:135] op_sel_hi:[1,0,1]
	v_pk_add_f32 v[128:129], v[128:129], 0 op_sel_hi:[1,0]
	v_max_f32_e32 v58, 0, v58
	v_mul_f32_e32 v66, v58, v58
	v_max_f32_e32 v58, 0, v62
	v_pk_fma_f32 v[60:61], v[68:69], v[184:185], v[132:133] op_sel_hi:[1,0,1]
	v_mul_f32_e32 v62, v58, v58
	v_max_f32_e32 v58, 0, v59
	v_pk_fma_f32 v[64:65], v[64:65], v[184:185], v[128:129] op_sel_hi:[1,0,1]
	v_max_f32_e32 v60, 0, v60
	v_max_f32_e32 v61, 0, v61
	v_mul_f32_e32 v59, v58, v58
	v_max_f32_e32 v58, 0, v63
	v_pk_fma_f32 v[48:49], v[48:49], v[182:183], v[128:129] op_sel_hi:[1,0,1]
	v_mul_f32_e32 v60, v60, v60
	v_max_f32_e32 v64, 0, v64
	v_mul_f32_e32 v61, v61, v61
	v_max_f32_e32 v65, 0, v65
	v_mul_f32_e32 v63, v58, v58
	v_cvt_pk_bf16_f32 v58, v60, v61
	v_pk_fma_f32 v[52:53], v[52:53], v[182:183], v[132:133] op_sel_hi:[1,0,1]
	v_pk_fma_f32 v[50:51], v[50:51], v[182:183], v[130:131] op_sel_hi:[1,0,1]
	v_max_f32_e32 v48, 0, v48
	v_mul_f32_e32 v64, v64, v64
	v_mul_f32_e32 v65, v65, v65
	v_cvt_pk_bf16_f32 v59, v66, v59
	v_cvt_pk_bf16_f32 v60, v64, v65
	v_cvt_pk_bf16_f32 v61, v62, v63
	global_store_dwordx4 v[120:121], v[58:61], off offset:256 sc1
	v_pk_fma_f32 v[54:55], v[54:55], v[182:183], v[134:135] op_sel_hi:[1,0,1]
	v_max_f32_e32 v49, 0, v49
	v_mul_f32_e32 v58, v48, v48
	v_max_f32_e32 v48, 0, v53
	v_max_f32_e32 v50, 0, v50
	v_max_f32_e32 v52, 0, v52
	v_mul_f32_e32 v48, v48, v48
	v_mul_f32_e32 v53, v49, v49
	v_max_f32_e32 v49, 0, v54
	v_mul_f32_e32 v54, v50, v50
	v_max_f32_e32 v50, 0, v55
	v_max_f32_e32 v51, 0, v51
	v_pk_fma_f32 v[40:41], v[40:41], v[180:181], v[128:129] op_sel_hi:[1,0,1]
	v_mul_f32_e32 v52, v52, v52
	v_mul_f32_e32 v49, v49, v49
	v_mul_f32_e32 v50, v50, v50
	v_mul_f32_e32 v51, v51, v51
	v_cvt_pk_bf16_f32 v48, v52, v48
	v_pk_fma_f32 v[44:45], v[44:45], v[180:181], v[132:133] op_sel_hi:[1,0,1]
	v_pk_fma_f32 v[42:43], v[42:43], v[180:181], v[130:131] op_sel_hi:[1,0,1]
	v_max_f32_e32 v40, 0, v40
	v_cvt_pk_bf16_f32 v49, v49, v50
	v_cvt_pk_bf16_f32 v50, v58, v53
	v_cvt_pk_bf16_f32 v51, v54, v51
	global_store_dwordx4 v[112:113], v[48:51], off offset:256 sc1
	v_pk_fma_f32 v[46:47], v[46:47], v[180:181], v[134:135] op_sel_hi:[1,0,1]
	v_max_f32_e32 v41, 0, v41
	v_mul_f32_e32 v48, v40, v40
	v_max_f32_e32 v40, 0, v45
	v_max_f32_e32 v42, 0, v42
	v_max_f32_e32 v44, 0, v44
	v_mul_f32_e32 v40, v40, v40
	v_mul_f32_e32 v45, v41, v41
	v_max_f32_e32 v41, 0, v46
	v_mul_f32_e32 v46, v42, v42
	v_max_f32_e32 v42, 0, v47
	v_max_f32_e32 v43, 0, v43
	v_pk_fma_f32 v[32:33], v[32:33], v[178:179], v[128:129] op_sel_hi:[1,0,1]
	v_mul_f32_e32 v44, v44, v44
	v_mul_f32_e32 v41, v41, v41
	v_mul_f32_e32 v42, v42, v42
	v_mul_f32_e32 v43, v43, v43
	v_cvt_pk_bf16_f32 v40, v44, v40
	v_pk_fma_f32 v[36:37], v[36:37], v[178:179], v[132:133] op_sel_hi:[1,0,1]
	v_pk_fma_f32 v[34:35], v[34:35], v[178:179], v[130:131] op_sel_hi:[1,0,1]
	v_max_f32_e32 v32, 0, v32
	v_cvt_pk_bf16_f32 v41, v41, v42
	v_cvt_pk_bf16_f32 v42, v48, v45
	v_cvt_pk_bf16_f32 v43, v46, v43
	global_store_dwordx4 v[104:105], v[40:43], off offset:256 sc1
	v_pk_fma_f32 v[38:39], v[38:39], v[178:179], v[134:135] op_sel_hi:[1,0,1]
	v_max_f32_e32 v33, 0, v33
	v_mul_f32_e32 v40, v32, v32
	v_max_f32_e32 v32, 0, v37
	v_max_f32_e32 v34, 0, v34
	v_max_f32_e32 v36, 0, v36
	v_mul_f32_e32 v32, v32, v32
	v_mul_f32_e32 v37, v33, v33
	v_max_f32_e32 v33, 0, v38
	v_mul_f32_e32 v38, v34, v34
	v_max_f32_e32 v34, 0, v39
	v_max_f32_e32 v35, 0, v35
	v_pk_fma_f32 v[24:25], v[24:25], v[176:177], v[128:129] op_sel_hi:[1,0,1]
	v_mul_f32_e32 v36, v36, v36
	v_mul_f32_e32 v33, v33, v33
	v_mul_f32_e32 v34, v34, v34
	v_mul_f32_e32 v35, v35, v35
	v_cvt_pk_bf16_f32 v32, v36, v32
	v_pk_fma_f32 v[28:29], v[28:29], v[176:177], v[132:133] op_sel_hi:[1,0,1]
	v_pk_fma_f32 v[26:27], v[26:27], v[176:177], v[130:131] op_sel_hi:[1,0,1]
	v_max_f32_e32 v24, 0, v24
	v_cvt_pk_bf16_f32 v33, v33, v34
	v_cvt_pk_bf16_f32 v34, v40, v37
	v_cvt_pk_bf16_f32 v35, v38, v35
	global_store_dwordx4 v[96:97], v[32:35], off offset:256 sc1
	v_pk_fma_f32 v[30:31], v[30:31], v[176:177], v[134:135] op_sel_hi:[1,0,1]
	v_max_f32_e32 v25, 0, v25
	v_mul_f32_e32 v32, v24, v24
	v_max_f32_e32 v24, 0, v29
	v_max_f32_e32 v26, 0, v26
	s_mov_b64 s[8:9], 0x100000
	v_max_f32_e32 v28, 0, v28
	v_mul_f32_e32 v24, v24, v24
	v_mul_f32_e32 v29, v25, v25
	v_max_f32_e32 v25, 0, v30
	v_mul_f32_e32 v30, v26, v26
	v_max_f32_e32 v26, 0, v31
	v_max_f32_e32 v27, 0, v27
	v_pk_fma_f32 v[16:17], v[16:17], v[174:175], v[128:129] op_sel_hi:[1,0,1]
	v_lshl_add_u64 v[88:89], v[120:121], 0, s[8:9]
	v_mul_f32_e32 v28, v28, v28
	v_mul_f32_e32 v25, v25, v25
	v_mul_f32_e32 v26, v26, v26
	v_mul_f32_e32 v27, v27, v27
	v_cvt_pk_bf16_f32 v24, v28, v24
	v_pk_fma_f32 v[20:21], v[20:21], v[174:175], v[132:133] op_sel_hi:[1,0,1]
	v_pk_fma_f32 v[18:19], v[18:19], v[174:175], v[130:131] op_sel_hi:[1,0,1]
	v_max_f32_e32 v16, 0, v16
	v_cvt_pk_bf16_f32 v25, v25, v26
	v_cvt_pk_bf16_f32 v26, v32, v29
	v_cvt_pk_bf16_f32 v27, v30, v27
	global_store_dwordx4 v[88:89], v[24:27], off offset:256 sc1
	v_pk_fma_f32 v[22:23], v[22:23], v[174:175], v[134:135] op_sel_hi:[1,0,1]
	v_max_f32_e32 v17, 0, v17
	v_mul_f32_e32 v24, v16, v16
	v_max_f32_e32 v16, 0, v21
	v_max_f32_e32 v18, 0, v18
	s_mov_b64 s[8:9], 0x120000
	v_max_f32_e32 v20, 0, v20
	v_mul_f32_e32 v16, v16, v16
	v_mul_f32_e32 v21, v17, v17
	v_max_f32_e32 v17, 0, v22
	v_mul_f32_e32 v22, v18, v18
	v_max_f32_e32 v18, 0, v23
	v_max_f32_e32 v19, 0, v19
	v_pk_fma_f32 v[8:9], v[8:9], v[172:173], v[128:129] op_sel_hi:[1,0,1]
	v_lshl_add_u64 v[80:81], v[120:121], 0, s[8:9]
	v_mul_f32_e32 v20, v20, v20
	v_mul_f32_e32 v17, v17, v17
	v_mul_f32_e32 v18, v18, v18
	v_mul_f32_e32 v19, v19, v19
	v_cvt_pk_bf16_f32 v16, v20, v16
	v_pk_fma_f32 v[12:13], v[12:13], v[172:173], v[132:133] op_sel_hi:[1,0,1]
	v_pk_fma_f32 v[10:11], v[10:11], v[172:173], v[130:131] op_sel_hi:[1,0,1]
	v_max_f32_e32 v8, 0, v8
	v_cvt_pk_bf16_f32 v17, v17, v18
	v_cvt_pk_bf16_f32 v18, v24, v21
	v_cvt_pk_bf16_f32 v19, v22, v19
	global_store_dwordx4 v[80:81], v[16:19], off offset:256 sc1
	v_pk_fma_f32 v[14:15], v[14:15], v[172:173], v[134:135] op_sel_hi:[1,0,1]
	v_max_f32_e32 v9, 0, v9
	v_mul_f32_e32 v16, v8, v8
	v_max_f32_e32 v8, 0, v13
	v_max_f32_e32 v10, 0, v10
	s_mov_b64 s[8:9], 0x140000
	v_max_f32_e32 v12, 0, v12
	v_mul_f32_e32 v8, v8, v8
	v_mul_f32_e32 v13, v9, v9
	v_max_f32_e32 v9, 0, v14
	v_mul_f32_e32 v14, v10, v10
	v_max_f32_e32 v10, 0, v15
	v_max_f32_e32 v11, 0, v11
	v_pk_fma_f32 v[2:3], v[2:3], v[158:159], v[130:131] op_sel_hi:[1,0,1]
	v_pk_fma_f32 v[0:1], v[0:1], v[158:159], v[128:129] op_sel_hi:[1,0,1]
	v_lshl_add_u64 v[72:73], v[120:121], 0, s[8:9]
	v_mul_f32_e32 v12, v12, v12
	v_mul_f32_e32 v9, v9, v9
	v_mul_f32_e32 v10, v10, v10
	v_mul_f32_e32 v11, v11, v11
	v_cvt_pk_bf16_f32 v8, v12, v8
	v_pk_fma_f32 v[6:7], v[6:7], v[158:159], v[134:135] op_sel_hi:[1,0,1]
	v_pk_fma_f32 v[4:5], v[4:5], v[158:159], v[132:133] op_sel_hi:[1,0,1]
	v_max_f32_e32 v0, 0, v0
	v_max_f32_e32 v1, 0, v1
	v_max_f32_e32 v2, 0, v2
	s_mov_b64 s[8:9], 0x160000
	v_cvt_pk_bf16_f32 v9, v9, v10
	v_cvt_pk_bf16_f32 v10, v16, v13
	v_cvt_pk_bf16_f32 v11, v14, v11
	global_store_dwordx4 v[72:73], v[8:11], off offset:256 sc1
	v_max_f32_e32 v3, 0, v3
	v_lshl_add_u64 v[56:57], v[120:121], 0, s[8:9]
	v_mul_f32_e32 v8, v0, v0
	v_max_f32_e32 v0, 0, v5
	v_mul_f32_e32 v5, v1, v1
	v_max_f32_e32 v1, 0, v6
	v_mul_f32_e32 v6, v2, v2
	v_max_f32_e32 v2, 0, v7
	v_max_f32_e32 v4, 0, v4
	v_mul_f32_e32 v0, v0, v0
	v_mul_f32_e32 v1, v1, v1
	v_mul_f32_e32 v2, v2, v2
	v_mul_f32_e32 v3, v3, v3
	s_and_b64 vcc, exec, s[2:3]
	s_mov_b64 s[8:9], s[58:59]
	v_mul_f32_e32 v4, v4, v4
	v_cvt_pk_bf16_f32 v0, v4, v0
	v_cvt_pk_bf16_f32 v1, v1, v2
	v_cvt_pk_bf16_f32 v2, v8, v5
	v_cvt_pk_bf16_f32 v3, v6, v3
	global_store_dwordx4 v[56:57], v[0:3], off offset:256 sc1
	s_cbranch_vccz .LBB0_343
	s_waitcnt vmcnt(0)
	s_mov_b32 s90, s62
	s_cmpk_gt_u32 s36, 0xff
	s_cbranch_scc1 .LBB0_354
	s_barrier
